# hoist epilogue loads (phases 12,13,14,18) with wait-state slots kept + pipelined topk loop
# baseline (speedup 1.0000x reference)
.LBB0_703:
	s_mov_b32 s94, 0x7fff0000
	s_mov_b32 s95, 0x7fff0000
	s_mov_b32 s97, 0
.Ltk_block:
	s_add_i32 s30, s30, 1
	s_cmp_lt_u32 s30, s24
	s_cbranch_scc0 .Ltk_nopf
	v_lshl_or_b32 v242, s30, 8, v102
	v_mov_b32_e32 v243, s21
	v_cmp_gt_i32_e32 vcc, s22, v242
	s_nop 1
	v_cndmask_b32_e32 v242, v243, v242, vcc
	v_ashrrev_i32_e32 v243, 31, v242
	v_lshlrev_b64 v[242:243], 7, v[242:243]
	v_lshl_add_u64 v[242:243], v[84:85], 0, v[242:243]
	global_load_dwordx4 v[46:49], v[242:243], off offset:48
	global_load_dwordx4 v[42:45], v[242:243], off offset:32
	global_load_dwordx4 v[38:41], v[242:243], off offset:16
	global_load_dwordx4 v[34:37], v[242:243], off
.Ltk_nopf:
	v_add_u32_e32 v160, s97, v120
	s_mov_b32 s31, 0
	s_nop 0
	ds_read_b128 v[162:165], v160 offset:0
	ds_read_b128 v[166:169], v160 offset:32
	ds_read_b128 v[170:173], v160 offset:64
	ds_read_b128 v[174:177], v160 offset:96
.Ltk_pair:
	s_add_i32 s33, s29, s31
	s_add_i32 s16, s33, 32
	s_cmp_gt_i32 s16, s23
	s_cbranch_scc1 .Ltk_e_nob1
	ds_read_b128 v[178:181], v160 offset:4608
	ds_read_b128 v[182:185], v160 offset:4640
	ds_read_b128 v[186:189], v160 offset:4672
	ds_read_b128 v[190:193], v160 offset:4704
	s_waitcnt lgkmcnt(4)
	s_branch .Ltk_e_go

.Ltk_e_go:
	v_med3_f32 v194, v194, 0, v125
	v_mfma_f32_32x32x16_bf16 v[2:17], v[58:61], v[162:165], 0
	v_fma_f32 v226, v91, v194, 0
	v_med3_f32 v195, v195, 0, v125
	v_fma_f32 v227, v93, v195, 0
	v_med3_f32 v196, v196, 0, v125
	v_fmac_f32_e32 v226, v95, v196
	v_med3_f32 v197, v197, 0, v125
	v_fmac_f32_e32 v227, v129, v197
	v_mfma_f32_32x32x16_bf16 v[18:33], v[74:77], v[162:165], 0
	v_med3_f32 v198, v198, 0, v125
	v_fmac_f32_e32 v226, v130, v198
	v_med3_f32 v199, v199, 0, v125
	v_fmac_f32_e32 v227, v131, v199
	v_med3_f32 v200, v200, 0, v125
	v_fmac_f32_e32 v226, v132, v200
	v_med3_f32 v201, v201, 0, v125
	v_mfma_f32_32x32x16_bf16 v[2:17], v[50:53], v[166:169], v[2:17]
	v_fmac_f32_e32 v227, v133, v201
	v_med3_f32 v202, v202, 0, v125
	v_fmac_f32_e32 v226, v134, v202
	v_med3_f32 v203, v203, 0, v125
	v_fmac_f32_e32 v227, v135, v203
	v_med3_f32 v204, v204, 0, v125
	v_fmac_f32_e32 v226, v136, v204
	v_mfma_f32_32x32x16_bf16 v[18:33], v[66:69], v[166:169], v[18:33]
	v_med3_f32 v205, v205, 0, v125
	v_fmac_f32_e32 v227, v137, v205
	v_med3_f32 v206, v206, 0, v125
	v_fmac_f32_e32 v226, v138, v206
	v_med3_f32 v207, v207, 0, v125
	v_fmac_f32_e32 v227, v139, v207
	v_med3_f32 v208, v208, 0, v125
	v_mfma_f32_32x32x16_bf16 v[2:17], v[54:57], v[170:173], v[2:17]
	v_fmac_f32_e32 v226, v140, v208
	v_med3_f32 v209, v209, 0, v125
	v_fmac_f32_e32 v227, v141, v209
	v_add_f32_e32 v228, v227, v226
	v_med3_f32 v210, v210, 0, v125
	v_fma_f32 v229, v142, v210, 0
	v_med3_f32 v211, v211, 0, v125
	v_mfma_f32_32x32x16_bf16 v[18:33], v[70:73], v[170:173], v[18:33]
	v_fma_f32 v230, v143, v211, 0
	v_med3_f32 v212, v212, 0, v125
	v_fmac_f32_e32 v229, v144, v212
	v_med3_f32 v213, v213, 0, v125
	v_fmac_f32_e32 v230, v145, v213
	v_med3_f32 v214, v214, 0, v125
	v_fmac_f32_e32 v229, v146, v214
	v_mfma_f32_32x32x16_bf16 v[2:17], v[62:65], v[174:177], v[2:17]
	v_med3_f32 v215, v215, 0, v125
	v_fmac_f32_e32 v230, v147, v215
	v_med3_f32 v216, v216, 0, v125
	v_fmac_f32_e32 v229, v148, v216
	v_med3_f32 v217, v217, 0, v125
	v_fmac_f32_e32 v230, v149, v217
	v_med3_f32 v218, v218, 0, v125
	v_mfma_f32_32x32x16_bf16 v[18:33], v[78:81], v[174:177], v[18:33]
	v_fmac_f32_e32 v229, v150, v218
	v_med3_f32 v219, v219, 0, v125
	v_fmac_f32_e32 v230, v151, v219
	v_med3_f32 v220, v220, 0, v125
	v_fmac_f32_e32 v229, v152, v220
	v_med3_f32 v221, v221, 0, v125
	v_fmac_f32_e32 v230, v153, v221
	v_med3_f32 v222, v222, 0, v125
	v_fmac_f32_e32 v229, v154, v222
	v_med3_f32 v223, v223, 0, v125
	v_fmac_f32_e32 v230, v155, v223
	v_med3_f32 v224, v224, 0, v125
	v_fmac_f32_e32 v229, v156, v224
	v_med3_f32 v225, v225, 0, v125
	v_fmac_f32_e32 v230, v157, v225
	v_add_f32_e32 v231, v230, v229
	s_sub_i32 s96, s22, s95
	s_nop 1
	v_permlane32_swap_b32_e32 v228, v231
	v_add_f32_e32 v232, v228, v231
	v_cmp_gt_i32_e32 vcc, s96, v100
	s_and_saveexec_b64 s[18:19], vcc
	v_add_u32_e32 v82, s95, v121
	v_lshl_add_u64 v[236:237], v[82:83], 2, s[36:37]
	global_store_dword v[236:237], v232, off
	v_not_b32_e32 v233, v232
	v_or_b32_e32 v234, 0x80000000, v232
	v_cmp_gt_i32_e32 vcc, 0, v232
	s_nop 1
	v_cndmask_b32_e32 v233, v234, v233, vcc
	v_lshrrev_b32_e32 v233, 20, v233
	v_and_b32_e32 v233, 0xffc, v233
	v_add_u32_e32 v233, v119, v233
	ds_add_u32 v233, v124
	s_or_b64 exec, exec, s[18:19]
	s_mov_b32 s94, s33
	s_add_i32 s16, s33, 32
	s_cmp_gt_i32 s16, s23
	s_cbranch_scc1 .Ltk_drain_e
	s_add_i32 s17, s33, 64
	s_cmpk_eq_i32 s31, 0xc0
	s_cbranch_scc1 .Ltk_o_nob0
	s_cmp_gt_i32 s17, s23
	s_cbranch_scc1 .Ltk_o_nob0
	ds_read_b128 v[162:165], v160 offset:9216
	ds_read_b128 v[166:169], v160 offset:9248
	ds_read_b128 v[170:173], v160 offset:9280
	ds_read_b128 v[174:177], v160 offset:9312
	s_waitcnt lgkmcnt(4)
	s_branch .Ltk_o_go

.Ltk_o_go:
	v_med3_f32 v2, v2, 0, v125
	v_mfma_f32_32x32x16_bf16 v[194:209], v[58:61], v[178:181], 0
	v_fma_f32 v226, v91, v2, 0
	v_med3_f32 v3, v3, 0, v125
	v_fma_f32 v227, v93, v3, 0
	v_med3_f32 v4, v4, 0, v125
	v_fmac_f32_e32 v226, v95, v4
	v_med3_f32 v5, v5, 0, v125
	v_fmac_f32_e32 v227, v129, v5
	v_mfma_f32_32x32x16_bf16 v[210:225], v[74:77], v[178:181], 0
	v_med3_f32 v6, v6, 0, v125
	v_fmac_f32_e32 v226, v130, v6
	v_med3_f32 v7, v7, 0, v125
	v_fmac_f32_e32 v227, v131, v7
	v_med3_f32 v8, v8, 0, v125
	v_fmac_f32_e32 v226, v132, v8
	v_med3_f32 v9, v9, 0, v125
	v_mfma_f32_32x32x16_bf16 v[194:209], v[50:53], v[182:185], v[194:209]
	v_fmac_f32_e32 v227, v133, v9
	v_med3_f32 v10, v10, 0, v125
	v_fmac_f32_e32 v226, v134, v10
	v_med3_f32 v11, v11, 0, v125
	v_fmac_f32_e32 v227, v135, v11
	v_med3_f32 v12, v12, 0, v125
	v_fmac_f32_e32 v226, v136, v12
	v_mfma_f32_32x32x16_bf16 v[210:225], v[66:69], v[182:185], v[210:225]
	v_med3_f32 v13, v13, 0, v125
	v_fmac_f32_e32 v227, v137, v13
	v_med3_f32 v14, v14, 0, v125
	v_fmac_f32_e32 v226, v138, v14
	v_med3_f32 v15, v15, 0, v125
	v_fmac_f32_e32 v227, v139, v15
	v_med3_f32 v16, v16, 0, v125
	v_mfma_f32_32x32x16_bf16 v[194:209], v[54:57], v[186:189], v[194:209]
	v_fmac_f32_e32 v226, v140, v16
	v_med3_f32 v17, v17, 0, v125
	v_fmac_f32_e32 v227, v141, v17
	v_add_f32_e32 v228, v227, v226
	v_med3_f32 v18, v18, 0, v125
	v_fma_f32 v229, v142, v18, 0
	v_med3_f32 v19, v19, 0, v125
	v_mfma_f32_32x32x16_bf16 v[210:225], v[70:73], v[186:189], v[210:225]
	v_fma_f32 v230, v143, v19, 0
	v_med3_f32 v20, v20, 0, v125
	v_fmac_f32_e32 v229, v144, v20
	v_med3_f32 v21, v21, 0, v125
	v_fmac_f32_e32 v230, v145, v21
	v_med3_f32 v22, v22, 0, v125
	v_fmac_f32_e32 v229, v146, v22
	v_mfma_f32_32x32x16_bf16 v[194:209], v[62:65], v[190:193], v[194:209]
	v_med3_f32 v23, v23, 0, v125
	v_fmac_f32_e32 v230, v147, v23
	v_med3_f32 v24, v24, 0, v125
	v_fmac_f32_e32 v229, v148, v24
	v_med3_f32 v25, v25, 0, v125
	v_fmac_f32_e32 v230, v149, v25
	v_med3_f32 v26, v26, 0, v125
	v_mfma_f32_32x32x16_bf16 v[210:225], v[78:81], v[190:193], v[210:225]
	v_fmac_f32_e32 v229, v150, v26
	v_med3_f32 v27, v27, 0, v125
	v_fmac_f32_e32 v230, v151, v27
	v_med3_f32 v28, v28, 0, v125
	v_fmac_f32_e32 v229, v152, v28
	v_med3_f32 v29, v29, 0, v125
	v_fmac_f32_e32 v230, v153, v29
	v_med3_f32 v30, v30, 0, v125
	v_fmac_f32_e32 v229, v154, v30
	v_med3_f32 v31, v31, 0, v125
	v_fmac_f32_e32 v230, v155, v31
	v_med3_f32 v32, v32, 0, v125
	v_fmac_f32_e32 v229, v156, v32
	v_med3_f32 v33, v33, 0, v125
	v_fmac_f32_e32 v230, v157, v33
	v_add_f32_e32 v231, v230, v229
	s_sub_i32 s96, s22, s94
	s_nop 1
	v_permlane32_swap_b32_e32 v228, v231
	v_add_f32_e32 v232, v228, v231
	v_cmp_gt_i32_e32 vcc, s96, v100
	s_and_saveexec_b64 s[18:19], vcc
	v_add_u32_e32 v82, s94, v121
	v_lshl_add_u64 v[236:237], v[82:83], 2, s[36:37]
	global_store_dword v[236:237], v232, off
	v_not_b32_e32 v233, v232
	v_or_b32_e32 v234, 0x80000000, v232
	v_cmp_gt_i32_e32 vcc, 0, v232
	s_nop 1
	v_cndmask_b32_e32 v233, v234, v233, vcc
	v_lshrrev_b32_e32 v233, 20, v233
	v_and_b32_e32 v233, 0xffc, v233
	v_add_u32_e32 v233, v119, v233
	ds_add_u32 v233, v124
	s_or_b64 exec, exec, s[18:19]
	s_add_i32 s95, s33, 32
	s_add_i32 s17, s33, 64
	s_cmp_gt_i32 s17, s23
	s_cbranch_scc1 .Ltk_drain_o
	s_cmpk_eq_i32 s31, 0xc0
	s_cbranch_scc1 .Ltk_blockend
	s_add_i32 s31, s31, 64
	v_add_u32_e32 v160, 0x2400, v160
	s_branch .Ltk_pair
.Ltk_blockend:
	s_xor_b32 s97, s97, 0x9000
	v_add_u32_e32 v242, s97, v103
	s_waitcnt vmcnt(0)
	ds_write_b128 v242, v[34:37]
	ds_write_b128 v242, v[38:41] offset:16
	ds_write_b128 v242, v[42:45] offset:32
	ds_write_b128 v242, v[46:49] offset:48
	s_addk_i32 s29, 0x100
	s_waitcnt lgkmcnt(0)
	s_barrier
	s_branch .Ltk_block
.Ltk_drain_e:
	v_med3_f32 v2, v2, 0, v125
	v_fma_f32 v226, v91, v2, 0
	v_med3_f32 v3, v3, 0, v125
	v_fma_f32 v227, v93, v3, 0
	v_med3_f32 v4, v4, 0, v125
	v_fmac_f32_e32 v226, v95, v4
	v_med3_f32 v5, v5, 0, v125
	v_fmac_f32_e32 v227, v129, v5
	v_med3_f32 v6, v6, 0, v125
	v_fmac_f32_e32 v226, v130, v6
	v_med3_f32 v7, v7, 0, v125
	v_fmac_f32_e32 v227, v131, v7
	v_med3_f32 v8, v8, 0, v125
	v_fmac_f32_e32 v226, v132, v8
	v_med3_f32 v9, v9, 0, v125
	v_fmac_f32_e32 v227, v133, v9
	v_med3_f32 v10, v10, 0, v125
	v_fmac_f32_e32 v226, v134, v10
	v_med3_f32 v11, v11, 0, v125
	v_fmac_f32_e32 v227, v135, v11
	v_med3_f32 v12, v12, 0, v125
	v_fmac_f32_e32 v226, v136, v12
	v_med3_f32 v13, v13, 0, v125
	v_fmac_f32_e32 v227, v137, v13
	v_med3_f32 v14, v14, 0, v125
	v_fmac_f32_e32 v226, v138, v14
	v_med3_f32 v15, v15, 0, v125
	v_fmac_f32_e32 v227, v139, v15
	v_med3_f32 v16, v16, 0, v125
	v_fmac_f32_e32 v226, v140, v16
	v_med3_f32 v17, v17, 0, v125
	v_fmac_f32_e32 v227, v141, v17
	v_add_f32_e32 v228, v227, v226
	v_med3_f32 v18, v18, 0, v125
	v_fma_f32 v229, v142, v18, 0
	v_med3_f32 v19, v19, 0, v125
	v_fma_f32 v230, v143, v19, 0
	v_med3_f32 v20, v20, 0, v125
	v_fmac_f32_e32 v229, v144, v20
	v_med3_f32 v21, v21, 0, v125
	v_fmac_f32_e32 v230, v145, v21
	v_med3_f32 v22, v22, 0, v125
	v_fmac_f32_e32 v229, v146, v22
	v_med3_f32 v23, v23, 0, v125
	v_fmac_f32_e32 v230, v147, v23
	v_med3_f32 v24, v24, 0, v125
	v_fmac_f32_e32 v229, v148, v24
	v_med3_f32 v25, v25, 0, v125
	v_fmac_f32_e32 v230, v149, v25
	v_med3_f32 v26, v26, 0, v125
	v_fmac_f32_e32 v229, v150, v26
	v_med3_f32 v27, v27, 0, v125
	v_fmac_f32_e32 v230, v151, v27
	v_med3_f32 v28, v28, 0, v125
	v_fmac_f32_e32 v229, v152, v28
	v_med3_f32 v29, v29, 0, v125
	v_fmac_f32_e32 v230, v153, v29
	v_med3_f32 v30, v30, 0, v125
	v_fmac_f32_e32 v229, v154, v30
	v_med3_f32 v31, v31, 0, v125
	v_fmac_f32_e32 v230, v155, v31
	v_med3_f32 v32, v32, 0, v125
	v_fmac_f32_e32 v229, v156, v32
	v_med3_f32 v33, v33, 0, v125
	v_fmac_f32_e32 v230, v157, v33
	v_add_f32_e32 v231, v230, v229
	s_sub_i32 s96, s22, s94
	s_nop 1
	v_permlane32_swap_b32_e32 v228, v231
	v_add_f32_e32 v232, v228, v231
	v_cmp_gt_i32_e32 vcc, s96, v100
	s_and_saveexec_b64 s[18:19], vcc
	v_add_u32_e32 v82, s94, v121
	v_lshl_add_u64 v[236:237], v[82:83], 2, s[36:37]
	global_store_dword v[236:237], v232, off
	v_not_b32_e32 v233, v232
	v_or_b32_e32 v234, 0x80000000, v232
	v_cmp_gt_i32_e32 vcc, 0, v232
	s_nop 1
	v_cndmask_b32_e32 v233, v234, v233, vcc
	v_lshrrev_b32_e32 v233, 20, v233
	v_and_b32_e32 v233, 0xffc, v233
	v_add_u32_e32 v233, v119, v233
	ds_add_u32 v233, v124
	s_or_b64 exec, exec, s[18:19]
	s_branch .Ltk_done
.Ltk_drain_o:
	v_med3_f32 v194, v194, 0, v125
	v_fma_f32 v226, v91, v194, 0
	v_med3_f32 v195, v195, 0, v125
	v_fma_f32 v227, v93, v195, 0
	v_med3_f32 v196, v196, 0, v125
	v_fmac_f32_e32 v226, v95, v196
	v_med3_f32 v197, v197, 0, v125
	v_fmac_f32_e32 v227, v129, v197
	v_med3_f32 v198, v198, 0, v125
	v_fmac_f32_e32 v226, v130, v198
	v_med3_f32 v199, v199, 0, v125
	v_fmac_f32_e32 v227, v131, v199
	v_med3_f32 v200, v200, 0, v125
	v_fmac_f32_e32 v226, v132, v200
	v_med3_f32 v201, v201, 0, v125
	v_fmac_f32_e32 v227, v133, v201
	v_med3_f32 v202, v202, 0, v125
	v_fmac_f32_e32 v226, v134, v202
	v_med3_f32 v203, v203, 0, v125
	v_fmac_f32_e32 v227, v135, v203
	v_med3_f32 v204, v204, 0, v125
	v_fmac_f32_e32 v226, v136, v204
	v_med3_f32 v205, v205, 0, v125
	v_fmac_f32_e32 v227, v137, v205
	v_med3_f32 v206, v206, 0, v125
	v_fmac_f32_e32 v226, v138, v206
	v_med3_f32 v207, v207, 0, v125
	v_fmac_f32_e32 v227, v139, v207
	v_med3_f32 v208, v208, 0, v125
	v_fmac_f32_e32 v226, v140, v208
	v_med3_f32 v209, v209, 0, v125
	v_fmac_f32_e32 v227, v141, v209
	v_add_f32_e32 v228, v227, v226
	v_med3_f32 v210, v210, 0, v125
	v_fma_f32 v229, v142, v210, 0
	v_med3_f32 v211, v211, 0, v125
	v_fma_f32 v230, v143, v211, 0
	v_med3_f32 v212, v212, 0, v125
	v_fmac_f32_e32 v229, v144, v212
	v_med3_f32 v213, v213, 0, v125
	v_fmac_f32_e32 v230, v145, v213
	v_med3_f32 v214, v214, 0, v125
	v_fmac_f32_e32 v229, v146, v214
	v_med3_f32 v215, v215, 0, v125
	v_fmac_f32_e32 v230, v147, v215
	v_med3_f32 v216, v216, 0, v125
	v_fmac_f32_e32 v229, v148, v216
	v_med3_f32 v217, v217, 0, v125
	v_fmac_f32_e32 v230, v149, v217
	v_med3_f32 v218, v218, 0, v125
	v_fmac_f32_e32 v229, v150, v218
	v_med3_f32 v219, v219, 0, v125
	v_fmac_f32_e32 v230, v151, v219
	v_med3_f32 v220, v220, 0, v125
	v_fmac_f32_e32 v229, v152, v220
	v_med3_f32 v221, v221, 0, v125
	v_fmac_f32_e32 v230, v153, v221
	v_med3_f32 v222, v222, 0, v125
	v_fmac_f32_e32 v229, v154, v222
	v_med3_f32 v223, v223, 0, v125
	v_fmac_f32_e32 v230, v155, v223
	v_med3_f32 v224, v224, 0, v125
	v_fmac_f32_e32 v229, v156, v224
	v_med3_f32 v225, v225, 0, v125
	v_fmac_f32_e32 v230, v157, v225
	v_add_f32_e32 v231, v230, v229
	s_sub_i32 s96, s22, s95
	s_nop 1
	v_permlane32_swap_b32_e32 v228, v231
	v_add_f32_e32 v232, v228, v231
	v_cmp_gt_i32_e32 vcc, s96, v100
	s_and_saveexec_b64 s[18:19], vcc
	v_add_u32_e32 v82, s95, v121
	v_lshl_add_u64 v[236:237], v[82:83], 2, s[36:37]
	global_store_dword v[236:237], v232, off
	v_not_b32_e32 v233, v232
	v_or_b32_e32 v234, 0x80000000, v232
	v_cmp_gt_i32_e32 vcc, 0, v232
	s_nop 1
	v_cndmask_b32_e32 v233, v234, v233, vcc
	v_lshrrev_b32_e32 v233, 20, v233
	v_and_b32_e32 v233, 0xffc, v233
	v_add_u32_e32 v233, v119, v233
	ds_add_u32 v233, v124
	s_or_b64 exec, exec, s[18:19]
.Ltk_done:
	s_waitcnt lgkmcnt(0)
	s_barrier
	s_branch .LBB0_717

.LBB0_1565:
	v_lshl_add_u32 v148, s22, 8, v1
	v_lshl_or_b32 v146, s45, 8, v151
	v_ashrrev_i32_e32 v149, 31, v148
	v_ashrrev_i32_e32 v147, 31, v146
	v_lshlrev_b64 v[156:157], 14, v[148:149]
	v_lshlrev_b64 v[146:147], 1, v[146:147]
	v_lshl_add_u64 v[156:157], s[8:9], 0, v[156:157]
	v_lshl_add_u64 v[160:161], v[156:157], 0, v[146:147]
	v_lshl_add_u32 v166, s22, 8, v1
	v_lshl_or_b32 v232, s45, 8, v151
	v_ashrrev_i32_e32 v167, 31, v166
	v_ashrrev_i32_e32 v233, 31, v232
	v_lshlrev_b64 v[234:235], 14, v[166:167]
	v_lshlrev_b64 v[232:233], 1, v[232:233]
	v_lshl_add_u64 v[234:235], s[8:9], 0, v[234:235]
	v_lshl_add_u64 v[236:237], v[234:235], 0, v[232:233]
	global_load_dwordx4 v[168:171], v[236:237], off
	v_lshl_add_u32 v166, s22, 8, v1
	v_lshl_or_b32 v232, s45, 8, v151
	v_ashrrev_i32_e32 v167, 31, v166
	v_ashrrev_i32_e32 v233, 31, v232
	v_lshlrev_b64 v[234:235], 14, v[166:167]
	v_lshlrev_b64 v[232:233], 1, v[232:233]
	v_lshl_add_u64 v[234:235], s[8:9], 0, v[234:235]
	v_lshl_add_u64 v[236:237], v[234:235], 0, v[232:233]
	global_load_dwordx4 v[172:175], v[236:237], off offset:256
	v_lshl_add_u32 v166, s22, 8, v1
	v_lshl_or_b32 v232, s45, 8, v151
	v_ashrrev_i32_e32 v233, 31, v232
	v_lshlrev_b64 v[232:233], 1, v[232:233]
	v_or_b32_e32 v234, 16, v166
	v_ashrrev_i32_e32 v235, 31, v234
	v_lshlrev_b64 v[236:237], 14, v[234:235]
	v_lshl_add_u64 v[236:237], s[8:9], 0, v[236:237]
	v_lshl_add_u64 v[236:237], v[236:237], 0, v[232:233]
	global_load_dwordx4 v[176:179], v[236:237], off
	v_lshl_add_u32 v166, s22, 8, v1
	v_lshl_or_b32 v232, s45, 8, v151
	v_ashrrev_i32_e32 v233, 31, v232
	v_lshlrev_b64 v[232:233], 1, v[232:233]
	v_or_b32_e32 v234, 16, v166
	v_ashrrev_i32_e32 v235, 31, v234
	v_lshlrev_b64 v[236:237], 14, v[234:235]
	v_lshl_add_u64 v[236:237], s[8:9], 0, v[236:237]
	v_lshl_add_u64 v[236:237], v[236:237], 0, v[232:233]
	global_load_dwordx4 v[180:183], v[236:237], off offset:256
	v_lshl_add_u32 v166, s22, 8, v1
	v_lshl_or_b32 v232, s45, 8, v151
	v_ashrrev_i32_e32 v233, 31, v232
	v_lshlrev_b64 v[232:233], 1, v[232:233]
	v_or_b32_e32 v234, 32, v166
	v_ashrrev_i32_e32 v235, 31, v234
	v_lshlrev_b64 v[236:237], 14, v[234:235]
	v_lshl_add_u64 v[236:237], s[8:9], 0, v[236:237]
	v_lshl_add_u64 v[236:237], v[236:237], 0, v[232:233]
	global_load_dwordx4 v[184:187], v[236:237], off
	v_lshl_add_u32 v166, s22, 8, v1
	v_lshl_or_b32 v232, s45, 8, v151
	v_ashrrev_i32_e32 v233, 31, v232
	v_lshlrev_b64 v[232:233], 1, v[232:233]
	v_or_b32_e32 v234, 32, v166
	v_ashrrev_i32_e32 v235, 31, v234
	v_lshlrev_b64 v[236:237], 14, v[234:235]
	v_lshl_add_u64 v[236:237], s[8:9], 0, v[236:237]
	v_lshl_add_u64 v[236:237], v[236:237], 0, v[232:233]
	global_load_dwordx4 v[188:191], v[236:237], off offset:256
	v_lshl_add_u32 v166, s22, 8, v1
	v_lshl_or_b32 v232, s45, 8, v151
	v_ashrrev_i32_e32 v233, 31, v232
	v_lshlrev_b64 v[232:233], 1, v[232:233]
	v_or_b32_e32 v234, 48, v166
	v_ashrrev_i32_e32 v235, 31, v234
	v_lshlrev_b64 v[236:237], 14, v[234:235]
	v_lshl_add_u64 v[236:237], s[8:9], 0, v[236:237]
	v_lshl_add_u64 v[236:237], v[236:237], 0, v[232:233]
	global_load_dwordx4 v[192:195], v[236:237], off
	v_lshl_add_u32 v166, s22, 8, v1
	v_lshl_or_b32 v232, s45, 8, v151
	v_ashrrev_i32_e32 v233, 31, v232
	v_lshlrev_b64 v[232:233], 1, v[232:233]
	v_or_b32_e32 v234, 48, v166
	v_ashrrev_i32_e32 v235, 31, v234
	v_lshlrev_b64 v[236:237], 14, v[234:235]
	v_lshl_add_u64 v[236:237], s[8:9], 0, v[236:237]
	v_lshl_add_u64 v[236:237], v[236:237], 0, v[232:233]
	global_load_dwordx4 v[196:199], v[236:237], off offset:256
	v_lshl_add_u32 v166, s22, 8, v1
	v_lshl_or_b32 v232, s45, 8, v151
	v_ashrrev_i32_e32 v233, 31, v232
	v_lshlrev_b64 v[232:233], 1, v[232:233]
	v_add_u32_e32 v234, 0x80, v166
	v_ashrrev_i32_e32 v235, 31, v234
	v_lshlrev_b64 v[236:237], 14, v[234:235]
	v_lshl_add_u64 v[236:237], s[8:9], 0, v[236:237]
	v_lshl_add_u64 v[236:237], v[236:237], 0, v[232:233]
	global_load_dwordx4 v[200:203], v[236:237], off
	v_lshl_add_u32 v166, s22, 8, v1
	v_lshl_or_b32 v232, s45, 8, v151
	v_ashrrev_i32_e32 v233, 31, v232
	v_lshlrev_b64 v[232:233], 1, v[232:233]
	v_add_u32_e32 v234, 0x80, v166
	v_ashrrev_i32_e32 v235, 31, v234
	v_lshlrev_b64 v[236:237], 14, v[234:235]
	v_lshl_add_u64 v[236:237], s[8:9], 0, v[236:237]
	v_lshl_add_u64 v[236:237], v[236:237], 0, v[232:233]
	global_load_dwordx4 v[204:207], v[236:237], off offset:256
	v_lshl_add_u32 v166, s22, 8, v1
	v_lshl_or_b32 v232, s45, 8, v151
	v_ashrrev_i32_e32 v233, 31, v232
	v_lshlrev_b64 v[232:233], 1, v[232:233]
	v_add_u32_e32 v234, 0x90, v166
	v_ashrrev_i32_e32 v235, 31, v234
	v_lshlrev_b64 v[236:237], 14, v[234:235]
	v_lshl_add_u64 v[236:237], s[8:9], 0, v[236:237]
	v_lshl_add_u64 v[236:237], v[236:237], 0, v[232:233]
	global_load_dwordx4 v[208:211], v[236:237], off
	v_lshl_add_u32 v166, s22, 8, v1
	v_lshl_or_b32 v232, s45, 8, v151
	v_ashrrev_i32_e32 v233, 31, v232
	v_lshlrev_b64 v[232:233], 1, v[232:233]
	v_add_u32_e32 v234, 0x90, v166
	v_ashrrev_i32_e32 v235, 31, v234
	v_lshlrev_b64 v[236:237], 14, v[234:235]
	v_lshl_add_u64 v[236:237], s[8:9], 0, v[236:237]
	v_lshl_add_u64 v[236:237], v[236:237], 0, v[232:233]
	global_load_dwordx4 v[212:215], v[236:237], off offset:256
	v_lshl_add_u32 v166, s22, 8, v1
	v_lshl_or_b32 v232, s45, 8, v151
	v_ashrrev_i32_e32 v233, 31, v232
	v_lshlrev_b64 v[232:233], 1, v[232:233]
	v_add_u32_e32 v234, 0xa0, v166
	v_ashrrev_i32_e32 v235, 31, v234
	v_lshlrev_b64 v[236:237], 14, v[234:235]
	v_lshl_add_u64 v[236:237], s[8:9], 0, v[236:237]
	v_lshl_add_u64 v[236:237], v[236:237], 0, v[232:233]
	global_load_dwordx4 v[216:219], v[236:237], off
	v_lshl_add_u32 v166, s22, 8, v1
	v_lshl_or_b32 v232, s45, 8, v151
	v_ashrrev_i32_e32 v233, 31, v232
	v_lshlrev_b64 v[232:233], 1, v[232:233]
	v_add_u32_e32 v234, 0xa0, v166
	v_ashrrev_i32_e32 v235, 31, v234
	v_lshlrev_b64 v[236:237], 14, v[234:235]
	v_lshl_add_u64 v[236:237], s[8:9], 0, v[236:237]
	v_lshl_add_u64 v[236:237], v[236:237], 0, v[232:233]
	global_load_dwordx4 v[220:223], v[236:237], off offset:256
	v_lshl_add_u32 v166, s22, 8, v1
	v_lshl_or_b32 v232, s45, 8, v151
	v_ashrrev_i32_e32 v233, 31, v232
	v_lshlrev_b64 v[232:233], 1, v[232:233]
	v_add_u32_e32 v234, 0xb0, v166
	v_ashrrev_i32_e32 v235, 31, v234
	v_lshlrev_b64 v[236:237], 14, v[234:235]
	v_lshl_add_u64 v[236:237], s[8:9], 0, v[236:237]
	v_lshl_add_u64 v[236:237], v[236:237], 0, v[232:233]
	global_load_dwordx4 v[224:227], v[236:237], off
	v_lshl_add_u32 v166, s22, 8, v1
	v_lshl_or_b32 v232, s45, 8, v151
	v_ashrrev_i32_e32 v233, 31, v232
	v_lshlrev_b64 v[232:233], 1, v[232:233]
	v_add_u32_e32 v234, 0xb0, v166
	v_ashrrev_i32_e32 v235, 31, v234
	v_lshlrev_b64 v[236:237], 14, v[234:235]
	v_lshl_add_u64 v[236:237], s[8:9], 0, v[236:237]
	v_lshl_add_u64 v[236:237], v[236:237], 0, v[232:233]
	global_load_dwordx4 v[228:231], v[236:237], off offset:256
	s_nop 1
	s_waitcnt vmcnt(15)
	v_mov_b32_e32 v156, v168
	v_mov_b32_e32 v157, v169
	v_mov_b32_e32 v158, v170
	v_mov_b32_e32 v159, v171
	s_andn2_b64 vcc, exec, s[4:5]
	s_mov_b64 s[4:5], -1
	s_nop 0
	v_lshlrev_b32_e32 v155, 16, v156
	v_and_b32_e32 v156, 0xffff0000, v156
	v_lshlrev_b32_e32 v162, 16, v157
	v_and_b32_e32 v157, 0xffff0000, v157
	v_lshlrev_b32_e32 v164, 16, v159
	v_and_b32_e32 v159, 0xffff0000, v159
	v_lshlrev_b32_e32 v163, 16, v158
	v_and_b32_e32 v158, 0xffff0000, v158
	v_mul_f32_e32 v126, v126, v155
	v_mul_f32_e32 v127, v127, v156
	v_mul_f32_e32 v128, v128, v162
	v_mul_f32_e32 v129, v129, v157
	v_mul_f32_e32 v125, v125, v159
	v_mul_f32_e32 v155, v122, v163
	v_mul_f32_e32 v156, v123, v158
	v_mul_f32_e32 v157, v124, v164
	v_cvt_pk_bf16_f32 v122, v126, v127
	v_cvt_pk_bf16_f32 v123, v128, v129
	v_cvt_pk_bf16_f32 v124, v155, v156
	v_cvt_pk_bf16_f32 v125, v157, v125
	s_nop 1
	s_waitcnt vmcnt(14)
	v_mov_b32_e32 v126, v172
	v_mov_b32_e32 v127, v173
	v_mov_b32_e32 v128, v174
	v_mov_b32_e32 v129, v175
	v_or_b32_e32 v156, 16, v148
	v_lshlrev_b64 v[158:159], 13, v[148:149]
	v_ashrrev_i32_e32 v157, 31, v156
	v_lshl_add_u64 v[158:159], s[6:7], 0, v[158:159]
	v_lshlrev_b64 v[160:161], 14, v[156:157]
	v_lshl_add_u64 v[158:159], v[158:159], 0, v[146:147]
	v_lshl_add_u64 v[160:161], s[8:9], 0, v[160:161]
	global_store_dwordx4 v[158:159], v[122:125], off
	v_lshl_add_u64 v[160:161], v[160:161], 0, v[146:147]
	s_nop 0
	v_lshlrev_b32_e32 v122, 16, v126
	v_and_b32_e32 v123, 0xffff0000, v126
	v_lshlrev_b32_e32 v124, 16, v127
	v_and_b32_e32 v125, 0xffff0000, v127
	v_lshlrev_b32_e32 v126, 16, v128
	v_and_b32_e32 v127, 0xffff0000, v128
	v_lshlrev_b32_e32 v128, 16, v129
	v_and_b32_e32 v129, 0xffff0000, v129
	v_mul_f32_e32 v118, v118, v122
	v_mul_f32_e32 v119, v119, v123
	v_mul_f32_e32 v120, v120, v124
	v_mul_f32_e32 v121, v121, v125
	v_mul_f32_e32 v113, v113, v129
	v_mul_f32_e32 v122, v110, v126
	v_mul_f32_e32 v123, v111, v127
	v_mul_f32_e32 v124, v112, v128
	v_cvt_pk_bf16_f32 v110, v118, v119
	v_cvt_pk_bf16_f32 v111, v120, v121
	v_cvt_pk_bf16_f32 v112, v122, v123
	v_cvt_pk_bf16_f32 v113, v124, v113
	s_nop 1
	s_waitcnt vmcnt(14)
	v_mov_b32_e32 v118, v176
	v_mov_b32_e32 v119, v177
	v_mov_b32_e32 v120, v178
	v_mov_b32_e32 v121, v179
	s_nop 0
	global_store_dwordx4 v[158:159], v[110:113], off offset:256
	s_nop 0
	s_nop 0
	v_lshlrev_b32_e32 v110, 16, v118
	v_and_b32_e32 v111, 0xffff0000, v118
	v_lshlrev_b32_e32 v112, 16, v119
	v_and_b32_e32 v113, 0xffff0000, v119
	v_lshlrev_b32_e32 v118, 16, v120
	v_and_b32_e32 v119, 0xffff0000, v120
	v_lshlrev_b32_e32 v120, 16, v121
	v_and_b32_e32 v121, 0xffff0000, v121
	v_mul_f32_e32 v110, v114, v110
	v_mul_f32_e32 v111, v115, v111
	v_mul_f32_e32 v112, v116, v112
	v_mul_f32_e32 v113, v117, v113
	v_mul_f32_e32 v109, v109, v121
	v_mul_f32_e32 v114, v106, v118
	v_mul_f32_e32 v115, v107, v119
	v_mul_f32_e32 v116, v108, v120
	v_cvt_pk_bf16_f32 v106, v110, v111
	v_cvt_pk_bf16_f32 v107, v112, v113
	v_cvt_pk_bf16_f32 v108, v114, v115
	v_cvt_pk_bf16_f32 v109, v116, v109
	s_nop 1
	s_waitcnt vmcnt(14)
	v_mov_b32_e32 v110, v180
	v_mov_b32_e32 v111, v181
	v_mov_b32_e32 v112, v182
	v_mov_b32_e32 v113, v183
	v_or_b32_e32 v114, 32, v148
	v_lshlrev_b64 v[116:117], 13, v[156:157]
	v_ashrrev_i32_e32 v115, 31, v114
	v_lshl_add_u64 v[116:117], s[6:7], 0, v[116:117]
	v_lshlrev_b64 v[118:119], 14, v[114:115]
	v_lshl_add_u64 v[116:117], v[116:117], 0, v[146:147]
	v_lshl_add_u64 v[118:119], s[8:9], 0, v[118:119]
	global_store_dwordx4 v[116:117], v[106:109], off
	v_lshl_add_u64 v[118:119], v[118:119], 0, v[146:147]
	s_nop 0
	v_lshlrev_b32_e32 v106, 16, v110
	v_and_b32_e32 v107, 0xffff0000, v110
	v_lshlrev_b32_e32 v108, 16, v111
	v_and_b32_e32 v109, 0xffff0000, v111
	v_lshlrev_b32_e32 v110, 16, v112
	v_and_b32_e32 v111, 0xffff0000, v112
	v_lshlrev_b32_e32 v112, 16, v113
	v_and_b32_e32 v113, 0xffff0000, v113
	v_mul_f32_e32 v102, v102, v106
	v_mul_f32_e32 v103, v103, v107
	v_mul_f32_e32 v104, v104, v108
	v_mul_f32_e32 v105, v105, v109
	v_mul_f32_e32 v97, v97, v113
	v_mul_f32_e32 v106, v94, v110
	v_mul_f32_e32 v107, v95, v111
	v_mul_f32_e32 v108, v96, v112
	v_cvt_pk_bf16_f32 v94, v102, v103
	v_cvt_pk_bf16_f32 v95, v104, v105
	v_cvt_pk_bf16_f32 v96, v106, v107
	v_cvt_pk_bf16_f32 v97, v108, v97
	s_nop 1
	s_waitcnt vmcnt(14)
	v_mov_b32_e32 v102, v184
	v_mov_b32_e32 v103, v185
	v_mov_b32_e32 v104, v186
	v_mov_b32_e32 v105, v187
	s_nop 0
	global_store_dwordx4 v[116:117], v[94:97], off offset:256
	s_nop 0
	s_nop 0
	v_lshlrev_b32_e32 v94, 16, v102
	v_and_b32_e32 v95, 0xffff0000, v102
	v_lshlrev_b32_e32 v96, 16, v103
	v_and_b32_e32 v97, 0xffff0000, v103
	v_lshlrev_b32_e32 v102, 16, v104
	v_and_b32_e32 v103, 0xffff0000, v104
	v_lshlrev_b32_e32 v104, 16, v105
	v_and_b32_e32 v105, 0xffff0000, v105
	v_mul_f32_e32 v94, v98, v94
	v_mul_f32_e32 v95, v99, v95
	v_mul_f32_e32 v96, v100, v96
	v_mul_f32_e32 v97, v101, v97
	v_mul_f32_e32 v93, v93, v105
	v_mul_f32_e32 v98, v90, v102
	v_mul_f32_e32 v99, v91, v103
	v_mul_f32_e32 v100, v92, v104
	v_cvt_pk_bf16_f32 v90, v94, v95
	v_cvt_pk_bf16_f32 v91, v96, v97
	v_cvt_pk_bf16_f32 v92, v98, v99
	v_cvt_pk_bf16_f32 v93, v100, v93
	s_nop 1
	s_waitcnt vmcnt(14)
	v_mov_b32_e32 v94, v188
	v_mov_b32_e32 v95, v189
	v_mov_b32_e32 v96, v190
	v_mov_b32_e32 v97, v191
	v_or_b32_e32 v98, 48, v148
	v_lshlrev_b64 v[100:101], 13, v[114:115]
	v_ashrrev_i32_e32 v99, 31, v98
	v_lshl_add_u64 v[100:101], s[6:7], 0, v[100:101]
	v_lshlrev_b64 v[102:103], 14, v[98:99]
	v_lshl_add_u64 v[100:101], v[100:101], 0, v[146:147]
	v_lshl_add_u64 v[102:103], s[8:9], 0, v[102:103]
	global_store_dwordx4 v[100:101], v[90:93], off
	v_lshl_add_u64 v[102:103], v[102:103], 0, v[146:147]
	s_nop 0
	v_lshlrev_b32_e32 v90, 16, v94
	v_and_b32_e32 v91, 0xffff0000, v94
	v_lshlrev_b32_e32 v92, 16, v95
	v_and_b32_e32 v93, 0xffff0000, v95
	v_lshlrev_b32_e32 v94, 16, v96
	v_and_b32_e32 v95, 0xffff0000, v96
	v_lshlrev_b32_e32 v96, 16, v97
	v_and_b32_e32 v97, 0xffff0000, v97
	v_mul_f32_e32 v86, v86, v90
	v_mul_f32_e32 v87, v87, v91
	v_mul_f32_e32 v88, v88, v92
	v_mul_f32_e32 v89, v89, v93
	v_mul_f32_e32 v81, v81, v97
	v_mul_f32_e32 v90, v78, v94
	v_mul_f32_e32 v91, v79, v95
	v_mul_f32_e32 v92, v80, v96
	v_cvt_pk_bf16_f32 v78, v86, v87
	v_cvt_pk_bf16_f32 v79, v88, v89
	v_cvt_pk_bf16_f32 v80, v90, v91
	v_cvt_pk_bf16_f32 v81, v92, v81
	s_nop 1
	s_waitcnt vmcnt(14)
	v_mov_b32_e32 v86, v192
	v_mov_b32_e32 v87, v193
	v_mov_b32_e32 v88, v194
	v_mov_b32_e32 v89, v195
	s_nop 0
	global_store_dwordx4 v[100:101], v[78:81], off offset:256
	s_nop 0
	s_nop 0
	v_lshlrev_b32_e32 v78, 16, v86
	v_and_b32_e32 v79, 0xffff0000, v86
	v_lshlrev_b32_e32 v80, 16, v87
	v_and_b32_e32 v81, 0xffff0000, v87
	v_lshlrev_b32_e32 v86, 16, v88
	v_and_b32_e32 v87, 0xffff0000, v88
	v_lshlrev_b32_e32 v88, 16, v89
	v_and_b32_e32 v89, 0xffff0000, v89
	v_mul_f32_e32 v78, v82, v78
	v_mul_f32_e32 v79, v83, v79
	v_mul_f32_e32 v80, v84, v80
	v_mul_f32_e32 v81, v85, v81
	v_mul_f32_e32 v77, v77, v89
	v_mul_f32_e32 v82, v74, v86
	v_mul_f32_e32 v83, v75, v87
	v_mul_f32_e32 v84, v76, v88
	v_cvt_pk_bf16_f32 v74, v78, v79
	v_cvt_pk_bf16_f32 v75, v80, v81
	v_cvt_pk_bf16_f32 v76, v82, v83
	v_cvt_pk_bf16_f32 v77, v84, v77
	s_nop 1
	s_waitcnt vmcnt(14)
	v_mov_b32_e32 v78, v196
	v_mov_b32_e32 v79, v197
	v_mov_b32_e32 v80, v198
	v_mov_b32_e32 v81, v199
	v_add_u32_e32 v82, 0x80, v148
	v_lshlrev_b64 v[84:85], 13, v[98:99]
	v_ashrrev_i32_e32 v83, 31, v82
	v_lshl_add_u64 v[84:85], s[6:7], 0, v[84:85]
	v_lshlrev_b64 v[86:87], 14, v[82:83]
	v_lshl_add_u64 v[84:85], v[84:85], 0, v[146:147]
	v_lshl_add_u64 v[86:87], s[8:9], 0, v[86:87]
	global_store_dwordx4 v[84:85], v[74:77], off
	v_lshl_add_u64 v[86:87], v[86:87], 0, v[146:147]
	s_nop 0
	v_lshlrev_b32_e32 v74, 16, v78
	v_and_b32_e32 v75, 0xffff0000, v78
	v_lshlrev_b32_e32 v76, 16, v79
	v_and_b32_e32 v77, 0xffff0000, v79
	v_lshlrev_b32_e32 v78, 16, v80
	v_and_b32_e32 v79, 0xffff0000, v80
	v_lshlrev_b32_e32 v80, 16, v81
	v_and_b32_e32 v81, 0xffff0000, v81
	v_mul_f32_e32 v70, v70, v74
	v_mul_f32_e32 v71, v71, v75
	v_mul_f32_e32 v72, v72, v76
	v_mul_f32_e32 v73, v73, v77
	v_mul_f32_e32 v69, v69, v81
	v_mul_f32_e32 v74, v66, v78
	v_mul_f32_e32 v75, v67, v79
	v_mul_f32_e32 v76, v68, v80
	v_cvt_pk_bf16_f32 v66, v70, v71
	v_cvt_pk_bf16_f32 v67, v72, v73
	v_cvt_pk_bf16_f32 v68, v74, v75
	v_cvt_pk_bf16_f32 v69, v76, v69
	s_nop 1
	s_waitcnt vmcnt(14)
	v_mov_b32_e32 v70, v200
	v_mov_b32_e32 v71, v201
	v_mov_b32_e32 v72, v202
	v_mov_b32_e32 v73, v203
	s_nop 0
	global_store_dwordx4 v[84:85], v[66:69], off offset:256
	s_nop 0
	s_nop 0
	v_lshlrev_b32_e32 v66, 16, v70
	v_and_b32_e32 v67, 0xffff0000, v70
	v_lshlrev_b32_e32 v68, 16, v71
	v_and_b32_e32 v69, 0xffff0000, v71
	v_lshlrev_b32_e32 v70, 16, v72
	v_and_b32_e32 v71, 0xffff0000, v72
	v_lshlrev_b32_e32 v72, 16, v73
	v_and_b32_e32 v73, 0xffff0000, v73
	v_mul_f32_e32 v62, v62, v66
	v_mul_f32_e32 v63, v63, v67
	v_mul_f32_e32 v64, v64, v68
	v_mul_f32_e32 v65, v65, v69
	v_mul_f32_e32 v61, v61, v73
	v_mul_f32_e32 v66, v58, v70
	v_mul_f32_e32 v67, v59, v71
	v_mul_f32_e32 v68, v60, v72
	v_cvt_pk_bf16_f32 v58, v62, v63
	v_cvt_pk_bf16_f32 v59, v64, v65
	v_cvt_pk_bf16_f32 v60, v66, v67
	v_cvt_pk_bf16_f32 v61, v68, v61
	s_nop 1
	s_waitcnt vmcnt(14)
	v_mov_b32_e32 v62, v204
	v_mov_b32_e32 v63, v205
	v_mov_b32_e32 v64, v206
	v_mov_b32_e32 v65, v207
	v_add_u32_e32 v66, 0x90, v148
	v_lshlrev_b64 v[68:69], 13, v[82:83]
	v_ashrrev_i32_e32 v67, 31, v66
	v_lshl_add_u64 v[68:69], s[6:7], 0, v[68:69]
	v_lshlrev_b64 v[70:71], 14, v[66:67]
	v_lshl_add_u64 v[68:69], v[68:69], 0, v[146:147]
	v_lshl_add_u64 v[70:71], s[8:9], 0, v[70:71]
	global_store_dwordx4 v[68:69], v[58:61], off
	v_lshl_add_u64 v[70:71], v[70:71], 0, v[146:147]
	s_nop 0
	v_lshlrev_b32_e32 v58, 16, v62
	v_and_b32_e32 v59, 0xffff0000, v62
	v_lshlrev_b32_e32 v60, 16, v63
	v_and_b32_e32 v61, 0xffff0000, v63
	v_lshlrev_b32_e32 v62, 16, v64
	v_and_b32_e32 v63, 0xffff0000, v64
	v_lshlrev_b32_e32 v64, 16, v65
	v_and_b32_e32 v65, 0xffff0000, v65
	v_mul_f32_e32 v54, v54, v58
	v_mul_f32_e32 v55, v55, v59
	v_mul_f32_e32 v56, v56, v60
	v_mul_f32_e32 v57, v57, v61
	v_mul_f32_e32 v49, v49, v65
	v_mul_f32_e32 v58, v46, v62
	v_mul_f32_e32 v59, v47, v63
	v_mul_f32_e32 v60, v48, v64
	v_cvt_pk_bf16_f32 v46, v54, v55
	v_cvt_pk_bf16_f32 v47, v56, v57
	v_cvt_pk_bf16_f32 v48, v58, v59
	v_cvt_pk_bf16_f32 v49, v60, v49
	s_nop 1
	s_waitcnt vmcnt(14)
	v_mov_b32_e32 v54, v208
	v_mov_b32_e32 v55, v209
	v_mov_b32_e32 v56, v210
	v_mov_b32_e32 v57, v211
	s_nop 0
	global_store_dwordx4 v[68:69], v[46:49], off offset:256
	s_nop 0
	s_nop 0
	v_lshlrev_b32_e32 v46, 16, v54
	v_and_b32_e32 v47, 0xffff0000, v54
	v_lshlrev_b32_e32 v48, 16, v55
	v_and_b32_e32 v49, 0xffff0000, v55
	v_lshlrev_b32_e32 v54, 16, v56
	v_and_b32_e32 v55, 0xffff0000, v56
	v_lshlrev_b32_e32 v56, 16, v57
	v_and_b32_e32 v57, 0xffff0000, v57
	v_mul_f32_e32 v46, v50, v46
	v_mul_f32_e32 v47, v51, v47
	v_mul_f32_e32 v48, v52, v48
	v_mul_f32_e32 v49, v53, v49
	v_mul_f32_e32 v45, v45, v57
	v_mul_f32_e32 v50, v42, v54
	v_mul_f32_e32 v51, v43, v55
	v_mul_f32_e32 v52, v44, v56
	v_cvt_pk_bf16_f32 v42, v46, v47
	v_cvt_pk_bf16_f32 v43, v48, v49
	v_cvt_pk_bf16_f32 v44, v50, v51
	v_cvt_pk_bf16_f32 v45, v52, v45
	s_nop 1
	s_waitcnt vmcnt(14)
	v_mov_b32_e32 v46, v212
	v_mov_b32_e32 v47, v213
	v_mov_b32_e32 v48, v214
	v_mov_b32_e32 v49, v215
	v_add_u32_e32 v50, 0xa0, v148
	v_lshlrev_b64 v[52:53], 13, v[66:67]
	v_ashrrev_i32_e32 v51, 31, v50
	v_lshl_add_u64 v[52:53], s[6:7], 0, v[52:53]
	v_lshlrev_b64 v[54:55], 14, v[50:51]
	v_lshl_add_u64 v[52:53], v[52:53], 0, v[146:147]
	v_lshl_add_u64 v[54:55], s[8:9], 0, v[54:55]
	global_store_dwordx4 v[52:53], v[42:45], off
	v_lshl_add_u64 v[54:55], v[54:55], 0, v[146:147]
	s_nop 0
	v_lshlrev_b32_e32 v42, 16, v46
	v_and_b32_e32 v43, 0xffff0000, v46
	v_lshlrev_b32_e32 v44, 16, v47
	v_and_b32_e32 v45, 0xffff0000, v47
	v_lshlrev_b32_e32 v46, 16, v48
	v_and_b32_e32 v47, 0xffff0000, v48
	v_lshlrev_b32_e32 v48, 16, v49
	v_and_b32_e32 v49, 0xffff0000, v49
	v_mul_f32_e32 v38, v38, v42
	v_mul_f32_e32 v39, v39, v43
	v_mul_f32_e32 v40, v40, v44
	v_mul_f32_e32 v41, v41, v45
	v_mul_f32_e32 v33, v33, v49
	v_mul_f32_e32 v42, v30, v46
	v_mul_f32_e32 v43, v31, v47
	v_mul_f32_e32 v44, v32, v48
	v_cvt_pk_bf16_f32 v30, v38, v39
	v_cvt_pk_bf16_f32 v31, v40, v41
	v_cvt_pk_bf16_f32 v32, v42, v43
	v_cvt_pk_bf16_f32 v33, v44, v33
	s_nop 1
	s_waitcnt vmcnt(14)
	v_mov_b32_e32 v38, v216
	v_mov_b32_e32 v39, v217
	v_mov_b32_e32 v40, v218
	v_mov_b32_e32 v41, v219
	s_nop 0
	global_store_dwordx4 v[52:53], v[30:33], off offset:256
	s_nop 0
	s_nop 0
	v_lshlrev_b32_e32 v30, 16, v38
	v_and_b32_e32 v31, 0xffff0000, v38
	v_lshlrev_b32_e32 v32, 16, v39
	v_and_b32_e32 v33, 0xffff0000, v39
	v_lshlrev_b32_e32 v38, 16, v40
	v_and_b32_e32 v39, 0xffff0000, v40
	v_lshlrev_b32_e32 v40, 16, v41
	v_and_b32_e32 v41, 0xffff0000, v41
	v_mul_f32_e32 v30, v34, v30
	v_mul_f32_e32 v31, v35, v31
	v_mul_f32_e32 v32, v36, v32
	v_mul_f32_e32 v33, v37, v33
	v_mul_f32_e32 v29, v29, v41
	v_mul_f32_e32 v34, v26, v38
	v_mul_f32_e32 v35, v27, v39
	v_mul_f32_e32 v36, v28, v40
	v_cvt_pk_bf16_f32 v26, v30, v31
	v_cvt_pk_bf16_f32 v27, v32, v33
	v_cvt_pk_bf16_f32 v28, v34, v35
	v_cvt_pk_bf16_f32 v29, v36, v29
	s_nop 1
	s_waitcnt vmcnt(14)
	v_mov_b32_e32 v30, v220
	v_mov_b32_e32 v31, v221
	v_mov_b32_e32 v32, v222
	v_mov_b32_e32 v33, v223
	v_add_u32_e32 v34, 0xb0, v148
	v_lshlrev_b64 v[36:37], 13, v[50:51]
	v_ashrrev_i32_e32 v35, 31, v34
	v_lshl_add_u64 v[36:37], s[6:7], 0, v[36:37]
	v_lshlrev_b64 v[38:39], 14, v[34:35]
	v_lshl_add_u64 v[36:37], v[36:37], 0, v[146:147]
	v_lshl_add_u64 v[38:39], s[8:9], 0, v[38:39]
	global_store_dwordx4 v[36:37], v[26:29], off
	v_lshl_add_u64 v[38:39], v[38:39], 0, v[146:147]
	s_nop 0
	v_lshlrev_b32_e32 v26, 16, v30
	v_and_b32_e32 v27, 0xffff0000, v30
	v_lshlrev_b32_e32 v28, 16, v31
	v_and_b32_e32 v29, 0xffff0000, v31
	v_lshlrev_b32_e32 v30, 16, v32
	v_and_b32_e32 v31, 0xffff0000, v32
	v_lshlrev_b32_e32 v32, 16, v33
	v_and_b32_e32 v33, 0xffff0000, v33
	v_mul_f32_e32 v22, v22, v26
	v_mul_f32_e32 v23, v23, v27
	v_mul_f32_e32 v24, v24, v28
	v_mul_f32_e32 v25, v25, v29
	v_mul_f32_e32 v17, v17, v33
	v_mul_f32_e32 v26, v14, v30
	v_mul_f32_e32 v27, v15, v31
	v_mul_f32_e32 v28, v16, v32
	v_cvt_pk_bf16_f32 v14, v22, v23
	v_cvt_pk_bf16_f32 v15, v24, v25
	v_cvt_pk_bf16_f32 v16, v26, v27
	v_cvt_pk_bf16_f32 v17, v28, v17
	s_nop 1
	s_waitcnt vmcnt(14)
	v_mov_b32_e32 v22, v224
	v_mov_b32_e32 v23, v225
	v_mov_b32_e32 v24, v226
	v_mov_b32_e32 v25, v227
	s_nop 0
	global_store_dwordx4 v[36:37], v[14:17], off offset:256
	s_nop 0
	s_nop 0
	v_lshlrev_b32_e32 v14, 16, v22
	v_and_b32_e32 v15, 0xffff0000, v22
	v_lshlrev_b32_e32 v16, 16, v23
	v_and_b32_e32 v17, 0xffff0000, v23
	v_lshlrev_b32_e32 v22, 16, v24
	v_and_b32_e32 v23, 0xffff0000, v24
	v_lshlrev_b32_e32 v24, 16, v25
	v_and_b32_e32 v25, 0xffff0000, v25
	v_mul_f32_e32 v14, v18, v14
	v_mul_f32_e32 v15, v19, v15
	v_mul_f32_e32 v16, v20, v16
	v_mul_f32_e32 v17, v21, v17
	v_mul_f32_e32 v13, v13, v25
	v_mul_f32_e32 v18, v10, v22
	v_mul_f32_e32 v19, v11, v23
	v_mul_f32_e32 v20, v12, v24
	v_cvt_pk_bf16_f32 v10, v14, v15
	v_cvt_pk_bf16_f32 v11, v16, v17
	v_cvt_pk_bf16_f32 v12, v18, v19
	v_cvt_pk_bf16_f32 v13, v20, v13
	s_nop 1
	s_waitcnt vmcnt(14)
	v_mov_b32_e32 v14, v228
	v_mov_b32_e32 v15, v229
	v_mov_b32_e32 v16, v230
	v_mov_b32_e32 v17, v231
	v_lshlrev_b64 v[18:19], 13, v[34:35]
	v_lshl_add_u64 v[18:19], s[6:7], 0, v[18:19]
	v_lshl_add_u64 v[18:19], v[18:19], 0, v[146:147]
	global_store_dwordx4 v[18:19], v[10:13], off
	s_nop 0
	s_nop 0
	v_lshlrev_b32_e32 v10, 16, v14
	v_and_b32_e32 v11, 0xffff0000, v14
	v_lshlrev_b32_e32 v12, 16, v15
	v_and_b32_e32 v13, 0xffff0000, v15
	v_lshlrev_b32_e32 v14, 16, v16
	v_and_b32_e32 v15, 0xffff0000, v16
	v_lshlrev_b32_e32 v16, 16, v17
	v_and_b32_e32 v17, 0xffff0000, v17
	v_mul_f32_e32 v5, v5, v17
	v_mul_f32_e32 v6, v6, v10
	v_mul_f32_e32 v7, v7, v11
	v_mul_f32_e32 v8, v8, v12
	v_mul_f32_e32 v9, v9, v13
	v_mul_f32_e32 v10, v2, v14
	v_mul_f32_e32 v11, v3, v15
	v_mul_f32_e32 v12, v4, v16
	v_cvt_pk_bf16_f32 v2, v6, v7
	v_cvt_pk_bf16_f32 v3, v8, v9
	v_cvt_pk_bf16_f32 v4, v10, v11
	v_cvt_pk_bf16_f32 v5, v12, v5
	global_store_dwordx4 v[18:19], v[2:5], off offset:256
	s_cbranch_vccnz .LBB0_1554
	s_andn2_b64 vcc, exec, s[0:1]
	s_cbranch_vccnz .LBB0_1553
	s_barrier
	s_branch .LBB0_1553

.LBB0_1645:
	v_lshl_add_u32 v148, s26, 8, v1
	v_lshl_or_b32 v146, s50, 8, v151
	v_ashrrev_i32_e32 v149, 31, v148
	v_ashrrev_i32_e32 v147, 31, v146
	v_lshlrev_b64 v[164:165], 13, v[148:149]
	v_lshlrev_b64 v[146:147], 1, v[146:147]
	v_lshl_add_u64 v[156:157], s[8:9], 0, v[164:165]
	v_lshl_add_u64 v[166:167], v[156:157], 0, v[146:147]
	v_lshlrev_b64 v[156:157], 14, v[148:149]
	v_lshl_add_u64 v[156:157], s[10:11], 0, v[156:157]
	v_lshl_add_u64 v[168:169], v[156:157], 0, v[146:147]
	v_add_co_u32_e32 v160, vcc, s43, v168
	s_mov_b32 s2, s86
	s_nop 0
	v_addc_co_u32_e32 v161, vcc, 0, v169, vcc
	v_lshl_add_u32 v240, s26, 8, v1
	v_lshl_or_b32 v242, s50, 8, v151
	v_ashrrev_i32_e32 v241, 31, v240
	v_ashrrev_i32_e32 v243, 31, v242
	v_lshlrev_b64 v[244:245], 13, v[240:241]
	v_lshlrev_b64 v[242:243], 1, v[242:243]
	v_lshl_add_u64 v[246:247], s[8:9], 0, v[244:245]
	v_lshl_add_u64 v[248:249], v[246:247], 0, v[242:243]
	global_load_dwordx4 v[176:179], v[248:249], off
	v_lshl_add_u32 v240, s26, 8, v1
	v_lshl_or_b32 v242, s50, 8, v151
	v_ashrrev_i32_e32 v241, 31, v240
	v_ashrrev_i32_e32 v243, 31, v242
	v_lshlrev_b64 v[242:243], 1, v[242:243]
	v_lshlrev_b64 v[244:245], 14, v[240:241]
	v_lshl_add_u64 v[244:245], s[10:11], 0, v[244:245]
	v_lshl_add_u64 v[246:247], v[244:245], 0, v[242:243]
	v_add_co_u32_e32 v248, vcc, s43, v246
	s_nop 1
	v_addc_co_u32_e32 v249, vcc, 0, v247, vcc
	global_load_dwordx4 v[180:183], v[248:249], off
	v_lshl_add_u32 v240, s26, 8, v1
	v_lshl_or_b32 v242, s50, 8, v151
	v_ashrrev_i32_e32 v241, 31, v240
	v_ashrrev_i32_e32 v243, 31, v242
	v_lshlrev_b64 v[244:245], 13, v[240:241]
	v_lshlrev_b64 v[242:243], 1, v[242:243]
	v_lshl_add_u64 v[246:247], s[8:9], 0, v[244:245]
	v_lshl_add_u64 v[248:249], v[246:247], 0, v[242:243]
	global_load_dwordx4 v[184:187], v[248:249], off offset:256
	v_lshl_add_u32 v240, s26, 8, v1
	v_lshl_or_b32 v242, s50, 8, v151
	v_ashrrev_i32_e32 v241, 31, v240
	v_ashrrev_i32_e32 v243, 31, v242
	v_lshlrev_b64 v[242:243], 1, v[242:243]
	v_lshlrev_b64 v[244:245], 14, v[240:241]
	v_lshl_add_u64 v[244:245], s[10:11], 0, v[244:245]
	v_lshl_add_u64 v[246:247], v[244:245], 0, v[242:243]
	v_lshl_add_u64 v[246:247], v[246:247], 0, s[16:17]
	global_load_dwordx4 v[188:191], v[246:247], off offset:256
	v_lshl_add_u32 v240, s26, 8, v1
	v_lshl_or_b32 v242, s50, 8, v151
	v_ashrrev_i32_e32 v243, 31, v242
	v_lshlrev_b64 v[242:243], 1, v[242:243]
	v_or_b32_e32 v244, 16, v240
	v_ashrrev_i32_e32 v245, 31, v244
	v_lshlrev_b64 v[246:247], 13, v[244:245]
	v_lshl_add_u64 v[248:249], s[8:9], 0, v[246:247]
	v_lshl_add_u64 v[248:249], v[248:249], 0, v[242:243]
	global_load_dwordx4 v[192:195], v[248:249], off
	v_lshl_add_u32 v240, s26, 8, v1
	v_lshl_or_b32 v242, s50, 8, v151
	v_ashrrev_i32_e32 v243, 31, v242
	v_lshlrev_b64 v[242:243], 1, v[242:243]
	v_or_b32_e32 v244, 16, v240
	v_ashrrev_i32_e32 v245, 31, v244
	v_lshlrev_b64 v[244:245], 14, v[244:245]
	v_lshl_add_u64 v[244:245], s[10:11], 0, v[244:245]
	v_lshl_add_u64 v[244:245], v[244:245], 0, v[242:243]
	v_add_co_u32_e32 v246, vcc, s43, v244
	s_nop 1
	v_addc_co_u32_e32 v247, vcc, 0, v245, vcc
	global_load_dwordx4 v[196:199], v[246:247], off
	v_lshl_add_u32 v240, s26, 8, v1
	v_lshl_or_b32 v242, s50, 8, v151
	v_ashrrev_i32_e32 v243, 31, v242
	v_lshlrev_b64 v[242:243], 1, v[242:243]
	v_or_b32_e32 v244, 16, v240
	v_ashrrev_i32_e32 v245, 31, v244
	v_lshlrev_b64 v[246:247], 13, v[244:245]
	v_lshl_add_u64 v[248:249], s[8:9], 0, v[246:247]
	v_lshl_add_u64 v[248:249], v[248:249], 0, v[242:243]
	global_load_dwordx4 v[200:203], v[248:249], off offset:256
	v_lshl_add_u32 v240, s26, 8, v1
	v_lshl_or_b32 v242, s50, 8, v151
	v_ashrrev_i32_e32 v243, 31, v242
	v_lshlrev_b64 v[242:243], 1, v[242:243]
	v_or_b32_e32 v244, 16, v240
	v_ashrrev_i32_e32 v245, 31, v244
	v_lshlrev_b64 v[244:245], 14, v[244:245]
	v_lshl_add_u64 v[244:245], s[10:11], 0, v[244:245]
	v_lshl_add_u64 v[244:245], v[244:245], 0, v[242:243]
	v_lshl_add_u64 v[246:247], v[244:245], 0, s[16:17]
	global_load_dwordx4 v[204:207], v[246:247], off offset:256
	v_lshl_add_u32 v240, s26, 8, v1
	v_lshl_or_b32 v242, s50, 8, v151
	v_ashrrev_i32_e32 v243, 31, v242
	v_lshlrev_b64 v[242:243], 1, v[242:243]
	v_or_b32_e32 v244, 32, v240
	v_ashrrev_i32_e32 v245, 31, v244
	v_lshlrev_b64 v[246:247], 13, v[244:245]
	v_lshl_add_u64 v[248:249], s[8:9], 0, v[246:247]
	v_lshl_add_u64 v[248:249], v[248:249], 0, v[242:243]
	global_load_dwordx4 v[208:211], v[248:249], off
	v_lshl_add_u32 v240, s26, 8, v1
	v_lshl_or_b32 v242, s50, 8, v151
	v_ashrrev_i32_e32 v243, 31, v242
	v_lshlrev_b64 v[242:243], 1, v[242:243]
	v_or_b32_e32 v244, 32, v240
	v_ashrrev_i32_e32 v245, 31, v244
	v_lshlrev_b64 v[244:245], 14, v[244:245]
	v_lshl_add_u64 v[244:245], s[10:11], 0, v[244:245]
	v_lshl_add_u64 v[244:245], v[244:245], 0, v[242:243]
	v_add_co_u32_e32 v246, vcc, s43, v244
	s_nop 1
	v_addc_co_u32_e32 v247, vcc, 0, v245, vcc
	global_load_dwordx4 v[212:215], v[246:247], off
	v_lshl_add_u32 v240, s26, 8, v1
	v_lshl_or_b32 v242, s50, 8, v151
	v_ashrrev_i32_e32 v243, 31, v242
	v_lshlrev_b64 v[242:243], 1, v[242:243]
	v_or_b32_e32 v244, 32, v240
	v_ashrrev_i32_e32 v245, 31, v244
	v_lshlrev_b64 v[246:247], 13, v[244:245]
	v_lshl_add_u64 v[248:249], s[8:9], 0, v[246:247]
	v_lshl_add_u64 v[248:249], v[248:249], 0, v[242:243]
	global_load_dwordx4 v[216:219], v[248:249], off offset:256
	v_lshl_add_u32 v240, s26, 8, v1
	v_lshl_or_b32 v242, s50, 8, v151
	v_ashrrev_i32_e32 v243, 31, v242
	v_lshlrev_b64 v[242:243], 1, v[242:243]
	v_or_b32_e32 v244, 32, v240
	v_ashrrev_i32_e32 v245, 31, v244
	v_lshlrev_b64 v[244:245], 14, v[244:245]
	v_lshl_add_u64 v[244:245], s[10:11], 0, v[244:245]
	v_lshl_add_u64 v[244:245], v[244:245], 0, v[242:243]
	v_lshl_add_u64 v[246:247], v[244:245], 0, s[16:17]
	global_load_dwordx4 v[220:223], v[246:247], off offset:256
	v_lshl_add_u32 v240, s26, 8, v1
	v_lshl_or_b32 v242, s50, 8, v151
	v_ashrrev_i32_e32 v243, 31, v242
	v_lshlrev_b64 v[242:243], 1, v[242:243]
	v_or_b32_e32 v244, 48, v240
	v_ashrrev_i32_e32 v245, 31, v244
	v_lshlrev_b64 v[246:247], 13, v[244:245]
	v_lshl_add_u64 v[248:249], s[8:9], 0, v[246:247]
	v_lshl_add_u64 v[248:249], v[248:249], 0, v[242:243]
	global_load_dwordx4 v[224:227], v[248:249], off
	v_lshl_add_u32 v240, s26, 8, v1
	v_lshl_or_b32 v242, s50, 8, v151
	v_ashrrev_i32_e32 v243, 31, v242
	v_lshlrev_b64 v[242:243], 1, v[242:243]
	v_or_b32_e32 v244, 48, v240
	v_ashrrev_i32_e32 v245, 31, v244
	v_lshlrev_b64 v[244:245], 14, v[244:245]
	v_lshl_add_u64 v[244:245], s[10:11], 0, v[244:245]
	v_lshl_add_u64 v[244:245], v[244:245], 0, v[242:243]
	v_add_co_u32_e32 v246, vcc, s43, v244
	s_nop 1
	v_addc_co_u32_e32 v247, vcc, 0, v245, vcc
	global_load_dwordx4 v[228:231], v[246:247], off
	v_lshl_add_u32 v240, s26, 8, v1
	v_lshl_or_b32 v242, s50, 8, v151
	v_ashrrev_i32_e32 v243, 31, v242
	v_lshlrev_b64 v[242:243], 1, v[242:243]
	v_or_b32_e32 v244, 48, v240
	v_ashrrev_i32_e32 v245, 31, v244
	v_lshlrev_b64 v[246:247], 13, v[244:245]
	v_lshl_add_u64 v[248:249], s[8:9], 0, v[246:247]
	v_lshl_add_u64 v[248:249], v[248:249], 0, v[242:243]
	global_load_dwordx4 v[232:235], v[248:249], off offset:256
	v_lshl_add_u32 v240, s26, 8, v1
	v_lshl_or_b32 v242, s50, 8, v151
	v_ashrrev_i32_e32 v243, 31, v242
	v_lshlrev_b64 v[242:243], 1, v[242:243]
	v_or_b32_e32 v244, 48, v240
	v_ashrrev_i32_e32 v245, 31, v244
	v_lshlrev_b64 v[244:245], 14, v[244:245]
	v_lshl_add_u64 v[244:245], s[10:11], 0, v[244:245]
	v_lshl_add_u64 v[244:245], v[244:245], 0, v[242:243]
	v_lshl_add_u64 v[246:247], v[244:245], 0, s[16:17]
	global_load_dwordx4 v[236:239], v[246:247], off offset:256
	s_nop 1
	s_waitcnt vmcnt(15)
	v_mov_b32_e32 v156, v176
	v_mov_b32_e32 v157, v177
	v_mov_b32_e32 v158, v178
	v_mov_b32_e32 v159, v179
	s_nop 1
	v_lshl_add_u32 v240, s26, 8, v1
	v_lshl_or_b32 v242, s50, 8, v151
	v_ashrrev_i32_e32 v243, 31, v242
	v_lshlrev_b64 v[242:243], 1, v[242:243]
	v_add_u32_e32 v244, 0x80, v240
	v_ashrrev_i32_e32 v245, 31, v244
	v_lshlrev_b64 v[246:247], 13, v[244:245]
	v_lshl_add_u64 v[248:249], s[8:9], 0, v[246:247]
	v_lshl_add_u64 v[248:249], v[248:249], 0, v[242:243]
	global_load_dwordx4 v[176:179], v[248:249], off
	s_nop 0
	s_nop 1
	s_waitcnt vmcnt(15)
	v_mov_b32_e32 v160, v180
	v_mov_b32_e32 v161, v181
	v_mov_b32_e32 v162, v182
	v_mov_b32_e32 v163, v183
	s_nop 1
	v_lshl_add_u32 v240, s26, 8, v1
	v_lshl_or_b32 v242, s50, 8, v151
	v_ashrrev_i32_e32 v243, 31, v242
	v_lshlrev_b64 v[242:243], 1, v[242:243]
	v_add_u32_e32 v244, 0x80, v240
	v_ashrrev_i32_e32 v245, 31, v244
	v_lshlrev_b64 v[244:245], 14, v[244:245]
	v_lshl_add_u64 v[244:245], s[10:11], 0, v[244:245]
	v_lshl_add_u64 v[244:245], v[244:245], 0, v[242:243]
	v_add_co_u32_e32 v246, vcc, s43, v244
	s_nop 1
	v_addc_co_u32_e32 v247, vcc, 0, v245, vcc
	global_load_dwordx4 v[180:183], v[246:247], off
	v_lshl_add_u64 v[168:169], v[168:169], 0, s[16:17]
	s_nop 0
	v_lshlrev_b32_e32 v149, 16, v156
	v_lshlrev_b32_e32 v155, 16, v160
	v_and_b32_e32 v156, 0xffff0000, v156
	v_and_b32_e32 v160, 0xffff0000, v160
	v_lshlrev_b32_e32 v170, 16, v157
	v_lshlrev_b32_e32 v171, 16, v161
	v_and_b32_e32 v157, 0xffff0000, v157
	v_and_b32_e32 v161, 0xffff0000, v161
	v_lshlrev_b32_e32 v172, 16, v158
	v_lshlrev_b32_e32 v173, 16, v162
	v_and_b32_e32 v158, 0xffff0000, v158
	v_and_b32_e32 v162, 0xffff0000, v162
	v_lshlrev_b32_e32 v174, 16, v159
	v_lshlrev_b32_e32 v175, 16, v163
	v_and_b32_e32 v159, 0xffff0000, v159
	v_and_b32_e32 v163, 0xffff0000, v163
	v_fmac_f32_e32 v156, v127, v160
	v_fmac_f32_e32 v157, v129, v161
	v_fmac_f32_e32 v158, v123, v162
	v_fmac_f32_e32 v159, v125, v163
	v_fmac_f32_e32 v149, v126, v155
	v_fmac_f32_e32 v170, v128, v171
	v_fmac_f32_e32 v172, v122, v173
	v_fmac_f32_e32 v174, v124, v175
	v_cvt_pk_bf16_f32 v122, v149, v156
	v_cvt_pk_bf16_f32 v123, v170, v157
	v_cvt_pk_bf16_f32 v124, v172, v158
	v_cvt_pk_bf16_f32 v125, v174, v159
	s_nop 1
	s_waitcnt vmcnt(15)
	v_mov_b32_e32 v126, v184
	v_mov_b32_e32 v127, v185
	v_mov_b32_e32 v128, v186
	v_mov_b32_e32 v129, v187
	s_nop 1
	v_lshl_add_u32 v240, s26, 8, v1
	v_lshl_or_b32 v242, s50, 8, v151
	v_ashrrev_i32_e32 v243, 31, v242
	v_lshlrev_b64 v[242:243], 1, v[242:243]
	v_add_u32_e32 v244, 0x80, v240
	v_ashrrev_i32_e32 v245, 31, v244
	v_lshlrev_b64 v[246:247], 13, v[244:245]
	v_lshl_add_u64 v[248:249], s[8:9], 0, v[246:247]
	v_lshl_add_u64 v[248:249], v[248:249], 0, v[242:243]
	global_load_dwordx4 v[184:187], v[248:249], off offset:256
	s_nop 1
	s_waitcnt vmcnt(15)
	v_mov_b32_e32 v156, v188
	v_mov_b32_e32 v157, v189
	v_mov_b32_e32 v158, v190
	v_mov_b32_e32 v159, v191
	s_nop 1
	v_lshl_add_u32 v240, s26, 8, v1
	v_lshl_or_b32 v242, s50, 8, v151
	v_ashrrev_i32_e32 v243, 31, v242
	v_lshlrev_b64 v[242:243], 1, v[242:243]
	v_add_u32_e32 v244, 0x80, v240
	v_ashrrev_i32_e32 v245, 31, v244
	v_lshlrev_b64 v[244:245], 14, v[244:245]
	v_lshl_add_u64 v[244:245], s[10:11], 0, v[244:245]
	v_lshl_add_u64 v[244:245], v[244:245], 0, v[242:243]
	v_lshl_add_u64 v[246:247], v[244:245], 0, s[16:17]
	global_load_dwordx4 v[188:191], v[246:247], off offset:256
	v_or_b32_e32 v160, 16, v148
	v_ashrrev_i32_e32 v161, 31, v160
	v_lshl_add_u64 v[162:163], s[6:7], 0, v[164:165]
	v_lshlrev_b64 v[164:165], 13, v[160:161]
	v_lshlrev_b64 v[160:161], 14, v[160:161]
	v_lshl_add_u64 v[162:163], v[162:163], 0, v[146:147]
	v_lshl_add_u64 v[160:161], s[10:11], 0, v[160:161]
	v_lshl_add_u64 v[166:167], s[8:9], 0, v[164:165]
	v_lshl_add_u64 v[160:161], v[160:161], 0, v[146:147]
	global_store_dwordx4 v[162:163], v[122:125], off
	v_lshl_add_u64 v[166:167], v[166:167], 0, v[146:147]
	v_add_co_u32_e32 v168, vcc, s43, v160
	s_nop 0
	v_lshlrev_b32_e32 v122, 16, v126
	s_nop 0
	v_lshlrev_b32_e32 v123, 16, v156
	v_and_b32_e32 v124, 0xffff0000, v126
	v_and_b32_e32 v125, 0xffff0000, v156
	v_lshlrev_b32_e32 v126, 16, v127
	v_lshlrev_b32_e32 v149, 16, v157
	v_and_b32_e32 v127, 0xffff0000, v127
	v_and_b32_e32 v155, 0xffff0000, v157
	v_lshlrev_b32_e32 v156, 16, v128
	v_lshlrev_b32_e32 v157, 16, v158
	v_and_b32_e32 v128, 0xffff0000, v128
	v_and_b32_e32 v158, 0xffff0000, v158
	v_lshlrev_b32_e32 v170, 16, v129
	v_lshlrev_b32_e32 v171, 16, v159
	v_and_b32_e32 v129, 0xffff0000, v129
	v_and_b32_e32 v159, 0xffff0000, v159
	v_fmac_f32_e32 v122, v118, v123
	v_fmac_f32_e32 v124, v119, v125
	v_addc_co_u32_e32 v169, vcc, 0, v161, vcc
	v_fmac_f32_e32 v126, v120, v149
	v_fmac_f32_e32 v127, v121, v155
	v_fmac_f32_e32 v156, v114, v157
	v_fmac_f32_e32 v128, v115, v158
	v_fmac_f32_e32 v170, v116, v171
	v_fmac_f32_e32 v129, v117, v159
	v_cvt_pk_bf16_f32 v114, v122, v124
	v_cvt_pk_bf16_f32 v115, v126, v127
	v_cvt_pk_bf16_f32 v116, v156, v128
	v_cvt_pk_bf16_f32 v117, v170, v129
	s_nop 1
	s_waitcnt vmcnt(16)
	v_mov_b32_e32 v118, v192
	v_mov_b32_e32 v119, v193
	v_mov_b32_e32 v120, v194
	v_mov_b32_e32 v121, v195
	s_nop 1
	v_lshl_add_u32 v240, s26, 8, v1
	v_lshl_or_b32 v242, s50, 8, v151
	v_ashrrev_i32_e32 v243, 31, v242
	v_lshlrev_b64 v[242:243], 1, v[242:243]
	v_add_u32_e32 v244, 0x90, v240
	v_ashrrev_i32_e32 v245, 31, v244
	v_lshlrev_b64 v[246:247], 13, v[244:245]
	v_lshl_add_u64 v[248:249], s[8:9], 0, v[246:247]
	v_lshl_add_u64 v[248:249], v[248:249], 0, v[242:243]
	global_load_dwordx4 v[192:195], v[248:249], off
	s_nop 1
	s_waitcnt vmcnt(16)
	v_mov_b32_e32 v122, v196
	v_mov_b32_e32 v123, v197
	v_mov_b32_e32 v124, v198
	v_mov_b32_e32 v125, v199
	s_nop 1
	v_lshl_add_u32 v240, s26, 8, v1
	v_lshl_or_b32 v242, s50, 8, v151
	v_ashrrev_i32_e32 v243, 31, v242
	v_lshlrev_b64 v[242:243], 1, v[242:243]
	v_add_u32_e32 v244, 0x90, v240
	v_ashrrev_i32_e32 v245, 31, v244
	v_lshlrev_b64 v[244:245], 14, v[244:245]
	v_lshl_add_u64 v[244:245], s[10:11], 0, v[244:245]
	v_lshl_add_u64 v[244:245], v[244:245], 0, v[242:243]
	v_add_co_u32_e32 v246, vcc, s43, v244
	s_nop 1
	v_addc_co_u32_e32 v247, vcc, 0, v245, vcc
	global_load_dwordx4 v[196:199], v[246:247], off
	v_lshl_add_u64 v[126:127], v[160:161], 0, s[16:17]
	global_store_dwordx4 v[162:163], v[114:117], off offset:256
	s_nop 0
	v_lshlrev_b32_e32 v128, 16, v120
	v_lshlrev_b32_e32 v114, 16, v118
	s_nop 0
	v_lshlrev_b32_e32 v115, 16, v122
	v_and_b32_e32 v116, 0xffff0000, v118
	v_and_b32_e32 v117, 0xffff0000, v122
	v_lshlrev_b32_e32 v118, 16, v119
	v_lshlrev_b32_e32 v122, 16, v123
	v_and_b32_e32 v119, 0xffff0000, v119
	v_and_b32_e32 v123, 0xffff0000, v123
	v_lshlrev_b32_e32 v129, 16, v124
	v_and_b32_e32 v120, 0xffff0000, v120
	v_and_b32_e32 v124, 0xffff0000, v124
	v_lshlrev_b32_e32 v149, 16, v121
	v_lshlrev_b32_e32 v155, 16, v125
	v_and_b32_e32 v121, 0xffff0000, v121
	v_and_b32_e32 v125, 0xffff0000, v125
	v_fmac_f32_e32 v114, v110, v115
	v_fmac_f32_e32 v116, v111, v117
	v_fmac_f32_e32 v118, v112, v122
	v_fmac_f32_e32 v119, v113, v123
	v_fmac_f32_e32 v128, v106, v129
	v_fmac_f32_e32 v120, v107, v124
	v_fmac_f32_e32 v149, v108, v155
	v_fmac_f32_e32 v121, v109, v125
	v_cvt_pk_bf16_f32 v106, v114, v116
	v_cvt_pk_bf16_f32 v107, v118, v119
	v_cvt_pk_bf16_f32 v108, v128, v120
	v_cvt_pk_bf16_f32 v109, v149, v121
	s_nop 1
	s_waitcnt vmcnt(17)
	v_mov_b32_e32 v110, v200
	v_mov_b32_e32 v111, v201
	v_mov_b32_e32 v112, v202
	v_mov_b32_e32 v113, v203
	s_nop 1
	v_lshl_add_u32 v240, s26, 8, v1
	v_lshl_or_b32 v242, s50, 8, v151
	v_ashrrev_i32_e32 v243, 31, v242
	v_lshlrev_b64 v[242:243], 1, v[242:243]
	v_add_u32_e32 v244, 0x90, v240
	v_ashrrev_i32_e32 v245, 31, v244
	v_lshlrev_b64 v[246:247], 13, v[244:245]
	v_lshl_add_u64 v[248:249], s[8:9], 0, v[246:247]
	v_lshl_add_u64 v[248:249], v[248:249], 0, v[242:243]
	global_load_dwordx4 v[200:203], v[248:249], off offset:256
	s_nop 1
	s_waitcnt vmcnt(17)
	v_mov_b32_e32 v114, v204
	v_mov_b32_e32 v115, v205
	v_mov_b32_e32 v116, v206
	v_mov_b32_e32 v117, v207
	s_nop 1
	v_lshl_add_u32 v240, s26, 8, v1
	v_lshl_or_b32 v242, s50, 8, v151
	v_ashrrev_i32_e32 v243, 31, v242
	v_lshlrev_b64 v[242:243], 1, v[242:243]
	v_add_u32_e32 v244, 0x90, v240
	v_ashrrev_i32_e32 v245, 31, v244
	v_lshlrev_b64 v[244:245], 14, v[244:245]
	v_lshl_add_u64 v[244:245], s[10:11], 0, v[244:245]
	v_lshl_add_u64 v[244:245], v[244:245], 0, v[242:243]
	v_lshl_add_u64 v[246:247], v[244:245], 0, s[16:17]
	global_load_dwordx4 v[204:207], v[246:247], off offset:256
	v_or_b32_e32 v118, 32, v148
	v_ashrrev_i32_e32 v119, 31, v118
	v_lshlrev_b64 v[120:121], 13, v[118:119]
	v_lshlrev_b64 v[118:119], 14, v[118:119]
	v_lshl_add_u64 v[122:123], s[6:7], 0, v[164:165]
	v_lshl_add_u64 v[118:119], s[10:11], 0, v[118:119]
	v_lshl_add_u64 v[122:123], v[122:123], 0, v[146:147]
	v_lshl_add_u64 v[124:125], s[8:9], 0, v[120:121]
	v_lshl_add_u64 v[118:119], v[118:119], 0, v[146:147]
	global_store_dwordx4 v[122:123], v[106:109], off
	v_lshl_add_u64 v[124:125], v[124:125], 0, v[146:147]
	v_add_co_u32_e32 v126, vcc, s43, v118
	s_nop 0
	v_lshlrev_b32_e32 v106, 16, v110
	s_nop 0
	v_lshlrev_b32_e32 v107, 16, v114
	v_and_b32_e32 v108, 0xffff0000, v110
	v_and_b32_e32 v109, 0xffff0000, v114
	v_lshlrev_b32_e32 v110, 16, v111
	v_lshlrev_b32_e32 v114, 16, v115
	v_and_b32_e32 v111, 0xffff0000, v111
	v_and_b32_e32 v115, 0xffff0000, v115
	v_lshlrev_b32_e32 v128, 16, v112
	v_lshlrev_b32_e32 v129, 16, v116
	v_and_b32_e32 v112, 0xffff0000, v112
	v_and_b32_e32 v116, 0xffff0000, v116
	v_lshlrev_b32_e32 v149, 16, v113
	v_lshlrev_b32_e32 v155, 16, v117
	v_and_b32_e32 v113, 0xffff0000, v113
	v_and_b32_e32 v117, 0xffff0000, v117
	v_fmac_f32_e32 v106, v102, v107
	v_fmac_f32_e32 v108, v103, v109
	v_addc_co_u32_e32 v127, vcc, 0, v119, vcc
	v_fmac_f32_e32 v110, v104, v114
	v_fmac_f32_e32 v111, v105, v115
	v_fmac_f32_e32 v128, v98, v129
	v_fmac_f32_e32 v112, v99, v116
	v_fmac_f32_e32 v149, v100, v155
	v_fmac_f32_e32 v113, v101, v117
	v_cvt_pk_bf16_f32 v98, v106, v108
	v_cvt_pk_bf16_f32 v99, v110, v111
	v_cvt_pk_bf16_f32 v100, v128, v112
	v_cvt_pk_bf16_f32 v101, v149, v113
	s_nop 1
	s_waitcnt vmcnt(18)
	v_mov_b32_e32 v102, v208
	v_mov_b32_e32 v103, v209
	v_mov_b32_e32 v104, v210
	v_mov_b32_e32 v105, v211
	s_nop 1
	v_lshl_add_u32 v240, s26, 8, v1
	v_lshl_or_b32 v242, s50, 8, v151
	v_ashrrev_i32_e32 v243, 31, v242
	v_lshlrev_b64 v[242:243], 1, v[242:243]
	v_add_u32_e32 v244, 0xa0, v240
	v_ashrrev_i32_e32 v245, 31, v244
	v_lshlrev_b64 v[246:247], 13, v[244:245]
	v_lshl_add_u64 v[248:249], s[8:9], 0, v[246:247]
	v_lshl_add_u64 v[248:249], v[248:249], 0, v[242:243]
	global_load_dwordx4 v[208:211], v[248:249], off
	s_nop 1
	s_waitcnt vmcnt(18)
	v_mov_b32_e32 v106, v212
	v_mov_b32_e32 v107, v213
	v_mov_b32_e32 v108, v214
	v_mov_b32_e32 v109, v215
	s_nop 1
	v_lshl_add_u32 v240, s26, 8, v1
	v_lshl_or_b32 v242, s50, 8, v151
	v_ashrrev_i32_e32 v243, 31, v242
	v_lshlrev_b64 v[242:243], 1, v[242:243]
	v_add_u32_e32 v244, 0xa0, v240
	v_ashrrev_i32_e32 v245, 31, v244
	v_lshlrev_b64 v[244:245], 14, v[244:245]
	v_lshl_add_u64 v[244:245], s[10:11], 0, v[244:245]
	v_lshl_add_u64 v[244:245], v[244:245], 0, v[242:243]
	v_add_co_u32_e32 v246, vcc, s43, v244
	s_nop 1
	v_addc_co_u32_e32 v247, vcc, 0, v245, vcc
	global_load_dwordx4 v[212:215], v[246:247], off
	v_lshl_add_u64 v[110:111], v[118:119], 0, s[16:17]
	global_store_dwordx4 v[122:123], v[98:101], off offset:256
	s_nop 0
	v_lshlrev_b32_e32 v112, 16, v104
	v_lshlrev_b32_e32 v98, 16, v102
	s_nop 0
	v_lshlrev_b32_e32 v99, 16, v106
	v_and_b32_e32 v100, 0xffff0000, v102
	v_and_b32_e32 v101, 0xffff0000, v106
	v_lshlrev_b32_e32 v102, 16, v103
	v_lshlrev_b32_e32 v106, 16, v107
	v_and_b32_e32 v103, 0xffff0000, v103
	v_and_b32_e32 v107, 0xffff0000, v107
	v_lshlrev_b32_e32 v113, 16, v108
	v_and_b32_e32 v104, 0xffff0000, v104
	v_and_b32_e32 v108, 0xffff0000, v108
	v_lshlrev_b32_e32 v114, 16, v105
	v_lshlrev_b32_e32 v115, 16, v109
	v_and_b32_e32 v105, 0xffff0000, v105
	v_and_b32_e32 v109, 0xffff0000, v109
	v_fmac_f32_e32 v98, v94, v99
	v_fmac_f32_e32 v100, v95, v101
	v_fmac_f32_e32 v102, v96, v106
	v_fmac_f32_e32 v103, v97, v107
	v_fmac_f32_e32 v112, v90, v113
	v_fmac_f32_e32 v104, v91, v108
	v_fmac_f32_e32 v114, v92, v115
	v_fmac_f32_e32 v105, v93, v109
	v_cvt_pk_bf16_f32 v90, v98, v100
	v_cvt_pk_bf16_f32 v91, v102, v103
	v_cvt_pk_bf16_f32 v92, v112, v104
	v_cvt_pk_bf16_f32 v93, v114, v105
	s_nop 1
	s_waitcnt vmcnt(19)
	v_mov_b32_e32 v94, v216
	v_mov_b32_e32 v95, v217
	v_mov_b32_e32 v96, v218
	v_mov_b32_e32 v97, v219
	s_nop 1
	v_lshl_add_u32 v240, s26, 8, v1
	v_lshl_or_b32 v242, s50, 8, v151
	v_ashrrev_i32_e32 v243, 31, v242
	v_lshlrev_b64 v[242:243], 1, v[242:243]
	v_add_u32_e32 v244, 0xa0, v240
	v_ashrrev_i32_e32 v245, 31, v244
	v_lshlrev_b64 v[246:247], 13, v[244:245]
	v_lshl_add_u64 v[248:249], s[8:9], 0, v[246:247]
	v_lshl_add_u64 v[248:249], v[248:249], 0, v[242:243]
	global_load_dwordx4 v[216:219], v[248:249], off offset:256
	s_nop 1
	s_waitcnt vmcnt(19)
	v_mov_b32_e32 v98, v220
	v_mov_b32_e32 v99, v221
	v_mov_b32_e32 v100, v222
	v_mov_b32_e32 v101, v223
	s_nop 1
	v_lshl_add_u32 v240, s26, 8, v1
	v_lshl_or_b32 v242, s50, 8, v151
	v_ashrrev_i32_e32 v243, 31, v242
	v_lshlrev_b64 v[242:243], 1, v[242:243]
	v_add_u32_e32 v244, 0xa0, v240
	v_ashrrev_i32_e32 v245, 31, v244
	v_lshlrev_b64 v[244:245], 14, v[244:245]
	v_lshl_add_u64 v[244:245], s[10:11], 0, v[244:245]
	v_lshl_add_u64 v[244:245], v[244:245], 0, v[242:243]
	v_lshl_add_u64 v[246:247], v[244:245], 0, s[16:17]
	global_load_dwordx4 v[220:223], v[246:247], off offset:256
	v_or_b32_e32 v102, 48, v148
	v_ashrrev_i32_e32 v103, 31, v102
	v_lshlrev_b64 v[104:105], 13, v[102:103]
	v_lshlrev_b64 v[102:103], 14, v[102:103]
	v_lshl_add_u64 v[106:107], s[6:7], 0, v[120:121]
	v_lshl_add_u64 v[102:103], s[10:11], 0, v[102:103]
	v_lshl_add_u64 v[106:107], v[106:107], 0, v[146:147]
	v_lshl_add_u64 v[108:109], s[8:9], 0, v[104:105]
	v_lshl_add_u64 v[102:103], v[102:103], 0, v[146:147]
	global_store_dwordx4 v[106:107], v[90:93], off
	v_lshl_add_u64 v[108:109], v[108:109], 0, v[146:147]
	v_add_co_u32_e32 v110, vcc, s43, v102
	s_nop 0
	v_lshlrev_b32_e32 v90, 16, v94
	s_nop 0
	v_lshlrev_b32_e32 v91, 16, v98
	v_and_b32_e32 v92, 0xffff0000, v94
	v_and_b32_e32 v93, 0xffff0000, v98
	v_lshlrev_b32_e32 v94, 16, v95
	v_lshlrev_b32_e32 v98, 16, v99
	v_and_b32_e32 v95, 0xffff0000, v95
	v_and_b32_e32 v99, 0xffff0000, v99
	v_lshlrev_b32_e32 v112, 16, v96
	v_lshlrev_b32_e32 v113, 16, v100
	v_and_b32_e32 v96, 0xffff0000, v96
	v_and_b32_e32 v100, 0xffff0000, v100
	v_lshlrev_b32_e32 v114, 16, v97
	v_lshlrev_b32_e32 v115, 16, v101
	v_and_b32_e32 v97, 0xffff0000, v97
	v_and_b32_e32 v101, 0xffff0000, v101
	v_fmac_f32_e32 v90, v86, v91
	v_fmac_f32_e32 v92, v87, v93
	v_addc_co_u32_e32 v111, vcc, 0, v103, vcc
	v_fmac_f32_e32 v94, v88, v98
	v_fmac_f32_e32 v95, v89, v99
	v_fmac_f32_e32 v112, v82, v113
	v_fmac_f32_e32 v96, v83, v100
	v_fmac_f32_e32 v114, v84, v115
	v_fmac_f32_e32 v97, v85, v101
	v_cvt_pk_bf16_f32 v82, v90, v92
	v_cvt_pk_bf16_f32 v83, v94, v95
	v_cvt_pk_bf16_f32 v84, v112, v96
	v_cvt_pk_bf16_f32 v85, v114, v97
	s_nop 1
	s_waitcnt vmcnt(20)
	v_mov_b32_e32 v86, v224
	v_mov_b32_e32 v87, v225
	v_mov_b32_e32 v88, v226
	v_mov_b32_e32 v89, v227
	s_nop 1
	v_lshl_add_u32 v240, s26, 8, v1
	v_lshl_or_b32 v242, s50, 8, v151
	v_ashrrev_i32_e32 v243, 31, v242
	v_lshlrev_b64 v[242:243], 1, v[242:243]
	v_add_u32_e32 v244, 0xb0, v240
	v_ashrrev_i32_e32 v245, 31, v244
	v_lshlrev_b64 v[246:247], 13, v[244:245]
	v_lshl_add_u64 v[248:249], s[8:9], 0, v[246:247]
	v_lshl_add_u64 v[248:249], v[248:249], 0, v[242:243]
	global_load_dwordx4 v[224:227], v[248:249], off
	s_nop 1
	s_waitcnt vmcnt(20)
	v_mov_b32_e32 v90, v228
	v_mov_b32_e32 v91, v229
	v_mov_b32_e32 v92, v230
	v_mov_b32_e32 v93, v231
	s_nop 1
	v_lshl_add_u32 v240, s26, 8, v1
	v_lshl_or_b32 v242, s50, 8, v151
	v_ashrrev_i32_e32 v243, 31, v242
	v_lshlrev_b64 v[242:243], 1, v[242:243]
	v_add_u32_e32 v244, 0xb0, v240
	v_ashrrev_i32_e32 v245, 31, v244
	v_lshlrev_b64 v[244:245], 14, v[244:245]
	v_lshl_add_u64 v[244:245], s[10:11], 0, v[244:245]
	v_lshl_add_u64 v[244:245], v[244:245], 0, v[242:243]
	v_add_co_u32_e32 v246, vcc, s43, v244
	s_nop 1
	v_addc_co_u32_e32 v247, vcc, 0, v245, vcc
	global_load_dwordx4 v[228:231], v[246:247], off
	v_lshl_add_u64 v[94:95], v[102:103], 0, s[16:17]
	global_store_dwordx4 v[106:107], v[82:85], off offset:256
	s_nop 0
	v_lshlrev_b32_e32 v96, 16, v88
	v_lshlrev_b32_e32 v82, 16, v86
	s_nop 0
	v_lshlrev_b32_e32 v83, 16, v90
	v_and_b32_e32 v84, 0xffff0000, v86
	v_and_b32_e32 v85, 0xffff0000, v90
	v_lshlrev_b32_e32 v86, 16, v87
	v_lshlrev_b32_e32 v90, 16, v91
	v_and_b32_e32 v87, 0xffff0000, v87
	v_and_b32_e32 v91, 0xffff0000, v91
	v_lshlrev_b32_e32 v97, 16, v92
	v_and_b32_e32 v88, 0xffff0000, v88
	v_and_b32_e32 v92, 0xffff0000, v92
	v_lshlrev_b32_e32 v98, 16, v89
	v_lshlrev_b32_e32 v99, 16, v93
	v_and_b32_e32 v89, 0xffff0000, v89
	v_and_b32_e32 v93, 0xffff0000, v93
	v_fmac_f32_e32 v82, v78, v83
	v_fmac_f32_e32 v84, v79, v85
	v_fmac_f32_e32 v86, v80, v90
	v_fmac_f32_e32 v87, v81, v91
	v_fmac_f32_e32 v96, v74, v97
	v_fmac_f32_e32 v88, v75, v92
	v_fmac_f32_e32 v98, v76, v99
	v_fmac_f32_e32 v89, v77, v93
	v_cvt_pk_bf16_f32 v74, v82, v84
	v_cvt_pk_bf16_f32 v75, v86, v87
	v_cvt_pk_bf16_f32 v76, v96, v88
	v_cvt_pk_bf16_f32 v77, v98, v89
	s_nop 1
	s_waitcnt vmcnt(21)
	v_mov_b32_e32 v78, v232
	v_mov_b32_e32 v79, v233
	v_mov_b32_e32 v80, v234
	v_mov_b32_e32 v81, v235
	s_nop 1
	v_lshl_add_u32 v240, s26, 8, v1
	v_lshl_or_b32 v242, s50, 8, v151
	v_ashrrev_i32_e32 v243, 31, v242
	v_lshlrev_b64 v[242:243], 1, v[242:243]
	v_add_u32_e32 v244, 0xb0, v240
	v_ashrrev_i32_e32 v245, 31, v244
	v_lshlrev_b64 v[246:247], 13, v[244:245]
	v_lshl_add_u64 v[248:249], s[8:9], 0, v[246:247]
	v_lshl_add_u64 v[248:249], v[248:249], 0, v[242:243]
	global_load_dwordx4 v[232:235], v[248:249], off offset:256
	s_nop 1
	s_waitcnt vmcnt(21)
	v_mov_b32_e32 v82, v236
	v_mov_b32_e32 v83, v237
	v_mov_b32_e32 v84, v238
	v_mov_b32_e32 v85, v239
	s_nop 1
	v_lshl_add_u32 v240, s26, 8, v1
	v_lshl_or_b32 v242, s50, 8, v151
	v_ashrrev_i32_e32 v243, 31, v242
	v_lshlrev_b64 v[242:243], 1, v[242:243]
	v_add_u32_e32 v244, 0xb0, v240
	v_ashrrev_i32_e32 v245, 31, v244
	v_lshlrev_b64 v[244:245], 14, v[244:245]
	v_lshl_add_u64 v[244:245], s[10:11], 0, v[244:245]
	v_lshl_add_u64 v[244:245], v[244:245], 0, v[242:243]
	v_lshl_add_u64 v[246:247], v[244:245], 0, s[16:17]
	global_load_dwordx4 v[236:239], v[246:247], off offset:256
	v_add_u32_e32 v86, 0x80, v148
	v_ashrrev_i32_e32 v87, 31, v86
	v_lshlrev_b64 v[88:89], 13, v[86:87]
	v_lshlrev_b64 v[86:87], 14, v[86:87]
	v_lshl_add_u64 v[90:91], s[6:7], 0, v[104:105]
	v_lshl_add_u64 v[86:87], s[10:11], 0, v[86:87]
	v_lshl_add_u64 v[90:91], v[90:91], 0, v[146:147]
	v_lshl_add_u64 v[92:93], s[8:9], 0, v[88:89]
	v_lshl_add_u64 v[86:87], v[86:87], 0, v[146:147]
	global_store_dwordx4 v[90:91], v[74:77], off
	v_lshl_add_u64 v[92:93], v[92:93], 0, v[146:147]
	v_add_co_u32_e32 v94, vcc, s43, v86
	s_nop 0
	v_lshlrev_b32_e32 v74, 16, v78
	s_nop 0
	v_lshlrev_b32_e32 v75, 16, v82
	v_and_b32_e32 v76, 0xffff0000, v78
	v_and_b32_e32 v77, 0xffff0000, v82
	v_lshlrev_b32_e32 v78, 16, v79
	v_lshlrev_b32_e32 v82, 16, v83
	v_and_b32_e32 v79, 0xffff0000, v79
	v_and_b32_e32 v83, 0xffff0000, v83
	v_lshlrev_b32_e32 v96, 16, v80
	v_lshlrev_b32_e32 v97, 16, v84
	v_and_b32_e32 v80, 0xffff0000, v80
	v_and_b32_e32 v84, 0xffff0000, v84
	v_lshlrev_b32_e32 v98, 16, v81
	v_lshlrev_b32_e32 v99, 16, v85
	v_and_b32_e32 v81, 0xffff0000, v81
	v_and_b32_e32 v85, 0xffff0000, v85
	v_fmac_f32_e32 v74, v70, v75
	v_fmac_f32_e32 v76, v71, v77
	v_addc_co_u32_e32 v95, vcc, 0, v87, vcc
	v_fmac_f32_e32 v78, v72, v82
	v_fmac_f32_e32 v79, v73, v83
	v_fmac_f32_e32 v96, v66, v97
	v_fmac_f32_e32 v80, v67, v84
	v_fmac_f32_e32 v98, v68, v99
	v_fmac_f32_e32 v81, v69, v85
	v_cvt_pk_bf16_f32 v66, v74, v76
	v_cvt_pk_bf16_f32 v67, v78, v79
	v_cvt_pk_bf16_f32 v68, v96, v80
	v_cvt_pk_bf16_f32 v69, v98, v81
	s_nop 1
	s_waitcnt vmcnt(22)
	v_mov_b32_e32 v70, v176
	v_mov_b32_e32 v71, v177
	v_mov_b32_e32 v72, v178
	v_mov_b32_e32 v73, v179
	s_nop 1
	s_waitcnt vmcnt(21)
	v_mov_b32_e32 v74, v180
	v_mov_b32_e32 v75, v181
	v_mov_b32_e32 v76, v182
	v_mov_b32_e32 v77, v183
	v_lshl_add_u64 v[78:79], v[86:87], 0, s[16:17]
	global_store_dwordx4 v[90:91], v[66:69], off offset:256
	s_nop 0
	v_lshlrev_b32_e32 v80, 16, v72
	v_lshlrev_b32_e32 v66, 16, v70
	s_nop 0
	v_lshlrev_b32_e32 v67, 16, v74
	v_and_b32_e32 v68, 0xffff0000, v70
	v_and_b32_e32 v69, 0xffff0000, v74
	v_lshlrev_b32_e32 v70, 16, v71
	v_lshlrev_b32_e32 v74, 16, v75
	v_and_b32_e32 v71, 0xffff0000, v71
	v_and_b32_e32 v75, 0xffff0000, v75
	v_lshlrev_b32_e32 v81, 16, v76
	v_and_b32_e32 v72, 0xffff0000, v72
	v_and_b32_e32 v76, 0xffff0000, v76
	v_lshlrev_b32_e32 v82, 16, v73
	v_lshlrev_b32_e32 v83, 16, v77
	v_and_b32_e32 v73, 0xffff0000, v73
	v_and_b32_e32 v77, 0xffff0000, v77
	v_fmac_f32_e32 v66, v62, v67
	v_fmac_f32_e32 v68, v63, v69
	v_fmac_f32_e32 v70, v64, v74
	v_fmac_f32_e32 v71, v65, v75
	v_fmac_f32_e32 v80, v58, v81
	v_fmac_f32_e32 v72, v59, v76
	v_fmac_f32_e32 v82, v60, v83
	v_fmac_f32_e32 v73, v61, v77
	v_cvt_pk_bf16_f32 v58, v66, v68
	v_cvt_pk_bf16_f32 v59, v70, v71
	v_cvt_pk_bf16_f32 v60, v80, v72
	v_cvt_pk_bf16_f32 v61, v82, v73
	s_nop 1
	s_waitcnt vmcnt(21)
	v_mov_b32_e32 v62, v184
	v_mov_b32_e32 v63, v185
	v_mov_b32_e32 v64, v186
	v_mov_b32_e32 v65, v187
	s_nop 1
	s_waitcnt vmcnt(20)
	v_mov_b32_e32 v66, v188
	v_mov_b32_e32 v67, v189
	v_mov_b32_e32 v68, v190
	v_mov_b32_e32 v69, v191
	v_add_u32_e32 v70, 0x90, v148
	v_ashrrev_i32_e32 v71, 31, v70
	v_lshlrev_b64 v[72:73], 13, v[70:71]
	v_lshlrev_b64 v[70:71], 14, v[70:71]
	v_lshl_add_u64 v[74:75], s[6:7], 0, v[88:89]
	v_lshl_add_u64 v[70:71], s[10:11], 0, v[70:71]
	v_lshl_add_u64 v[74:75], v[74:75], 0, v[146:147]
	v_lshl_add_u64 v[76:77], s[8:9], 0, v[72:73]
	v_lshl_add_u64 v[70:71], v[70:71], 0, v[146:147]
	global_store_dwordx4 v[74:75], v[58:61], off
	v_lshl_add_u64 v[76:77], v[76:77], 0, v[146:147]
	v_add_co_u32_e32 v78, vcc, s43, v70
	s_nop 0
	v_lshlrev_b32_e32 v58, 16, v62
	s_nop 0
	v_lshlrev_b32_e32 v59, 16, v66
	v_and_b32_e32 v60, 0xffff0000, v62
	v_and_b32_e32 v61, 0xffff0000, v66
	v_lshlrev_b32_e32 v62, 16, v63
	v_lshlrev_b32_e32 v66, 16, v67
	v_and_b32_e32 v63, 0xffff0000, v63
	v_and_b32_e32 v67, 0xffff0000, v67
	v_lshlrev_b32_e32 v80, 16, v64
	v_lshlrev_b32_e32 v81, 16, v68
	v_and_b32_e32 v64, 0xffff0000, v64
	v_and_b32_e32 v68, 0xffff0000, v68
	v_lshlrev_b32_e32 v82, 16, v65
	v_lshlrev_b32_e32 v83, 16, v69
	v_and_b32_e32 v65, 0xffff0000, v65
	v_and_b32_e32 v69, 0xffff0000, v69
	v_fmac_f32_e32 v58, v54, v59
	v_fmac_f32_e32 v60, v55, v61
	v_addc_co_u32_e32 v79, vcc, 0, v71, vcc
	v_fmac_f32_e32 v62, v56, v66
	v_fmac_f32_e32 v63, v57, v67
	v_fmac_f32_e32 v80, v50, v81
	v_fmac_f32_e32 v64, v51, v68
	v_fmac_f32_e32 v82, v52, v83
	v_fmac_f32_e32 v65, v53, v69
	v_cvt_pk_bf16_f32 v50, v58, v60
	v_cvt_pk_bf16_f32 v51, v62, v63
	v_cvt_pk_bf16_f32 v52, v80, v64
	v_cvt_pk_bf16_f32 v53, v82, v65
	s_nop 1
	s_waitcnt vmcnt(19)
	v_mov_b32_e32 v54, v192
	v_mov_b32_e32 v55, v193
	v_mov_b32_e32 v56, v194
	v_mov_b32_e32 v57, v195
	s_nop 1
	s_waitcnt vmcnt(18)
	v_mov_b32_e32 v58, v196
	v_mov_b32_e32 v59, v197
	v_mov_b32_e32 v60, v198
	v_mov_b32_e32 v61, v199
	v_lshl_add_u64 v[62:63], v[70:71], 0, s[16:17]
	global_store_dwordx4 v[74:75], v[50:53], off offset:256
	s_nop 0
	v_lshlrev_b32_e32 v64, 16, v56
	v_lshlrev_b32_e32 v50, 16, v54
	s_nop 0
	v_lshlrev_b32_e32 v51, 16, v58
	v_and_b32_e32 v52, 0xffff0000, v54
	v_and_b32_e32 v53, 0xffff0000, v58
	v_lshlrev_b32_e32 v54, 16, v55
	v_lshlrev_b32_e32 v58, 16, v59
	v_and_b32_e32 v55, 0xffff0000, v55
	v_and_b32_e32 v59, 0xffff0000, v59
	v_lshlrev_b32_e32 v65, 16, v60
	v_and_b32_e32 v56, 0xffff0000, v56
	v_and_b32_e32 v60, 0xffff0000, v60
	v_lshlrev_b32_e32 v66, 16, v57
	v_lshlrev_b32_e32 v67, 16, v61
	v_and_b32_e32 v57, 0xffff0000, v57
	v_and_b32_e32 v61, 0xffff0000, v61
	v_fmac_f32_e32 v50, v46, v51
	v_fmac_f32_e32 v52, v47, v53
	v_fmac_f32_e32 v54, v48, v58
	v_fmac_f32_e32 v55, v49, v59
	v_fmac_f32_e32 v64, v42, v65
	v_fmac_f32_e32 v56, v43, v60
	v_fmac_f32_e32 v66, v44, v67
	v_fmac_f32_e32 v57, v45, v61
	v_cvt_pk_bf16_f32 v42, v50, v52
	v_cvt_pk_bf16_f32 v43, v54, v55
	v_cvt_pk_bf16_f32 v44, v64, v56
	v_cvt_pk_bf16_f32 v45, v66, v57
	s_nop 1
	s_waitcnt vmcnt(17)
	v_mov_b32_e32 v46, v200
	v_mov_b32_e32 v47, v201
	v_mov_b32_e32 v48, v202
	v_mov_b32_e32 v49, v203
	s_nop 1
	s_waitcnt vmcnt(16)
	v_mov_b32_e32 v50, v204
	v_mov_b32_e32 v51, v205
	v_mov_b32_e32 v52, v206
	v_mov_b32_e32 v53, v207
	v_add_u32_e32 v54, 0xa0, v148
	v_ashrrev_i32_e32 v55, 31, v54
	v_lshlrev_b64 v[56:57], 13, v[54:55]
	v_lshlrev_b64 v[54:55], 14, v[54:55]
	v_lshl_add_u64 v[58:59], s[6:7], 0, v[72:73]
	v_lshl_add_u64 v[54:55], s[10:11], 0, v[54:55]
	v_lshl_add_u64 v[58:59], v[58:59], 0, v[146:147]
	v_lshl_add_u64 v[60:61], s[8:9], 0, v[56:57]
	v_lshl_add_u64 v[54:55], v[54:55], 0, v[146:147]
	global_store_dwordx4 v[58:59], v[42:45], off
	v_lshl_add_u64 v[60:61], v[60:61], 0, v[146:147]
	v_add_co_u32_e32 v62, vcc, s43, v54
	s_nop 0
	v_lshlrev_b32_e32 v42, 16, v46
	s_nop 0
	v_lshlrev_b32_e32 v43, 16, v50
	v_and_b32_e32 v44, 0xffff0000, v46
	v_and_b32_e32 v45, 0xffff0000, v50
	v_lshlrev_b32_e32 v46, 16, v47
	v_lshlrev_b32_e32 v50, 16, v51
	v_and_b32_e32 v47, 0xffff0000, v47
	v_and_b32_e32 v51, 0xffff0000, v51
	v_lshlrev_b32_e32 v64, 16, v48
	v_lshlrev_b32_e32 v65, 16, v52
	v_and_b32_e32 v48, 0xffff0000, v48
	v_and_b32_e32 v52, 0xffff0000, v52
	v_lshlrev_b32_e32 v66, 16, v49
	v_lshlrev_b32_e32 v67, 16, v53
	v_and_b32_e32 v49, 0xffff0000, v49
	v_and_b32_e32 v53, 0xffff0000, v53
	v_fmac_f32_e32 v42, v38, v43
	v_fmac_f32_e32 v44, v39, v45
	v_addc_co_u32_e32 v63, vcc, 0, v55, vcc
	v_fmac_f32_e32 v46, v40, v50
	v_fmac_f32_e32 v47, v41, v51
	v_fmac_f32_e32 v64, v34, v65
	v_fmac_f32_e32 v48, v35, v52
	v_fmac_f32_e32 v66, v36, v67
	v_fmac_f32_e32 v49, v37, v53
	v_cvt_pk_bf16_f32 v34, v42, v44
	v_cvt_pk_bf16_f32 v35, v46, v47
	v_cvt_pk_bf16_f32 v36, v64, v48
	v_cvt_pk_bf16_f32 v37, v66, v49
	s_nop 1
	s_waitcnt vmcnt(15)
	v_mov_b32_e32 v38, v208
	v_mov_b32_e32 v39, v209
	v_mov_b32_e32 v40, v210
	v_mov_b32_e32 v41, v211
	s_nop 1
	s_waitcnt vmcnt(14)
	v_mov_b32_e32 v42, v212
	v_mov_b32_e32 v43, v213
	v_mov_b32_e32 v44, v214
	v_mov_b32_e32 v45, v215
	v_lshl_add_u64 v[46:47], v[54:55], 0, s[16:17]
	global_store_dwordx4 v[58:59], v[34:37], off offset:256
	s_nop 0
	v_lshlrev_b32_e32 v48, 16, v40
	v_lshlrev_b32_e32 v34, 16, v38
	s_nop 0
	v_lshlrev_b32_e32 v35, 16, v42
	v_and_b32_e32 v36, 0xffff0000, v38
	v_and_b32_e32 v37, 0xffff0000, v42
	v_lshlrev_b32_e32 v38, 16, v39
	v_lshlrev_b32_e32 v42, 16, v43
	v_and_b32_e32 v39, 0xffff0000, v39
	v_and_b32_e32 v43, 0xffff0000, v43
	v_lshlrev_b32_e32 v49, 16, v44
	v_and_b32_e32 v40, 0xffff0000, v40
	v_and_b32_e32 v44, 0xffff0000, v44
	v_lshlrev_b32_e32 v50, 16, v41
	v_lshlrev_b32_e32 v51, 16, v45
	v_and_b32_e32 v41, 0xffff0000, v41
	v_and_b32_e32 v45, 0xffff0000, v45
	v_fmac_f32_e32 v34, v30, v35
	v_fmac_f32_e32 v36, v31, v37
	v_fmac_f32_e32 v38, v32, v42
	v_fmac_f32_e32 v39, v33, v43
	v_fmac_f32_e32 v48, v26, v49
	v_fmac_f32_e32 v40, v27, v44
	v_fmac_f32_e32 v50, v28, v51
	v_fmac_f32_e32 v41, v29, v45
	v_cvt_pk_bf16_f32 v26, v34, v36
	v_cvt_pk_bf16_f32 v27, v38, v39
	v_cvt_pk_bf16_f32 v28, v48, v40
	v_cvt_pk_bf16_f32 v29, v50, v41
	s_nop 1
	s_waitcnt vmcnt(13)
	v_mov_b32_e32 v30, v216
	v_mov_b32_e32 v31, v217
	v_mov_b32_e32 v32, v218
	v_mov_b32_e32 v33, v219
	s_nop 1
	s_waitcnt vmcnt(12)
	v_mov_b32_e32 v34, v220
	v_mov_b32_e32 v35, v221
	v_mov_b32_e32 v36, v222
	v_mov_b32_e32 v37, v223
	v_add_u32_e32 v38, 0xb0, v148
	v_ashrrev_i32_e32 v39, 31, v38
	v_lshlrev_b64 v[40:41], 13, v[38:39]
	v_lshlrev_b64 v[38:39], 14, v[38:39]
	v_lshl_add_u64 v[42:43], s[6:7], 0, v[56:57]
	v_lshl_add_u64 v[38:39], s[10:11], 0, v[38:39]
	v_lshl_add_u64 v[42:43], v[42:43], 0, v[146:147]
	v_lshl_add_u64 v[44:45], s[8:9], 0, v[40:41]
	v_lshl_add_u64 v[38:39], v[38:39], 0, v[146:147]
	global_store_dwordx4 v[42:43], v[26:29], off
	v_lshl_add_u64 v[44:45], v[44:45], 0, v[146:147]
	v_add_co_u32_e32 v46, vcc, s43, v38
	s_nop 0
	v_lshlrev_b32_e32 v26, 16, v30
	s_nop 0
	v_lshlrev_b32_e32 v27, 16, v34
	v_and_b32_e32 v28, 0xffff0000, v30
	v_and_b32_e32 v29, 0xffff0000, v34
	v_lshlrev_b32_e32 v30, 16, v31
	v_lshlrev_b32_e32 v34, 16, v35
	v_and_b32_e32 v31, 0xffff0000, v31
	v_and_b32_e32 v35, 0xffff0000, v35
	v_lshlrev_b32_e32 v48, 16, v32
	v_lshlrev_b32_e32 v49, 16, v36
	v_and_b32_e32 v32, 0xffff0000, v32
	v_and_b32_e32 v36, 0xffff0000, v36
	v_lshlrev_b32_e32 v50, 16, v33
	v_lshlrev_b32_e32 v51, 16, v37
	v_and_b32_e32 v33, 0xffff0000, v33
	v_and_b32_e32 v37, 0xffff0000, v37
	v_fmac_f32_e32 v26, v22, v27
	v_fmac_f32_e32 v28, v23, v29
	v_addc_co_u32_e32 v47, vcc, 0, v39, vcc
	v_fmac_f32_e32 v30, v24, v34
	v_fmac_f32_e32 v31, v25, v35
	v_fmac_f32_e32 v48, v18, v49
	v_fmac_f32_e32 v32, v19, v36
	v_fmac_f32_e32 v50, v20, v51
	v_fmac_f32_e32 v33, v21, v37
	v_cvt_pk_bf16_f32 v18, v26, v28
	v_cvt_pk_bf16_f32 v19, v30, v31
	v_cvt_pk_bf16_f32 v20, v48, v32
	v_cvt_pk_bf16_f32 v21, v50, v33
	s_nop 1
	s_waitcnt vmcnt(11)
	v_mov_b32_e32 v22, v224
	v_mov_b32_e32 v23, v225
	v_mov_b32_e32 v24, v226
	v_mov_b32_e32 v25, v227
	s_nop 1
	s_waitcnt vmcnt(10)
	v_mov_b32_e32 v26, v228
	v_mov_b32_e32 v27, v229
	v_mov_b32_e32 v28, v230
	v_mov_b32_e32 v29, v231
	v_lshl_add_u64 v[30:31], v[38:39], 0, s[16:17]
	global_store_dwordx4 v[42:43], v[18:21], off offset:256
	s_andn2_b64 vcc, exec, s[4:5]
	s_mov_b64 s[4:5], -1
	s_nop 0
	v_lshlrev_b32_e32 v18, 16, v22
	s_nop 0
	v_lshlrev_b32_e32 v19, 16, v26
	v_and_b32_e32 v20, 0xffff0000, v22
	v_and_b32_e32 v21, 0xffff0000, v26
	v_lshlrev_b32_e32 v22, 16, v23
	v_lshlrev_b32_e32 v26, 16, v27
	v_and_b32_e32 v23, 0xffff0000, v23
	v_and_b32_e32 v27, 0xffff0000, v27
	v_lshlrev_b32_e32 v32, 16, v24
	v_lshlrev_b32_e32 v33, 16, v28
	v_and_b32_e32 v24, 0xffff0000, v24
	v_and_b32_e32 v28, 0xffff0000, v28
	v_lshlrev_b32_e32 v34, 16, v25
	v_lshlrev_b32_e32 v35, 16, v29
	v_and_b32_e32 v25, 0xffff0000, v25
	v_and_b32_e32 v29, 0xffff0000, v29
	v_fmac_f32_e32 v18, v14, v19
	v_fmac_f32_e32 v20, v15, v21
	v_fmac_f32_e32 v22, v16, v26
	v_fmac_f32_e32 v23, v17, v27
	v_fmac_f32_e32 v32, v10, v33
	v_fmac_f32_e32 v24, v11, v28
	v_fmac_f32_e32 v34, v12, v35
	v_fmac_f32_e32 v25, v13, v29
	v_cvt_pk_bf16_f32 v10, v18, v20
	v_cvt_pk_bf16_f32 v11, v22, v23
	v_cvt_pk_bf16_f32 v12, v32, v24
	v_cvt_pk_bf16_f32 v13, v34, v25
	s_nop 1
	s_waitcnt vmcnt(9)
	v_mov_b32_e32 v14, v232
	v_mov_b32_e32 v15, v233
	v_mov_b32_e32 v16, v234
	v_mov_b32_e32 v17, v235
	s_nop 1
	s_waitcnt vmcnt(8)
	v_mov_b32_e32 v18, v236
	v_mov_b32_e32 v19, v237
	v_mov_b32_e32 v20, v238
	v_mov_b32_e32 v21, v239
	v_lshl_add_u64 v[22:23], s[6:7], 0, v[40:41]
	v_lshl_add_u64 v[22:23], v[22:23], 0, v[146:147]
	global_store_dwordx4 v[22:23], v[10:13], off
	s_nop 0
	v_lshlrev_b32_e32 v24, 16, v16
	v_lshlrev_b32_e32 v10, 16, v14
	s_nop 0
	v_lshlrev_b32_e32 v11, 16, v18
	v_and_b32_e32 v12, 0xffff0000, v14
	v_and_b32_e32 v13, 0xffff0000, v18
	v_lshlrev_b32_e32 v14, 16, v15
	v_lshlrev_b32_e32 v18, 16, v19
	v_and_b32_e32 v15, 0xffff0000, v15
	v_and_b32_e32 v19, 0xffff0000, v19
	v_lshlrev_b32_e32 v25, 16, v20
	v_and_b32_e32 v16, 0xffff0000, v16
	v_and_b32_e32 v20, 0xffff0000, v20
	v_lshlrev_b32_e32 v26, 16, v17
	v_lshlrev_b32_e32 v27, 16, v21
	v_and_b32_e32 v17, 0xffff0000, v17
	v_and_b32_e32 v21, 0xffff0000, v21
	v_fmac_f32_e32 v10, v6, v11
	v_fmac_f32_e32 v12, v7, v13
	v_fmac_f32_e32 v14, v8, v18
	v_fmac_f32_e32 v15, v9, v19
	v_fmac_f32_e32 v24, v2, v25
	v_fmac_f32_e32 v16, v3, v20
	v_fmac_f32_e32 v26, v4, v27
	v_fmac_f32_e32 v17, v5, v21
	v_cvt_pk_bf16_f32 v2, v10, v12
	v_cvt_pk_bf16_f32 v3, v14, v15
	v_cvt_pk_bf16_f32 v4, v24, v16
	v_cvt_pk_bf16_f32 v5, v26, v17
	global_store_dwordx4 v[22:23], v[2:5], off offset:256
	s_cbranch_vccnz .LBB0_1634
	s_andn2_b64 vcc, exec, s[0:1]
	s_cbranch_vccnz .LBB0_1633
	s_barrier
	s_branch .LBB0_1633

.LBB0_1725:
	v_lshl_add_u32 v150, s28, 8, v1
	v_lshl_or_b32 v148, s51, 8, v153
	v_ashrrev_i32_e32 v151, 31, v150
	v_ashrrev_i32_e32 v149, 31, v148
	v_lshlrev_b64 v[146:147], 12, v[150:151]
	v_readlane_b32 s68, v254, 4
	v_lshl_add_u64 v[146:147], v[146:147], 0, v[148:149]
	v_readlane_b32 s69, v254, 5
	v_lshl_add_u64 v[168:169], v[146:147], 1, s[6:7]
	s_andn2_b64 vcc, exec, s[4:5]
	v_lshl_add_u64 v[166:167], v[146:147], 2, s[68:69]
	v_lshl_add_u32 v170, s28, 8, v1
	v_lshl_or_b32 v236, s51, 8, v153
	v_ashrrev_i32_e32 v171, 31, v170
	v_ashrrev_i32_e32 v237, 31, v236
	v_lshlrev_b64 v[238:239], 12, v[170:171]
	v_lshl_add_u64 v[238:239], v[238:239], 0, v[236:237]
	v_lshl_add_u64 v[240:241], v[238:239], 2, s[68:69]
	global_load_dwordx4 v[172:175], v[240:241], off
	v_lshl_add_u32 v170, s28, 8, v1
	v_lshl_or_b32 v236, s51, 8, v153
	v_ashrrev_i32_e32 v171, 31, v170
	v_ashrrev_i32_e32 v237, 31, v236
	v_lshlrev_b64 v[238:239], 12, v[170:171]
	v_lshl_add_u64 v[238:239], v[238:239], 0, v[236:237]
	v_lshl_add_u64 v[240:241], v[238:239], 2, s[68:69]
	global_load_dwordx4 v[176:179], v[240:241], off offset:16
	v_lshl_add_u32 v170, s28, 8, v1
	v_lshl_or_b32 v236, s51, 8, v153
	v_ashrrev_i32_e32 v171, 31, v170
	v_ashrrev_i32_e32 v237, 31, v236
	v_lshlrev_b64 v[238:239], 12, v[170:171]
	v_lshl_add_u64 v[238:239], v[238:239], 0, v[236:237]
	v_lshl_add_u64 v[240:241], v[238:239], 2, s[68:69]
	global_load_dwordx4 v[180:183], v[240:241], off offset:512
	v_lshl_add_u32 v170, s28, 8, v1
	v_lshl_or_b32 v236, s51, 8, v153
	v_ashrrev_i32_e32 v171, 31, v170
	v_ashrrev_i32_e32 v237, 31, v236
	v_lshlrev_b64 v[238:239], 12, v[170:171]
	v_lshl_add_u64 v[238:239], v[238:239], 0, v[236:237]
	v_lshl_add_u64 v[240:241], v[238:239], 2, s[68:69]
	global_load_dwordx4 v[184:187], v[240:241], off offset:528
	v_lshl_add_u32 v170, s28, 8, v1
	v_lshl_or_b32 v236, s51, 8, v153
	v_ashrrev_i32_e32 v237, 31, v236
	v_or_b32_e32 v238, 16, v170
	v_ashrrev_i32_e32 v239, 31, v238
	v_lshlrev_b64 v[238:239], 12, v[238:239]
	v_lshl_add_u64 v[238:239], v[238:239], 0, v[236:237]
	v_lshl_add_u64 v[240:241], v[238:239], 2, s[68:69]
	global_load_dwordx4 v[188:191], v[240:241], off
	v_lshl_add_u32 v170, s28, 8, v1
	v_lshl_or_b32 v236, s51, 8, v153
	v_ashrrev_i32_e32 v237, 31, v236
	v_or_b32_e32 v238, 16, v170
	v_ashrrev_i32_e32 v239, 31, v238
	v_lshlrev_b64 v[238:239], 12, v[238:239]
	v_lshl_add_u64 v[238:239], v[238:239], 0, v[236:237]
	v_lshl_add_u64 v[240:241], v[238:239], 2, s[68:69]
	global_load_dwordx4 v[192:195], v[240:241], off offset:16
	v_lshl_add_u32 v170, s28, 8, v1
	v_lshl_or_b32 v236, s51, 8, v153
	v_ashrrev_i32_e32 v237, 31, v236
	v_or_b32_e32 v238, 16, v170
	v_ashrrev_i32_e32 v239, 31, v238
	v_lshlrev_b64 v[238:239], 12, v[238:239]
	v_lshl_add_u64 v[238:239], v[238:239], 0, v[236:237]
	v_lshl_add_u64 v[240:241], v[238:239], 2, s[68:69]
	global_load_dwordx4 v[196:199], v[240:241], off offset:512
	v_lshl_add_u32 v170, s28, 8, v1
	v_lshl_or_b32 v236, s51, 8, v153
	v_ashrrev_i32_e32 v237, 31, v236
	v_or_b32_e32 v238, 16, v170
	v_ashrrev_i32_e32 v239, 31, v238
	v_lshlrev_b64 v[238:239], 12, v[238:239]
	v_lshl_add_u64 v[238:239], v[238:239], 0, v[236:237]
	v_lshl_add_u64 v[240:241], v[238:239], 2, s[68:69]
	global_load_dwordx4 v[200:203], v[240:241], off offset:528
	v_lshl_add_u32 v170, s28, 8, v1
	v_lshl_or_b32 v236, s51, 8, v153
	v_ashrrev_i32_e32 v237, 31, v236
	v_or_b32_e32 v238, 32, v170
	v_ashrrev_i32_e32 v239, 31, v238
	v_lshlrev_b64 v[238:239], 12, v[238:239]
	v_lshl_add_u64 v[238:239], v[238:239], 0, v[236:237]
	v_lshl_add_u64 v[240:241], v[238:239], 2, s[68:69]
	global_load_dwordx4 v[204:207], v[240:241], off
	v_lshl_add_u32 v170, s28, 8, v1
	v_lshl_or_b32 v236, s51, 8, v153
	v_ashrrev_i32_e32 v237, 31, v236
	v_or_b32_e32 v238, 32, v170
	v_ashrrev_i32_e32 v239, 31, v238
	v_lshlrev_b64 v[238:239], 12, v[238:239]
	v_lshl_add_u64 v[238:239], v[238:239], 0, v[236:237]
	v_lshl_add_u64 v[240:241], v[238:239], 2, s[68:69]
	global_load_dwordx4 v[208:211], v[240:241], off offset:16
	v_lshl_add_u32 v170, s28, 8, v1
	v_lshl_or_b32 v236, s51, 8, v153
	v_ashrrev_i32_e32 v237, 31, v236
	v_or_b32_e32 v238, 32, v170
	v_ashrrev_i32_e32 v239, 31, v238
	v_lshlrev_b64 v[238:239], 12, v[238:239]
	v_lshl_add_u64 v[238:239], v[238:239], 0, v[236:237]
	v_lshl_add_u64 v[240:241], v[238:239], 2, s[68:69]
	global_load_dwordx4 v[212:215], v[240:241], off offset:512
	v_lshl_add_u32 v170, s28, 8, v1
	v_lshl_or_b32 v236, s51, 8, v153
	v_ashrrev_i32_e32 v237, 31, v236
	v_or_b32_e32 v238, 32, v170
	v_ashrrev_i32_e32 v239, 31, v238
	v_lshlrev_b64 v[238:239], 12, v[238:239]
	v_lshl_add_u64 v[238:239], v[238:239], 0, v[236:237]
	v_lshl_add_u64 v[240:241], v[238:239], 2, s[68:69]
	global_load_dwordx4 v[216:219], v[240:241], off offset:528
	v_lshl_add_u32 v170, s28, 8, v1
	v_lshl_or_b32 v236, s51, 8, v153
	v_ashrrev_i32_e32 v237, 31, v236
	v_or_b32_e32 v238, 48, v170
	v_ashrrev_i32_e32 v239, 31, v238
	v_lshlrev_b64 v[238:239], 12, v[238:239]
	v_lshl_add_u64 v[238:239], v[238:239], 0, v[236:237]
	v_lshl_add_u64 v[240:241], v[238:239], 2, s[68:69]
	global_load_dwordx4 v[220:223], v[240:241], off
	v_lshl_add_u32 v170, s28, 8, v1
	v_lshl_or_b32 v236, s51, 8, v153
	v_ashrrev_i32_e32 v237, 31, v236
	v_or_b32_e32 v238, 48, v170
	v_ashrrev_i32_e32 v239, 31, v238
	v_lshlrev_b64 v[238:239], 12, v[238:239]
	v_lshl_add_u64 v[238:239], v[238:239], 0, v[236:237]
	v_lshl_add_u64 v[240:241], v[238:239], 2, s[68:69]
	global_load_dwordx4 v[224:227], v[240:241], off offset:16
	v_lshl_add_u32 v170, s28, 8, v1
	v_lshl_or_b32 v236, s51, 8, v153
	v_ashrrev_i32_e32 v237, 31, v236
	v_or_b32_e32 v238, 48, v170
	v_ashrrev_i32_e32 v239, 31, v238
	v_lshlrev_b64 v[238:239], 12, v[238:239]
	v_lshl_add_u64 v[238:239], v[238:239], 0, v[236:237]
	v_lshl_add_u64 v[240:241], v[238:239], 2, s[68:69]
	global_load_dwordx4 v[228:231], v[240:241], off offset:512
	v_lshl_add_u32 v170, s28, 8, v1
	v_lshl_or_b32 v236, s51, 8, v153
	v_ashrrev_i32_e32 v237, 31, v236
	v_or_b32_e32 v238, 48, v170
	v_ashrrev_i32_e32 v239, 31, v238
	v_lshlrev_b64 v[238:239], 12, v[238:239]
	v_lshl_add_u64 v[238:239], v[238:239], 0, v[236:237]
	v_lshl_add_u64 v[240:241], v[238:239], 2, s[68:69]
	global_load_dwordx4 v[232:235], v[240:241], off offset:528
	s_nop 1
	s_waitcnt vmcnt(15)
	v_mov_b32_e32 v158, v172
	v_mov_b32_e32 v159, v173
	v_mov_b32_e32 v160, v174
	v_mov_b32_e32 v161, v175
	s_nop 1
	v_lshl_add_u32 v170, s28, 8, v1
	v_lshl_or_b32 v236, s51, 8, v153
	v_ashrrev_i32_e32 v171, 31, v170
	v_ashrrev_i32_e32 v237, 31, v236
	v_lshlrev_b64 v[238:239], 12, v[170:171]
	v_lshl_add_u64 v[238:239], v[238:239], 0, v[236:237]
	v_lshl_add_u64 v[240:241], v[238:239], 0, s[12:13]
	v_lshl_add_u64 v[242:243], v[240:241], 2, s[68:69]
	global_load_dwordx4 v[172:175], v[242:243], off
	s_nop 1
	s_waitcnt vmcnt(15)
	v_mov_b32_e32 v162, v176
	v_mov_b32_e32 v163, v177
	v_mov_b32_e32 v164, v178
	v_mov_b32_e32 v165, v179
	s_nop 1
	v_lshl_add_u32 v170, s28, 8, v1
	v_lshl_or_b32 v236, s51, 8, v153
	v_ashrrev_i32_e32 v171, 31, v170
	v_ashrrev_i32_e32 v237, 31, v236
	v_lshlrev_b64 v[238:239], 12, v[170:171]
	v_lshl_add_u64 v[238:239], v[238:239], 0, v[236:237]
	v_lshl_add_u64 v[240:241], v[238:239], 0, s[12:13]
	v_lshl_add_u64 v[242:243], v[240:241], 2, s[68:69]
	global_load_dwordx4 v[176:179], v[242:243], off offset:16
	s_mov_b64 s[4:5], -1
	s_mov_b32 s2, s86
	v_readlane_b32 s70, v254, 6
	v_readlane_b32 s71, v254, 7
	v_readlane_b32 s72, v254, 8
	v_readlane_b32 s73, v254, 9
	v_readlane_b32 s74, v254, 10
	v_readlane_b32 s75, v254, 11
	v_readlane_b32 s76, v254, 12
	v_readlane_b32 s77, v254, 13
	v_readlane_b32 s78, v254, 14
	v_readlane_b32 s79, v254, 15
	v_readlane_b32 s80, v254, 16
	v_readlane_b32 s81, v254, 17
	v_readlane_b32 s82, v254, 18
	v_readlane_b32 s83, v254, 19
	s_nop 0
	v_pk_add_f32 v[126:127], v[126:127], v[158:159]
	v_pk_add_f32 v[158:159], v[124:125], v[164:165]
	v_pk_add_f32 v[124:125], v[122:123], v[162:163]
	v_pk_add_f32 v[128:129], v[128:129], v[160:161]
	v_cvt_pk_bf16_f32 v122, v126, v127
	s_nop 0
	v_cvt_pk_bf16_f32 v123, v128, v129
	v_cvt_pk_bf16_f32 v124, v124, v125
	v_cvt_pk_bf16_f32 v125, v158, v159
	global_store_dwordx4 v[168:169], v[122:125], off
	s_nop 1
	s_waitcnt vmcnt(16)
	v_mov_b32_e32 v122, v180
	v_mov_b32_e32 v123, v181
	v_mov_b32_e32 v124, v182
	v_mov_b32_e32 v125, v183
	s_nop 1
	v_lshl_add_u32 v170, s28, 8, v1
	v_lshl_or_b32 v236, s51, 8, v153
	v_ashrrev_i32_e32 v171, 31, v170
	v_ashrrev_i32_e32 v237, 31, v236
	v_lshlrev_b64 v[238:239], 12, v[170:171]
	v_lshl_add_u64 v[238:239], v[238:239], 0, v[236:237]
	v_lshl_add_u64 v[240:241], v[238:239], 0, s[12:13]
	v_lshl_add_u64 v[242:243], v[240:241], 2, s[68:69]
	global_load_dwordx4 v[180:183], v[242:243], off offset:512
	s_nop 0
	s_nop 1
	s_waitcnt vmcnt(16)
	v_mov_b32_e32 v126, v184
	v_mov_b32_e32 v127, v185
	v_mov_b32_e32 v128, v186
	v_mov_b32_e32 v129, v187
	s_nop 1
	v_lshl_add_u32 v170, s28, 8, v1
	v_lshl_or_b32 v236, s51, 8, v153
	v_ashrrev_i32_e32 v171, 31, v170
	v_ashrrev_i32_e32 v237, 31, v236
	v_lshlrev_b64 v[238:239], 12, v[170:171]
	v_lshl_add_u64 v[238:239], v[238:239], 0, v[236:237]
	v_lshl_add_u64 v[240:241], v[238:239], 0, s[12:13]
	v_lshl_add_u64 v[242:243], v[240:241], 2, s[68:69]
	global_load_dwordx4 v[184:187], v[242:243], off offset:528
	v_or_b32_e32 v158, 16, v150
	v_ashrrev_i32_e32 v159, 31, v158
	v_lshlrev_b64 v[158:159], 12, v[158:159]
	v_lshl_add_u64 v[158:159], v[158:159], 0, v[148:149]
	v_lshl_add_u64 v[160:161], v[158:159], 2, s[68:69]
	s_nop 0
	v_pk_add_f32 v[118:119], v[118:119], v[122:123]
	s_nop 0
	v_pk_add_f32 v[122:123], v[116:117], v[128:129]
	v_pk_add_f32 v[116:117], v[114:115], v[126:127]
	v_pk_add_f32 v[120:121], v[120:121], v[124:125]
	v_cvt_pk_bf16_f32 v114, v118, v119
	s_nop 0
	v_cvt_pk_bf16_f32 v115, v120, v121
	v_cvt_pk_bf16_f32 v116, v116, v117
	v_cvt_pk_bf16_f32 v117, v122, v123
	global_store_dwordx4 v[168:169], v[114:117], off offset:256
	s_nop 1
	s_waitcnt vmcnt(17)
	v_mov_b32_e32 v114, v188
	v_mov_b32_e32 v115, v189
	v_mov_b32_e32 v116, v190
	v_mov_b32_e32 v117, v191
	s_nop 1
	v_lshl_add_u32 v170, s28, 8, v1
	v_lshl_or_b32 v236, s51, 8, v153
	v_ashrrev_i32_e32 v171, 31, v170
	v_ashrrev_i32_e32 v237, 31, v236
	v_lshlrev_b64 v[238:239], 12, v[170:171]
	v_lshl_add_u64 v[238:239], v[238:239], 0, v[236:237]
	v_lshl_add_u64 v[240:241], v[238:239], 0, s[14:15]
	v_lshl_add_u64 v[242:243], v[240:241], 2, s[68:69]
	global_load_dwordx4 v[188:191], v[242:243], off
	s_nop 0
	s_nop 1
	s_waitcnt vmcnt(17)
	v_mov_b32_e32 v118, v192
	v_mov_b32_e32 v119, v193
	v_mov_b32_e32 v120, v194
	v_mov_b32_e32 v121, v195
	s_nop 1
	v_lshl_add_u32 v170, s28, 8, v1
	v_lshl_or_b32 v236, s51, 8, v153
	v_ashrrev_i32_e32 v171, 31, v170
	v_ashrrev_i32_e32 v237, 31, v236
	v_lshlrev_b64 v[238:239], 12, v[170:171]
	v_lshl_add_u64 v[238:239], v[238:239], 0, v[236:237]
	v_lshl_add_u64 v[240:241], v[238:239], 0, s[14:15]
	v_lshl_add_u64 v[242:243], v[240:241], 2, s[68:69]
	global_load_dwordx4 v[192:195], v[242:243], off offset:16
	v_lshl_add_u64 v[122:123], v[158:159], 1, s[6:7]
	s_nop 0
	v_pk_add_f32 v[110:111], v[110:111], v[114:115]
	s_nop 0
	v_pk_add_f32 v[114:115], v[108:109], v[120:121]
	v_pk_add_f32 v[108:109], v[106:107], v[118:119]
	v_pk_add_f32 v[112:113], v[112:113], v[116:117]
	v_cvt_pk_bf16_f32 v106, v110, v111
	s_nop 0
	v_cvt_pk_bf16_f32 v107, v112, v113
	v_cvt_pk_bf16_f32 v108, v108, v109
	v_cvt_pk_bf16_f32 v109, v114, v115
	global_store_dwordx4 v[122:123], v[106:109], off
	s_nop 1
	s_waitcnt vmcnt(18)
	v_mov_b32_e32 v106, v196
	v_mov_b32_e32 v107, v197
	v_mov_b32_e32 v108, v198
	v_mov_b32_e32 v109, v199
	s_nop 1
	v_lshl_add_u32 v170, s28, 8, v1
	v_lshl_or_b32 v236, s51, 8, v153
	v_ashrrev_i32_e32 v171, 31, v170
	v_ashrrev_i32_e32 v237, 31, v236
	v_lshlrev_b64 v[238:239], 12, v[170:171]
	v_lshl_add_u64 v[238:239], v[238:239], 0, v[236:237]
	v_lshl_add_u64 v[240:241], v[238:239], 0, s[14:15]
	v_lshl_add_u64 v[242:243], v[240:241], 2, s[68:69]
	global_load_dwordx4 v[196:199], v[242:243], off offset:512
	s_nop 0
	s_nop 1
	s_waitcnt vmcnt(18)
	v_mov_b32_e32 v110, v200
	v_mov_b32_e32 v111, v201
	v_mov_b32_e32 v112, v202
	v_mov_b32_e32 v113, v203
	s_nop 1
	v_lshl_add_u32 v170, s28, 8, v1
	v_lshl_or_b32 v236, s51, 8, v153
	v_ashrrev_i32_e32 v171, 31, v170
	v_ashrrev_i32_e32 v237, 31, v236
	v_lshlrev_b64 v[238:239], 12, v[170:171]
	v_lshl_add_u64 v[238:239], v[238:239], 0, v[236:237]
	v_lshl_add_u64 v[240:241], v[238:239], 0, s[14:15]
	v_lshl_add_u64 v[242:243], v[240:241], 2, s[68:69]
	global_load_dwordx4 v[200:203], v[242:243], off offset:528
	v_or_b32_e32 v114, 32, v150
	v_ashrrev_i32_e32 v115, 31, v114
	v_lshlrev_b64 v[114:115], 12, v[114:115]
	v_lshl_add_u64 v[114:115], v[114:115], 0, v[148:149]
	v_lshl_add_u64 v[116:117], v[114:115], 2, s[68:69]
	s_nop 0
	v_pk_add_f32 v[102:103], v[102:103], v[106:107]
	s_nop 0
	v_pk_add_f32 v[106:107], v[100:101], v[112:113]
	v_pk_add_f32 v[100:101], v[98:99], v[110:111]
	v_pk_add_f32 v[104:105], v[104:105], v[108:109]
	v_cvt_pk_bf16_f32 v98, v102, v103
	s_nop 0
	v_cvt_pk_bf16_f32 v99, v104, v105
	v_cvt_pk_bf16_f32 v100, v100, v101
	v_cvt_pk_bf16_f32 v101, v106, v107
	global_store_dwordx4 v[122:123], v[98:101], off offset:256
	s_nop 1
	s_waitcnt vmcnt(19)
	v_mov_b32_e32 v98, v204
	v_mov_b32_e32 v99, v205
	v_mov_b32_e32 v100, v206
	v_mov_b32_e32 v101, v207
	s_nop 1
	v_lshl_add_u32 v170, s28, 8, v1
	v_lshl_or_b32 v236, s51, 8, v153
	v_ashrrev_i32_e32 v171, 31, v170
	v_ashrrev_i32_e32 v237, 31, v236
	v_lshlrev_b64 v[238:239], 12, v[170:171]
	v_lshl_add_u64 v[238:239], v[238:239], 0, v[236:237]
	v_lshl_add_u64 v[240:241], v[238:239], 0, s[16:17]
	v_lshl_add_u64 v[242:243], v[240:241], 2, s[68:69]
	global_load_dwordx4 v[204:207], v[242:243], off
	s_nop 0
	s_nop 1
	s_waitcnt vmcnt(19)
	v_mov_b32_e32 v102, v208
	v_mov_b32_e32 v103, v209
	v_mov_b32_e32 v104, v210
	v_mov_b32_e32 v105, v211
	s_nop 1
	v_lshl_add_u32 v170, s28, 8, v1
	v_lshl_or_b32 v236, s51, 8, v153
	v_ashrrev_i32_e32 v171, 31, v170
	v_ashrrev_i32_e32 v237, 31, v236
	v_lshlrev_b64 v[238:239], 12, v[170:171]
	v_lshl_add_u64 v[238:239], v[238:239], 0, v[236:237]
	v_lshl_add_u64 v[240:241], v[238:239], 0, s[16:17]
	v_lshl_add_u64 v[242:243], v[240:241], 2, s[68:69]
	global_load_dwordx4 v[208:211], v[242:243], off offset:16
	v_lshl_add_u64 v[106:107], v[114:115], 1, s[6:7]
	s_nop 0
	v_pk_add_f32 v[94:95], v[94:95], v[98:99]
	s_nop 0
	v_pk_add_f32 v[98:99], v[92:93], v[104:105]
	v_pk_add_f32 v[92:93], v[90:91], v[102:103]
	v_pk_add_f32 v[96:97], v[96:97], v[100:101]
	v_cvt_pk_bf16_f32 v90, v94, v95
	s_nop 0
	v_cvt_pk_bf16_f32 v91, v96, v97
	v_cvt_pk_bf16_f32 v92, v92, v93
	v_cvt_pk_bf16_f32 v93, v98, v99
	global_store_dwordx4 v[106:107], v[90:93], off
	s_nop 1
	s_waitcnt vmcnt(20)
	v_mov_b32_e32 v90, v212
	v_mov_b32_e32 v91, v213
	v_mov_b32_e32 v92, v214
	v_mov_b32_e32 v93, v215
	s_nop 1
	v_lshl_add_u32 v170, s28, 8, v1
	v_lshl_or_b32 v236, s51, 8, v153
	v_ashrrev_i32_e32 v171, 31, v170
	v_ashrrev_i32_e32 v237, 31, v236
	v_lshlrev_b64 v[238:239], 12, v[170:171]
	v_lshl_add_u64 v[238:239], v[238:239], 0, v[236:237]
	v_lshl_add_u64 v[240:241], v[238:239], 0, s[16:17]
	v_lshl_add_u64 v[242:243], v[240:241], 2, s[68:69]
	global_load_dwordx4 v[212:215], v[242:243], off offset:512
	s_nop 0
	s_nop 1
	s_waitcnt vmcnt(20)
	v_mov_b32_e32 v94, v216
	v_mov_b32_e32 v95, v217
	v_mov_b32_e32 v96, v218
	v_mov_b32_e32 v97, v219
	s_nop 1
	v_lshl_add_u32 v170, s28, 8, v1
	v_lshl_or_b32 v236, s51, 8, v153
	v_ashrrev_i32_e32 v171, 31, v170
	v_ashrrev_i32_e32 v237, 31, v236
	v_lshlrev_b64 v[238:239], 12, v[170:171]
	v_lshl_add_u64 v[238:239], v[238:239], 0, v[236:237]
	v_lshl_add_u64 v[240:241], v[238:239], 0, s[16:17]
	v_lshl_add_u64 v[242:243], v[240:241], 2, s[68:69]
	global_load_dwordx4 v[216:219], v[242:243], off offset:528
	v_or_b32_e32 v98, 48, v150
	v_ashrrev_i32_e32 v99, 31, v98
	v_lshlrev_b64 v[98:99], 12, v[98:99]
	v_lshl_add_u64 v[98:99], v[98:99], 0, v[148:149]
	v_lshl_add_u64 v[100:101], v[98:99], 2, s[68:69]
	s_nop 0
	v_pk_add_f32 v[86:87], v[86:87], v[90:91]
	s_nop 0
	v_pk_add_f32 v[90:91], v[84:85], v[96:97]
	v_pk_add_f32 v[84:85], v[82:83], v[94:95]
	v_pk_add_f32 v[88:89], v[88:89], v[92:93]
	v_cvt_pk_bf16_f32 v82, v86, v87
	s_nop 0
	v_cvt_pk_bf16_f32 v83, v88, v89
	v_cvt_pk_bf16_f32 v84, v84, v85
	v_cvt_pk_bf16_f32 v85, v90, v91
	global_store_dwordx4 v[106:107], v[82:85], off offset:256
	s_nop 1
	s_waitcnt vmcnt(21)
	v_mov_b32_e32 v82, v220
	v_mov_b32_e32 v83, v221
	v_mov_b32_e32 v84, v222
	v_mov_b32_e32 v85, v223
	s_nop 1
	v_lshl_add_u32 v170, s28, 8, v1
	v_lshl_or_b32 v236, s51, 8, v153
	v_ashrrev_i32_e32 v171, 31, v170
	v_ashrrev_i32_e32 v237, 31, v236
	v_lshlrev_b64 v[238:239], 12, v[170:171]
	v_lshl_add_u64 v[238:239], v[238:239], 0, v[236:237]
	v_lshl_add_u64 v[240:241], v[238:239], 0, s[18:19]
	v_lshl_add_u64 v[242:243], v[240:241], 2, s[68:69]
	global_load_dwordx4 v[220:223], v[242:243], off
	s_nop 0
	s_nop 1
	s_waitcnt vmcnt(21)
	v_mov_b32_e32 v86, v224
	v_mov_b32_e32 v87, v225
	v_mov_b32_e32 v88, v226
	v_mov_b32_e32 v89, v227
	s_nop 1
	v_lshl_add_u32 v170, s28, 8, v1
	v_lshl_or_b32 v236, s51, 8, v153
	v_ashrrev_i32_e32 v171, 31, v170
	v_ashrrev_i32_e32 v237, 31, v236
	v_lshlrev_b64 v[238:239], 12, v[170:171]
	v_lshl_add_u64 v[238:239], v[238:239], 0, v[236:237]
	v_lshl_add_u64 v[240:241], v[238:239], 0, s[18:19]
	v_lshl_add_u64 v[242:243], v[240:241], 2, s[68:69]
	global_load_dwordx4 v[224:227], v[242:243], off offset:16
	v_lshl_add_u64 v[90:91], v[98:99], 1, s[6:7]
	s_nop 0
	v_pk_add_f32 v[78:79], v[78:79], v[82:83]
	s_nop 0
	v_pk_add_f32 v[82:83], v[76:77], v[88:89]
	v_pk_add_f32 v[76:77], v[74:75], v[86:87]
	v_pk_add_f32 v[80:81], v[80:81], v[84:85]
	v_cvt_pk_bf16_f32 v74, v78, v79
	s_nop 0
	v_cvt_pk_bf16_f32 v75, v80, v81
	v_cvt_pk_bf16_f32 v76, v76, v77
	v_cvt_pk_bf16_f32 v77, v82, v83
	global_store_dwordx4 v[90:91], v[74:77], off
	s_nop 1
	s_waitcnt vmcnt(22)
	v_mov_b32_e32 v74, v228
	v_mov_b32_e32 v75, v229
	v_mov_b32_e32 v76, v230
	v_mov_b32_e32 v77, v231
	s_nop 1
	v_lshl_add_u32 v170, s28, 8, v1
	v_lshl_or_b32 v236, s51, 8, v153
	v_ashrrev_i32_e32 v171, 31, v170
	v_ashrrev_i32_e32 v237, 31, v236
	v_lshlrev_b64 v[238:239], 12, v[170:171]
	v_lshl_add_u64 v[238:239], v[238:239], 0, v[236:237]
	v_lshl_add_u64 v[240:241], v[238:239], 0, s[18:19]
	v_lshl_add_u64 v[242:243], v[240:241], 2, s[68:69]
	global_load_dwordx4 v[228:231], v[242:243], off offset:512
	s_nop 0
	s_nop 1
	s_waitcnt vmcnt(22)
	v_mov_b32_e32 v78, v232
	v_mov_b32_e32 v79, v233
	v_mov_b32_e32 v80, v234
	v_mov_b32_e32 v81, v235
	s_nop 1
	v_lshl_add_u32 v170, s28, 8, v1
	v_lshl_or_b32 v236, s51, 8, v153
	v_ashrrev_i32_e32 v171, 31, v170
	v_ashrrev_i32_e32 v237, 31, v236
	v_lshlrev_b64 v[238:239], 12, v[170:171]
	v_lshl_add_u64 v[238:239], v[238:239], 0, v[236:237]
	v_lshl_add_u64 v[240:241], v[238:239], 0, s[18:19]
	v_lshl_add_u64 v[242:243], v[240:241], 2, s[68:69]
	global_load_dwordx4 v[232:235], v[242:243], off offset:528
	v_lshl_add_u64 v[82:83], v[146:147], 0, s[12:13]
	v_lshl_add_u64 v[84:85], v[82:83], 2, s[68:69]
	s_nop 0
	v_pk_add_f32 v[70:71], v[70:71], v[74:75]
	s_nop 0
	v_pk_add_f32 v[74:75], v[68:69], v[80:81]
	v_pk_add_f32 v[68:69], v[66:67], v[78:79]
	v_pk_add_f32 v[72:73], v[72:73], v[76:77]
	v_cvt_pk_bf16_f32 v66, v70, v71
	s_nop 0
	v_cvt_pk_bf16_f32 v67, v72, v73
	v_cvt_pk_bf16_f32 v68, v68, v69
	v_cvt_pk_bf16_f32 v69, v74, v75
	global_store_dwordx4 v[90:91], v[66:69], off offset:256
	s_nop 1
	s_waitcnt vmcnt(23)
	v_mov_b32_e32 v66, v172
	v_mov_b32_e32 v67, v173
	v_mov_b32_e32 v68, v174
	v_mov_b32_e32 v69, v175
	s_nop 0
	s_nop 1
	s_waitcnt vmcnt(22)
	v_mov_b32_e32 v70, v176
	v_mov_b32_e32 v71, v177
	v_mov_b32_e32 v72, v178
	v_mov_b32_e32 v73, v179
	v_lshl_add_u64 v[74:75], v[82:83], 1, s[6:7]
	s_nop 0
	v_pk_add_f32 v[62:63], v[62:63], v[66:67]
	s_nop 0
	v_pk_add_f32 v[66:67], v[60:61], v[72:73]
	v_pk_add_f32 v[60:61], v[58:59], v[70:71]
	v_pk_add_f32 v[64:65], v[64:65], v[68:69]
	v_cvt_pk_bf16_f32 v58, v62, v63
	s_nop 0
	v_cvt_pk_bf16_f32 v59, v64, v65
	v_cvt_pk_bf16_f32 v60, v60, v61
	v_cvt_pk_bf16_f32 v61, v66, v67
	global_store_dwordx4 v[74:75], v[58:61], off
	s_nop 1
	s_waitcnt vmcnt(21)
	v_mov_b32_e32 v58, v180
	v_mov_b32_e32 v59, v181
	v_mov_b32_e32 v60, v182
	v_mov_b32_e32 v61, v183
	s_nop 0
	s_nop 1
	s_waitcnt vmcnt(20)
	v_mov_b32_e32 v62, v184
	v_mov_b32_e32 v63, v185
	v_mov_b32_e32 v64, v186
	v_mov_b32_e32 v65, v187
	v_lshl_add_u64 v[66:67], v[146:147], 0, s[14:15]
	v_lshl_add_u64 v[68:69], v[66:67], 2, s[68:69]
	s_nop 0
	v_pk_add_f32 v[54:55], v[54:55], v[58:59]
	s_nop 0
	v_pk_add_f32 v[58:59], v[52:53], v[64:65]
	v_pk_add_f32 v[52:53], v[50:51], v[62:63]
	v_pk_add_f32 v[56:57], v[56:57], v[60:61]
	v_cvt_pk_bf16_f32 v50, v54, v55
	s_nop 0
	v_cvt_pk_bf16_f32 v51, v56, v57
	v_cvt_pk_bf16_f32 v52, v52, v53
	v_cvt_pk_bf16_f32 v53, v58, v59
	global_store_dwordx4 v[74:75], v[50:53], off offset:256
	s_nop 1
	s_waitcnt vmcnt(19)
	v_mov_b32_e32 v50, v188
	v_mov_b32_e32 v51, v189
	v_mov_b32_e32 v52, v190
	v_mov_b32_e32 v53, v191
	s_nop 0
	s_nop 1
	s_waitcnt vmcnt(18)
	v_mov_b32_e32 v54, v192
	v_mov_b32_e32 v55, v193
	v_mov_b32_e32 v56, v194
	v_mov_b32_e32 v57, v195
	v_lshl_add_u64 v[58:59], v[66:67], 1, s[6:7]
	s_nop 0
	v_pk_add_f32 v[46:47], v[46:47], v[50:51]
	s_nop 0
	v_pk_add_f32 v[50:51], v[44:45], v[56:57]
	v_pk_add_f32 v[44:45], v[42:43], v[54:55]
	v_pk_add_f32 v[48:49], v[48:49], v[52:53]
	v_cvt_pk_bf16_f32 v42, v46, v47
	s_nop 0
	v_cvt_pk_bf16_f32 v43, v48, v49
	v_cvt_pk_bf16_f32 v44, v44, v45
	v_cvt_pk_bf16_f32 v45, v50, v51
	global_store_dwordx4 v[58:59], v[42:45], off
	s_nop 1
	s_waitcnt vmcnt(17)
	v_mov_b32_e32 v42, v196
	v_mov_b32_e32 v43, v197
	v_mov_b32_e32 v44, v198
	v_mov_b32_e32 v45, v199
	s_nop 0
	s_nop 1
	s_waitcnt vmcnt(16)
	v_mov_b32_e32 v46, v200
	v_mov_b32_e32 v47, v201
	v_mov_b32_e32 v48, v202
	v_mov_b32_e32 v49, v203
	v_lshl_add_u64 v[50:51], v[146:147], 0, s[16:17]
	v_lshl_add_u64 v[52:53], v[50:51], 2, s[68:69]
	s_nop 0
	v_pk_add_f32 v[38:39], v[38:39], v[42:43]
	s_nop 0
	v_pk_add_f32 v[42:43], v[36:37], v[48:49]
	v_pk_add_f32 v[36:37], v[34:35], v[46:47]
	v_pk_add_f32 v[40:41], v[40:41], v[44:45]
	v_cvt_pk_bf16_f32 v34, v38, v39
	s_nop 0
	v_cvt_pk_bf16_f32 v35, v40, v41
	v_cvt_pk_bf16_f32 v36, v36, v37
	v_cvt_pk_bf16_f32 v37, v42, v43
	global_store_dwordx4 v[58:59], v[34:37], off offset:256
	s_nop 1
	s_waitcnt vmcnt(15)
	v_mov_b32_e32 v34, v204
	v_mov_b32_e32 v35, v205
	v_mov_b32_e32 v36, v206
	v_mov_b32_e32 v37, v207
	s_nop 0
	s_nop 1
	s_waitcnt vmcnt(14)
	v_mov_b32_e32 v38, v208
	v_mov_b32_e32 v39, v209
	v_mov_b32_e32 v40, v210
	v_mov_b32_e32 v41, v211
	v_lshl_add_u64 v[42:43], v[50:51], 1, s[6:7]
	s_nop 0
	v_pk_add_f32 v[30:31], v[30:31], v[34:35]
	s_nop 0
	v_pk_add_f32 v[34:35], v[28:29], v[40:41]
	v_pk_add_f32 v[28:29], v[26:27], v[38:39]
	v_pk_add_f32 v[32:33], v[32:33], v[36:37]
	v_cvt_pk_bf16_f32 v26, v30, v31
	s_nop 0
	v_cvt_pk_bf16_f32 v27, v32, v33
	v_cvt_pk_bf16_f32 v28, v28, v29
	v_cvt_pk_bf16_f32 v29, v34, v35
	global_store_dwordx4 v[42:43], v[26:29], off
	s_nop 1
	s_waitcnt vmcnt(13)
	v_mov_b32_e32 v26, v212
	v_mov_b32_e32 v27, v213
	v_mov_b32_e32 v28, v214
	v_mov_b32_e32 v29, v215
	s_nop 0
	s_nop 1
	s_waitcnt vmcnt(12)
	v_mov_b32_e32 v30, v216
	v_mov_b32_e32 v31, v217
	v_mov_b32_e32 v32, v218
	v_mov_b32_e32 v33, v219
	v_lshl_add_u64 v[34:35], v[146:147], 0, s[18:19]
	v_lshl_add_u64 v[36:37], v[34:35], 2, s[68:69]
	s_nop 0
	v_pk_add_f32 v[22:23], v[22:23], v[26:27]
	s_nop 0
	v_pk_add_f32 v[26:27], v[20:21], v[32:33]
	v_pk_add_f32 v[20:21], v[18:19], v[30:31]
	v_pk_add_f32 v[24:25], v[24:25], v[28:29]
	v_cvt_pk_bf16_f32 v18, v22, v23
	s_nop 0
	v_cvt_pk_bf16_f32 v19, v24, v25
	v_cvt_pk_bf16_f32 v20, v20, v21
	v_cvt_pk_bf16_f32 v21, v26, v27
	global_store_dwordx4 v[42:43], v[18:21], off offset:256
	s_nop 1
	s_waitcnt vmcnt(11)
	v_mov_b32_e32 v18, v220
	v_mov_b32_e32 v19, v221
	v_mov_b32_e32 v20, v222
	v_mov_b32_e32 v21, v223
	s_nop 0
	s_nop 1
	s_waitcnt vmcnt(10)
	v_mov_b32_e32 v22, v224
	v_mov_b32_e32 v23, v225
	v_mov_b32_e32 v24, v226
	v_mov_b32_e32 v25, v227
	v_lshl_add_u64 v[26:27], v[34:35], 1, s[6:7]
	s_nop 0
	v_pk_add_f32 v[14:15], v[14:15], v[18:19]
	s_nop 0
	v_pk_add_f32 v[18:19], v[12:13], v[24:25]
	v_pk_add_f32 v[12:13], v[10:11], v[22:23]
	v_pk_add_f32 v[16:17], v[16:17], v[20:21]
	v_cvt_pk_bf16_f32 v10, v14, v15
	s_nop 0
	v_cvt_pk_bf16_f32 v11, v16, v17
	v_cvt_pk_bf16_f32 v12, v12, v13
	v_cvt_pk_bf16_f32 v13, v18, v19
	global_store_dwordx4 v[26:27], v[10:13], off
	s_nop 1
	s_waitcnt vmcnt(9)
	v_mov_b32_e32 v10, v228
	v_mov_b32_e32 v11, v229
	v_mov_b32_e32 v12, v230
	v_mov_b32_e32 v13, v231
	s_nop 0
	s_nop 1
	s_waitcnt vmcnt(8)
	v_mov_b32_e32 v14, v232
	v_mov_b32_e32 v15, v233
	v_mov_b32_e32 v16, v234
	v_mov_b32_e32 v17, v235
	s_nop 0
	v_pk_add_f32 v[6:7], v[6:7], v[10:11]
	s_nop 0
	v_pk_add_f32 v[10:11], v[4:5], v[16:17]
	v_pk_add_f32 v[4:5], v[2:3], v[14:15]
	v_pk_add_f32 v[8:9], v[8:9], v[12:13]
	v_cvt_pk_bf16_f32 v2, v6, v7
	s_nop 0
	v_cvt_pk_bf16_f32 v3, v8, v9
	v_cvt_pk_bf16_f32 v4, v4, v5
	v_cvt_pk_bf16_f32 v5, v10, v11
	global_store_dwordx4 v[26:27], v[2:5], off offset:256
	s_cbranch_vccnz .LBB0_1714
	s_andn2_b64 vcc, exec, s[0:1]
	s_cbranch_vccnz .LBB0_1713
	s_barrier
	s_branch .LBB0_1713

.LBB0_2043:
	v_lshl_add_u32 v150, s50, 8, v1
	v_lshl_or_b32 v148, s51, 8, v153
	v_ashrrev_i32_e32 v151, 31, v150
	v_ashrrev_i32_e32 v149, 31, v148
	v_lshlrev_b64 v[146:147], 12, v[150:151]
	v_lshl_add_u64 v[146:147], v[146:147], 0, v[148:149]
	v_lshlrev_b64 v[146:147], 1, v[146:147]
	v_lshl_add_u64 v[162:163], s[8:9], 0, v[146:147]
	v_lshl_add_u32 v166, s50, 8, v1
	v_lshl_or_b32 v232, s51, 8, v153
	v_ashrrev_i32_e32 v167, 31, v166
	v_ashrrev_i32_e32 v233, 31, v232
	v_lshlrev_b64 v[234:235], 12, v[166:167]
	v_lshl_add_u64 v[234:235], v[234:235], 0, v[232:233]
	v_lshlrev_b64 v[234:235], 1, v[234:235]
	v_lshl_add_u64 v[236:237], s[8:9], 0, v[234:235]
	global_load_dwordx4 v[168:171], v[236:237], off
	v_lshl_add_u32 v166, s50, 8, v1
	v_lshl_or_b32 v232, s51, 8, v153
	v_ashrrev_i32_e32 v167, 31, v166
	v_ashrrev_i32_e32 v233, 31, v232
	v_lshlrev_b64 v[234:235], 12, v[166:167]
	v_lshl_add_u64 v[234:235], v[234:235], 0, v[232:233]
	v_lshlrev_b64 v[234:235], 1, v[234:235]
	v_lshl_add_u64 v[236:237], s[8:9], 0, v[234:235]
	global_load_dwordx4 v[172:175], v[236:237], off offset:256
	v_lshl_add_u32 v166, s50, 8, v1
	v_lshl_or_b32 v232, s51, 8, v153
	v_ashrrev_i32_e32 v233, 31, v232
	v_or_b32_e32 v234, 16, v166
	v_ashrrev_i32_e32 v235, 31, v234
	v_lshlrev_b64 v[234:235], 12, v[234:235]
	v_lshl_add_u64 v[234:235], v[234:235], 0, v[232:233]
	v_lshlrev_b64 v[234:235], 1, v[234:235]
	v_lshl_add_u64 v[236:237], s[8:9], 0, v[234:235]
	global_load_dwordx4 v[176:179], v[236:237], off
	v_lshl_add_u32 v166, s50, 8, v1
	v_lshl_or_b32 v232, s51, 8, v153
	v_ashrrev_i32_e32 v233, 31, v232
	v_or_b32_e32 v234, 16, v166
	v_ashrrev_i32_e32 v235, 31, v234
	v_lshlrev_b64 v[234:235], 12, v[234:235]
	v_lshl_add_u64 v[234:235], v[234:235], 0, v[232:233]
	v_lshlrev_b64 v[234:235], 1, v[234:235]
	v_lshl_add_u64 v[236:237], s[8:9], 0, v[234:235]
	global_load_dwordx4 v[180:183], v[236:237], off offset:256
	v_lshl_add_u32 v166, s50, 8, v1
	v_lshl_or_b32 v232, s51, 8, v153
	v_ashrrev_i32_e32 v233, 31, v232
	v_or_b32_e32 v234, 32, v166
	v_ashrrev_i32_e32 v235, 31, v234
	v_lshlrev_b64 v[234:235], 12, v[234:235]
	v_lshl_add_u64 v[234:235], v[234:235], 0, v[232:233]
	v_lshlrev_b64 v[234:235], 1, v[234:235]
	v_lshl_add_u64 v[236:237], s[8:9], 0, v[234:235]
	global_load_dwordx4 v[184:187], v[236:237], off
	v_lshl_add_u32 v166, s50, 8, v1
	v_lshl_or_b32 v232, s51, 8, v153
	v_ashrrev_i32_e32 v233, 31, v232
	v_or_b32_e32 v234, 32, v166
	v_ashrrev_i32_e32 v235, 31, v234
	v_lshlrev_b64 v[234:235], 12, v[234:235]
	v_lshl_add_u64 v[234:235], v[234:235], 0, v[232:233]
	v_lshlrev_b64 v[234:235], 1, v[234:235]
	v_lshl_add_u64 v[236:237], s[8:9], 0, v[234:235]
	global_load_dwordx4 v[188:191], v[236:237], off offset:256
	v_lshl_add_u32 v166, s50, 8, v1
	v_lshl_or_b32 v232, s51, 8, v153
	v_ashrrev_i32_e32 v233, 31, v232
	v_or_b32_e32 v234, 48, v166
	v_ashrrev_i32_e32 v235, 31, v234
	v_lshlrev_b64 v[234:235], 12, v[234:235]
	v_lshl_add_u64 v[234:235], v[234:235], 0, v[232:233]
	v_lshlrev_b64 v[234:235], 1, v[234:235]
	v_lshl_add_u64 v[236:237], s[8:9], 0, v[234:235]
	global_load_dwordx4 v[192:195], v[236:237], off
	v_lshl_add_u32 v166, s50, 8, v1
	v_lshl_or_b32 v232, s51, 8, v153
	v_ashrrev_i32_e32 v233, 31, v232
	v_or_b32_e32 v234, 48, v166
	v_ashrrev_i32_e32 v235, 31, v234
	v_lshlrev_b64 v[234:235], 12, v[234:235]
	v_lshl_add_u64 v[234:235], v[234:235], 0, v[232:233]
	v_lshlrev_b64 v[234:235], 1, v[234:235]
	v_lshl_add_u64 v[236:237], s[8:9], 0, v[234:235]
	global_load_dwordx4 v[196:199], v[236:237], off offset:256
	v_lshl_add_u32 v166, s50, 8, v1
	v_lshl_or_b32 v232, s51, 8, v153
	v_ashrrev_i32_e32 v167, 31, v166
	v_ashrrev_i32_e32 v233, 31, v232
	v_lshlrev_b64 v[234:235], 12, v[166:167]
	v_lshl_add_u64 v[234:235], v[234:235], 0, v[232:233]
	v_lshlrev_b64 v[234:235], 1, v[234:235]
	v_lshl_add_u64 v[236:237], v[234:235], 0, s[16:17]
	v_lshl_add_u64 v[238:239], s[8:9], 0, v[236:237]
	global_load_dwordx4 v[200:203], v[238:239], off
	v_lshl_add_u32 v166, s50, 8, v1
	v_lshl_or_b32 v232, s51, 8, v153
	v_ashrrev_i32_e32 v167, 31, v166
	v_ashrrev_i32_e32 v233, 31, v232
	v_lshlrev_b64 v[234:235], 12, v[166:167]
	v_lshl_add_u64 v[234:235], v[234:235], 0, v[232:233]
	v_lshlrev_b64 v[234:235], 1, v[234:235]
	v_lshl_add_u64 v[236:237], v[234:235], 0, s[16:17]
	v_lshl_add_u64 v[238:239], s[8:9], 0, v[236:237]
	global_load_dwordx4 v[204:207], v[238:239], off offset:256
	v_lshl_add_u32 v166, s50, 8, v1
	v_lshl_or_b32 v232, s51, 8, v153
	v_ashrrev_i32_e32 v167, 31, v166
	v_ashrrev_i32_e32 v233, 31, v232
	v_lshlrev_b64 v[234:235], 12, v[166:167]
	v_lshl_add_u64 v[234:235], v[234:235], 0, v[232:233]
	v_lshlrev_b64 v[234:235], 1, v[234:235]
	v_lshl_add_u64 v[236:237], v[234:235], 0, s[18:19]
	v_lshl_add_u64 v[238:239], s[8:9], 0, v[236:237]
	global_load_dwordx4 v[208:211], v[238:239], off
	v_lshl_add_u32 v166, s50, 8, v1
	v_lshl_or_b32 v232, s51, 8, v153
	v_ashrrev_i32_e32 v167, 31, v166
	v_ashrrev_i32_e32 v233, 31, v232
	v_lshlrev_b64 v[234:235], 12, v[166:167]
	v_lshl_add_u64 v[234:235], v[234:235], 0, v[232:233]
	v_lshlrev_b64 v[234:235], 1, v[234:235]
	v_lshl_add_u64 v[236:237], v[234:235], 0, s[18:19]
	v_lshl_add_u64 v[238:239], s[8:9], 0, v[236:237]
	global_load_dwordx4 v[212:215], v[238:239], off offset:256
	v_lshl_add_u32 v166, s50, 8, v1
	v_lshl_or_b32 v232, s51, 8, v153
	v_ashrrev_i32_e32 v167, 31, v166
	v_ashrrev_i32_e32 v233, 31, v232
	v_lshlrev_b64 v[234:235], 12, v[166:167]
	v_lshl_add_u64 v[234:235], v[234:235], 0, v[232:233]
	v_lshlrev_b64 v[234:235], 1, v[234:235]
	v_lshl_add_u64 v[236:237], v[234:235], 0, s[20:21]
	v_lshl_add_u64 v[238:239], s[8:9], 0, v[236:237]
	global_load_dwordx4 v[216:219], v[238:239], off
	v_lshl_add_u32 v166, s50, 8, v1
	v_lshl_or_b32 v232, s51, 8, v153
	v_ashrrev_i32_e32 v167, 31, v166
	v_ashrrev_i32_e32 v233, 31, v232
	v_lshlrev_b64 v[234:235], 12, v[166:167]
	v_lshl_add_u64 v[234:235], v[234:235], 0, v[232:233]
	v_lshlrev_b64 v[234:235], 1, v[234:235]
	v_lshl_add_u64 v[236:237], v[234:235], 0, s[20:21]
	v_lshl_add_u64 v[238:239], s[8:9], 0, v[236:237]
	global_load_dwordx4 v[220:223], v[238:239], off offset:256
	v_lshl_add_u32 v166, s50, 8, v1
	v_lshl_or_b32 v232, s51, 8, v153
	v_ashrrev_i32_e32 v167, 31, v166
	v_ashrrev_i32_e32 v233, 31, v232
	v_lshlrev_b64 v[234:235], 12, v[166:167]
	v_lshl_add_u64 v[234:235], v[234:235], 0, v[232:233]
	v_lshlrev_b64 v[234:235], 1, v[234:235]
	v_lshl_add_u64 v[236:237], v[234:235], 0, s[22:23]
	v_lshl_add_u64 v[238:239], s[8:9], 0, v[236:237]
	global_load_dwordx4 v[224:227], v[238:239], off
	v_lshl_add_u32 v166, s50, 8, v1
	v_lshl_or_b32 v232, s51, 8, v153
	v_ashrrev_i32_e32 v167, 31, v166
	v_ashrrev_i32_e32 v233, 31, v232
	v_lshlrev_b64 v[234:235], 12, v[166:167]
	v_lshl_add_u64 v[234:235], v[234:235], 0, v[232:233]
	v_lshlrev_b64 v[234:235], 1, v[234:235]
	v_lshl_add_u64 v[236:237], v[234:235], 0, s[22:23]
	v_lshl_add_u64 v[238:239], s[8:9], 0, v[236:237]
	global_load_dwordx4 v[228:231], v[238:239], off offset:256
	s_nop 1
	s_waitcnt vmcnt(15)
	v_mov_b32_e32 v158, v168
	v_mov_b32_e32 v159, v169
	v_mov_b32_e32 v160, v170
	v_mov_b32_e32 v161, v171
	s_and_b64 vcc, exec, s[4:5]
	s_mov_b64 s[4:5], -1
	s_nop 0
	v_lshlrev_b32_e32 v151, 16, v158
	v_and_b32_e32 v157, 0xffff0000, v158
	v_lshlrev_b32_e32 v158, 16, v159
	v_and_b32_e32 v159, 0xffff0000, v159
	v_lshlrev_b32_e32 v165, 16, v161
	v_and_b32_e32 v161, 0xffff0000, v161
	v_lshlrev_b32_e32 v164, 16, v160
	v_and_b32_e32 v160, 0xffff0000, v160
	v_add_f32_e32 v126, v126, v151
	v_add_f32_e32 v127, v127, v157
	v_add_f32_e32 v128, v128, v158
	v_add_f32_e32 v129, v129, v159
	v_add_f32_e32 v125, v125, v161
	v_add_f32_e32 v151, v122, v164
	v_add_f32_e32 v157, v123, v160
	v_add_f32_e32 v158, v124, v165
	v_cvt_pk_bf16_f32 v122, v126, v127
	v_cvt_pk_bf16_f32 v123, v128, v129
	v_cvt_pk_bf16_f32 v124, v151, v157
	v_cvt_pk_bf16_f32 v125, v158, v125
	s_nop 1
	s_waitcnt vmcnt(14)
	v_mov_b32_e32 v126, v172
	v_mov_b32_e32 v127, v173
	v_mov_b32_e32 v128, v174
	v_mov_b32_e32 v129, v175
	v_or_b32_e32 v158, 16, v150
	v_ashrrev_i32_e32 v159, 31, v158
	v_lshlrev_b64 v[158:159], 12, v[158:159]
	v_lshl_add_u64 v[160:161], s[10:11], 0, v[146:147]
	v_lshl_add_u64 v[158:159], v[158:159], 0, v[148:149]
	global_store_dwordx4 v[160:161], v[122:125], off
	v_lshlrev_b64 v[158:159], 1, v[158:159]
	v_lshl_add_u64 v[162:163], s[8:9], 0, v[158:159]
	s_nop 0
	v_lshlrev_b32_e32 v122, 16, v126
	v_and_b32_e32 v123, 0xffff0000, v126
	v_lshlrev_b32_e32 v124, 16, v127
	v_and_b32_e32 v125, 0xffff0000, v127
	v_lshlrev_b32_e32 v126, 16, v128
	v_and_b32_e32 v127, 0xffff0000, v128
	v_lshlrev_b32_e32 v128, 16, v129
	v_and_b32_e32 v129, 0xffff0000, v129
	v_add_f32_e32 v113, v113, v129
	v_add_f32_e32 v118, v118, v122
	v_add_f32_e32 v119, v119, v123
	v_add_f32_e32 v120, v120, v124
	v_add_f32_e32 v121, v121, v125
	v_add_f32_e32 v122, v110, v126
	v_add_f32_e32 v123, v111, v127
	v_add_f32_e32 v124, v112, v128
	v_cvt_pk_bf16_f32 v110, v118, v119
	v_cvt_pk_bf16_f32 v111, v120, v121
	v_cvt_pk_bf16_f32 v112, v122, v123
	v_cvt_pk_bf16_f32 v113, v124, v113
	global_store_dwordx4 v[160:161], v[110:113], off offset:256
	s_nop 1
	s_waitcnt vmcnt(15)
	v_mov_b32_e32 v110, v176
	v_mov_b32_e32 v111, v177
	v_mov_b32_e32 v112, v178
	v_mov_b32_e32 v113, v179
	s_nop 0
	v_lshlrev_b32_e32 v118, 16, v110
	v_and_b32_e32 v110, 0xffff0000, v110
	v_lshlrev_b32_e32 v119, 16, v111
	v_and_b32_e32 v111, 0xffff0000, v111
	v_lshlrev_b32_e32 v120, 16, v112
	v_and_b32_e32 v112, 0xffff0000, v112
	v_lshlrev_b32_e32 v121, 16, v113
	v_and_b32_e32 v113, 0xffff0000, v113
	v_add_f32_e32 v110, v115, v110
	v_add_f32_e32 v111, v117, v111
	v_add_f32_e32 v112, v107, v112
	v_add_f32_e32 v109, v109, v113
	v_add_f32_e32 v114, v114, v118
	v_add_f32_e32 v115, v116, v119
	v_add_f32_e32 v116, v106, v120
	v_add_f32_e32 v117, v108, v121
	v_cvt_pk_bf16_f32 v106, v114, v110
	v_cvt_pk_bf16_f32 v107, v115, v111
	v_cvt_pk_bf16_f32 v108, v116, v112
	v_cvt_pk_bf16_f32 v109, v117, v109
	s_nop 1
	s_waitcnt vmcnt(14)
	v_mov_b32_e32 v110, v180
	v_mov_b32_e32 v111, v181
	v_mov_b32_e32 v112, v182
	v_mov_b32_e32 v113, v183
	v_or_b32_e32 v114, 32, v150
	v_ashrrev_i32_e32 v115, 31, v114
	v_lshlrev_b64 v[114:115], 12, v[114:115]
	v_lshl_add_u64 v[116:117], s[10:11], 0, v[158:159]
	v_lshl_add_u64 v[114:115], v[114:115], 0, v[148:149]
	global_store_dwordx4 v[116:117], v[106:109], off
	v_lshlrev_b64 v[114:115], 1, v[114:115]
	v_lshl_add_u64 v[118:119], s[8:9], 0, v[114:115]
	s_nop 0
	v_lshlrev_b32_e32 v106, 16, v110
	v_and_b32_e32 v107, 0xffff0000, v110
	v_lshlrev_b32_e32 v108, 16, v111
	v_and_b32_e32 v109, 0xffff0000, v111
	v_lshlrev_b32_e32 v110, 16, v112
	v_and_b32_e32 v111, 0xffff0000, v112
	v_lshlrev_b32_e32 v112, 16, v113
	v_and_b32_e32 v113, 0xffff0000, v113
	v_add_f32_e32 v97, v97, v113
	v_add_f32_e32 v102, v102, v106
	v_add_f32_e32 v103, v103, v107
	v_add_f32_e32 v104, v104, v108
	v_add_f32_e32 v105, v105, v109
	v_add_f32_e32 v106, v94, v110
	v_add_f32_e32 v107, v95, v111
	v_add_f32_e32 v108, v96, v112
	v_cvt_pk_bf16_f32 v94, v102, v103
	v_cvt_pk_bf16_f32 v95, v104, v105
	v_cvt_pk_bf16_f32 v96, v106, v107
	v_cvt_pk_bf16_f32 v97, v108, v97
	global_store_dwordx4 v[116:117], v[94:97], off offset:256
	s_nop 1
	s_waitcnt vmcnt(15)
	v_mov_b32_e32 v94, v184
	v_mov_b32_e32 v95, v185
	v_mov_b32_e32 v96, v186
	v_mov_b32_e32 v97, v187
	s_nop 0
	v_lshlrev_b32_e32 v102, 16, v94
	v_and_b32_e32 v94, 0xffff0000, v94
	v_lshlrev_b32_e32 v103, 16, v95
	v_and_b32_e32 v95, 0xffff0000, v95
	v_lshlrev_b32_e32 v104, 16, v96
	v_and_b32_e32 v96, 0xffff0000, v96
	v_lshlrev_b32_e32 v105, 16, v97
	v_and_b32_e32 v97, 0xffff0000, v97
	v_add_f32_e32 v94, v99, v94
	v_add_f32_e32 v95, v101, v95
	v_add_f32_e32 v96, v91, v96
	v_add_f32_e32 v93, v93, v97
	v_add_f32_e32 v98, v98, v102
	v_add_f32_e32 v99, v100, v103
	v_add_f32_e32 v100, v90, v104
	v_add_f32_e32 v101, v92, v105
	v_cvt_pk_bf16_f32 v90, v98, v94
	v_cvt_pk_bf16_f32 v91, v99, v95
	v_cvt_pk_bf16_f32 v92, v100, v96
	v_cvt_pk_bf16_f32 v93, v101, v93
	s_nop 1
	s_waitcnt vmcnt(14)
	v_mov_b32_e32 v94, v188
	v_mov_b32_e32 v95, v189
	v_mov_b32_e32 v96, v190
	v_mov_b32_e32 v97, v191
	v_or_b32_e32 v98, 48, v150
	v_ashrrev_i32_e32 v99, 31, v98
	v_lshlrev_b64 v[98:99], 12, v[98:99]
	v_lshl_add_u64 v[100:101], s[10:11], 0, v[114:115]
	v_lshl_add_u64 v[98:99], v[98:99], 0, v[148:149]
	global_store_dwordx4 v[100:101], v[90:93], off
	v_lshlrev_b64 v[98:99], 1, v[98:99]
	v_lshl_add_u64 v[102:103], s[8:9], 0, v[98:99]
	s_nop 0
	v_lshlrev_b32_e32 v90, 16, v94
	v_and_b32_e32 v91, 0xffff0000, v94
	v_lshlrev_b32_e32 v92, 16, v95
	v_and_b32_e32 v93, 0xffff0000, v95
	v_lshlrev_b32_e32 v94, 16, v96
	v_and_b32_e32 v95, 0xffff0000, v96
	v_lshlrev_b32_e32 v96, 16, v97
	v_and_b32_e32 v97, 0xffff0000, v97
	v_add_f32_e32 v81, v81, v97
	v_add_f32_e32 v86, v86, v90
	v_add_f32_e32 v87, v87, v91
	v_add_f32_e32 v88, v88, v92
	v_add_f32_e32 v89, v89, v93
	v_add_f32_e32 v90, v78, v94
	v_add_f32_e32 v91, v79, v95
	v_add_f32_e32 v92, v80, v96
	v_cvt_pk_bf16_f32 v78, v86, v87
	v_cvt_pk_bf16_f32 v79, v88, v89
	v_cvt_pk_bf16_f32 v80, v90, v91
	v_cvt_pk_bf16_f32 v81, v92, v81
	global_store_dwordx4 v[100:101], v[78:81], off offset:256
	s_nop 1
	s_waitcnt vmcnt(15)
	v_mov_b32_e32 v78, v192
	v_mov_b32_e32 v79, v193
	v_mov_b32_e32 v80, v194
	v_mov_b32_e32 v81, v195
	s_nop 0
	v_lshlrev_b32_e32 v86, 16, v78
	v_and_b32_e32 v78, 0xffff0000, v78
	v_lshlrev_b32_e32 v87, 16, v79
	v_and_b32_e32 v79, 0xffff0000, v79
	v_lshlrev_b32_e32 v88, 16, v80
	v_and_b32_e32 v80, 0xffff0000, v80
	v_lshlrev_b32_e32 v89, 16, v81
	v_and_b32_e32 v81, 0xffff0000, v81
	v_add_f32_e32 v78, v83, v78
	v_add_f32_e32 v79, v85, v79
	v_add_f32_e32 v80, v75, v80
	v_add_f32_e32 v77, v77, v81
	v_add_f32_e32 v82, v82, v86
	v_add_f32_e32 v83, v84, v87
	v_add_f32_e32 v84, v74, v88
	v_add_f32_e32 v85, v76, v89
	v_cvt_pk_bf16_f32 v74, v82, v78
	v_cvt_pk_bf16_f32 v75, v83, v79
	v_cvt_pk_bf16_f32 v76, v84, v80
	v_cvt_pk_bf16_f32 v77, v85, v77
	s_nop 1
	s_waitcnt vmcnt(14)
	v_mov_b32_e32 v78, v196
	v_mov_b32_e32 v79, v197
	v_mov_b32_e32 v80, v198
	v_mov_b32_e32 v81, v199
	v_lshl_add_u64 v[84:85], s[10:11], 0, v[98:99]
	global_store_dwordx4 v[84:85], v[74:77], off
	v_lshl_add_u64 v[82:83], v[146:147], 0, s[16:17]
	v_lshl_add_u64 v[86:87], s[8:9], 0, v[82:83]
	s_nop 0
	v_lshlrev_b32_e32 v74, 16, v78
	v_and_b32_e32 v75, 0xffff0000, v78
	v_lshlrev_b32_e32 v76, 16, v79
	v_and_b32_e32 v77, 0xffff0000, v79
	v_lshlrev_b32_e32 v78, 16, v80
	v_and_b32_e32 v79, 0xffff0000, v80
	v_lshlrev_b32_e32 v80, 16, v81
	v_and_b32_e32 v81, 0xffff0000, v81
	v_add_f32_e32 v69, v69, v81
	v_add_f32_e32 v70, v70, v74
	v_add_f32_e32 v71, v71, v75
	v_add_f32_e32 v72, v72, v76
	v_add_f32_e32 v73, v73, v77
	v_add_f32_e32 v74, v66, v78
	v_add_f32_e32 v75, v67, v79
	v_add_f32_e32 v76, v68, v80
	v_cvt_pk_bf16_f32 v66, v70, v71
	v_cvt_pk_bf16_f32 v67, v72, v73
	v_cvt_pk_bf16_f32 v68, v74, v75
	v_cvt_pk_bf16_f32 v69, v76, v69
	global_store_dwordx4 v[84:85], v[66:69], off offset:256
	s_nop 1
	s_waitcnt vmcnt(15)
	v_mov_b32_e32 v66, v200
	v_mov_b32_e32 v67, v201
	v_mov_b32_e32 v68, v202
	v_mov_b32_e32 v69, v203
	s_nop 0
	v_lshlrev_b32_e32 v70, 16, v66
	v_and_b32_e32 v66, 0xffff0000, v66
	v_lshlrev_b32_e32 v71, 16, v67
	v_and_b32_e32 v67, 0xffff0000, v67
	v_lshlrev_b32_e32 v73, 16, v69
	v_and_b32_e32 v69, 0xffff0000, v69
	v_lshlrev_b32_e32 v72, 16, v68
	v_and_b32_e32 v68, 0xffff0000, v68
	v_add_f32_e32 v62, v62, v70
	v_add_f32_e32 v63, v63, v66
	v_add_f32_e32 v64, v64, v71
	v_add_f32_e32 v65, v65, v67
	v_add_f32_e32 v61, v61, v69
	v_add_f32_e32 v66, v58, v72
	v_add_f32_e32 v67, v59, v68
	v_add_f32_e32 v68, v60, v73
	v_cvt_pk_bf16_f32 v58, v62, v63
	v_cvt_pk_bf16_f32 v59, v64, v65
	v_cvt_pk_bf16_f32 v60, v66, v67
	v_cvt_pk_bf16_f32 v61, v68, v61
	s_nop 1
	s_waitcnt vmcnt(14)
	v_mov_b32_e32 v62, v204
	v_mov_b32_e32 v63, v205
	v_mov_b32_e32 v64, v206
	v_mov_b32_e32 v65, v207
	v_lshl_add_u64 v[68:69], s[10:11], 0, v[82:83]
	global_store_dwordx4 v[68:69], v[58:61], off
	v_lshl_add_u64 v[66:67], v[146:147], 0, s[18:19]
	v_lshl_add_u64 v[70:71], s[8:9], 0, v[66:67]
	s_nop 0
	v_lshlrev_b32_e32 v58, 16, v62
	v_and_b32_e32 v59, 0xffff0000, v62
	v_lshlrev_b32_e32 v60, 16, v63
	v_and_b32_e32 v61, 0xffff0000, v63
	v_lshlrev_b32_e32 v62, 16, v64
	v_and_b32_e32 v63, 0xffff0000, v64
	v_lshlrev_b32_e32 v64, 16, v65
	v_and_b32_e32 v65, 0xffff0000, v65
	v_add_f32_e32 v49, v49, v65
	v_add_f32_e32 v54, v54, v58
	v_add_f32_e32 v55, v55, v59
	v_add_f32_e32 v56, v56, v60
	v_add_f32_e32 v57, v57, v61
	v_add_f32_e32 v58, v46, v62
	v_add_f32_e32 v59, v47, v63
	v_add_f32_e32 v60, v48, v64
	v_cvt_pk_bf16_f32 v46, v54, v55
	v_cvt_pk_bf16_f32 v47, v56, v57
	v_cvt_pk_bf16_f32 v48, v58, v59
	v_cvt_pk_bf16_f32 v49, v60, v49
	global_store_dwordx4 v[68:69], v[46:49], off offset:256
	s_nop 1
	s_waitcnt vmcnt(15)
	v_mov_b32_e32 v46, v208
	v_mov_b32_e32 v47, v209
	v_mov_b32_e32 v48, v210
	v_mov_b32_e32 v49, v211
	s_nop 0
	v_lshlrev_b32_e32 v54, 16, v46
	v_and_b32_e32 v46, 0xffff0000, v46
	v_lshlrev_b32_e32 v55, 16, v47
	v_and_b32_e32 v47, 0xffff0000, v47
	v_lshlrev_b32_e32 v56, 16, v48
	v_and_b32_e32 v48, 0xffff0000, v48
	v_lshlrev_b32_e32 v57, 16, v49
	v_and_b32_e32 v49, 0xffff0000, v49
	v_add_f32_e32 v46, v51, v46
	v_add_f32_e32 v47, v53, v47
	v_add_f32_e32 v48, v43, v48
	v_add_f32_e32 v45, v45, v49
	v_add_f32_e32 v50, v50, v54
	v_add_f32_e32 v51, v52, v55
	v_add_f32_e32 v52, v42, v56
	v_add_f32_e32 v53, v44, v57
	v_cvt_pk_bf16_f32 v42, v50, v46
	v_cvt_pk_bf16_f32 v43, v51, v47
	v_cvt_pk_bf16_f32 v44, v52, v48
	v_cvt_pk_bf16_f32 v45, v53, v45
	s_nop 1
	s_waitcnt vmcnt(14)
	v_mov_b32_e32 v46, v212
	v_mov_b32_e32 v47, v213
	v_mov_b32_e32 v48, v214
	v_mov_b32_e32 v49, v215
	v_lshl_add_u64 v[52:53], s[10:11], 0, v[66:67]
	global_store_dwordx4 v[52:53], v[42:45], off
	v_lshl_add_u64 v[50:51], v[146:147], 0, s[20:21]
	v_lshl_add_u64 v[54:55], s[8:9], 0, v[50:51]
	s_nop 0
	v_lshlrev_b32_e32 v42, 16, v46
	v_and_b32_e32 v43, 0xffff0000, v46
	v_lshlrev_b32_e32 v44, 16, v47
	v_and_b32_e32 v45, 0xffff0000, v47
	v_lshlrev_b32_e32 v46, 16, v48
	v_and_b32_e32 v47, 0xffff0000, v48
	v_lshlrev_b32_e32 v48, 16, v49
	v_and_b32_e32 v49, 0xffff0000, v49
	v_add_f32_e32 v33, v33, v49
	v_add_f32_e32 v38, v38, v42
	v_add_f32_e32 v39, v39, v43
	v_add_f32_e32 v40, v40, v44
	v_add_f32_e32 v41, v41, v45
	v_add_f32_e32 v42, v30, v46
	v_add_f32_e32 v43, v31, v47
	v_add_f32_e32 v44, v32, v48
	v_cvt_pk_bf16_f32 v30, v38, v39
	v_cvt_pk_bf16_f32 v31, v40, v41
	v_cvt_pk_bf16_f32 v32, v42, v43
	v_cvt_pk_bf16_f32 v33, v44, v33
	global_store_dwordx4 v[52:53], v[30:33], off offset:256
	s_nop 1
	s_waitcnt vmcnt(15)
	v_mov_b32_e32 v30, v216
	v_mov_b32_e32 v31, v217
	v_mov_b32_e32 v32, v218
	v_mov_b32_e32 v33, v219
	s_nop 0
	v_lshlrev_b32_e32 v38, 16, v30
	v_and_b32_e32 v30, 0xffff0000, v30
	v_lshlrev_b32_e32 v39, 16, v31
	v_and_b32_e32 v31, 0xffff0000, v31
	v_lshlrev_b32_e32 v40, 16, v32
	v_and_b32_e32 v32, 0xffff0000, v32
	v_lshlrev_b32_e32 v41, 16, v33
	v_and_b32_e32 v33, 0xffff0000, v33
	v_add_f32_e32 v30, v35, v30
	v_add_f32_e32 v31, v37, v31
	v_add_f32_e32 v32, v27, v32
	v_add_f32_e32 v29, v29, v33
	v_add_f32_e32 v34, v34, v38
	v_add_f32_e32 v35, v36, v39
	v_add_f32_e32 v36, v26, v40
	v_add_f32_e32 v37, v28, v41
	v_cvt_pk_bf16_f32 v26, v34, v30
	v_cvt_pk_bf16_f32 v27, v35, v31
	v_cvt_pk_bf16_f32 v28, v36, v32
	v_cvt_pk_bf16_f32 v29, v37, v29
	s_nop 1
	s_waitcnt vmcnt(14)
	v_mov_b32_e32 v30, v220
	v_mov_b32_e32 v31, v221
	v_mov_b32_e32 v32, v222
	v_mov_b32_e32 v33, v223
	v_lshl_add_u64 v[36:37], s[10:11], 0, v[50:51]
	global_store_dwordx4 v[36:37], v[26:29], off
	v_lshl_add_u64 v[34:35], v[146:147], 0, s[22:23]
	v_lshl_add_u64 v[38:39], s[8:9], 0, v[34:35]
	s_nop 0
	v_lshlrev_b32_e32 v26, 16, v30
	v_and_b32_e32 v27, 0xffff0000, v30
	v_lshlrev_b32_e32 v28, 16, v31
	v_and_b32_e32 v29, 0xffff0000, v31
	v_lshlrev_b32_e32 v30, 16, v32
	v_and_b32_e32 v31, 0xffff0000, v32
	v_lshlrev_b32_e32 v32, 16, v33
	v_and_b32_e32 v33, 0xffff0000, v33
	v_add_f32_e32 v17, v17, v33
	v_add_f32_e32 v22, v22, v26
	v_add_f32_e32 v23, v23, v27
	v_add_f32_e32 v24, v24, v28
	v_add_f32_e32 v25, v25, v29
	v_add_f32_e32 v26, v14, v30
	v_add_f32_e32 v27, v15, v31
	v_add_f32_e32 v28, v16, v32
	v_cvt_pk_bf16_f32 v14, v22, v23
	v_cvt_pk_bf16_f32 v15, v24, v25
	v_cvt_pk_bf16_f32 v16, v26, v27
	v_cvt_pk_bf16_f32 v17, v28, v17
	global_store_dwordx4 v[36:37], v[14:17], off offset:256
	s_nop 1
	s_waitcnt vmcnt(15)
	v_mov_b32_e32 v14, v224
	v_mov_b32_e32 v15, v225
	v_mov_b32_e32 v16, v226
	v_mov_b32_e32 v17, v227
	s_nop 0
	v_lshlrev_b32_e32 v22, 16, v14
	v_and_b32_e32 v14, 0xffff0000, v14
	v_lshlrev_b32_e32 v23, 16, v15
	v_and_b32_e32 v15, 0xffff0000, v15
	v_lshlrev_b32_e32 v24, 16, v16
	v_and_b32_e32 v16, 0xffff0000, v16
	v_lshlrev_b32_e32 v25, 16, v17
	v_and_b32_e32 v17, 0xffff0000, v17
	v_add_f32_e32 v14, v19, v14
	v_add_f32_e32 v15, v21, v15
	v_add_f32_e32 v16, v11, v16
	v_add_f32_e32 v13, v13, v17
	v_add_f32_e32 v18, v18, v22
	v_add_f32_e32 v19, v20, v23
	v_add_f32_e32 v20, v10, v24
	v_add_f32_e32 v21, v12, v25
	v_cvt_pk_bf16_f32 v10, v18, v14
	v_cvt_pk_bf16_f32 v11, v19, v15
	v_cvt_pk_bf16_f32 v12, v20, v16
	v_cvt_pk_bf16_f32 v13, v21, v13
	s_nop 1
	s_waitcnt vmcnt(14)
	v_mov_b32_e32 v14, v228
	v_mov_b32_e32 v15, v229
	v_mov_b32_e32 v16, v230
	v_mov_b32_e32 v17, v231
	v_lshl_add_u64 v[18:19], s[10:11], 0, v[34:35]
	global_store_dwordx4 v[18:19], v[10:13], off
	s_nop 0
	s_nop 0
	v_lshlrev_b32_e32 v10, 16, v14
	v_and_b32_e32 v11, 0xffff0000, v14
	v_lshlrev_b32_e32 v12, 16, v15
	v_and_b32_e32 v13, 0xffff0000, v15
	v_lshlrev_b32_e32 v14, 16, v16
	v_and_b32_e32 v15, 0xffff0000, v16
	v_lshlrev_b32_e32 v16, 16, v17
	v_and_b32_e32 v17, 0xffff0000, v17
	v_add_f32_e32 v5, v5, v17
	v_add_f32_e32 v6, v6, v10
	v_add_f32_e32 v7, v7, v11
	v_add_f32_e32 v8, v8, v12
	v_add_f32_e32 v9, v9, v13
	v_add_f32_e32 v10, v2, v14
	v_add_f32_e32 v11, v3, v15
	v_add_f32_e32 v12, v4, v16
	v_cvt_pk_bf16_f32 v2, v6, v7
	v_cvt_pk_bf16_f32 v3, v8, v9
	v_cvt_pk_bf16_f32 v4, v10, v11
	v_cvt_pk_bf16_f32 v5, v12, v5
	global_store_dwordx4 v[18:19], v[2:5], off offset:256
	s_cbranch_vccnz .LBB0_2028
	s_andn2_b64 vcc, exec, s[0:1]
	s_cbranch_vccnz .LBB0_2027
	s_barrier
	s_branch .LBB0_2027
